# SGU: u loads widened to 16B via permlane32_swap (on v20)
# speedup vs baseline: 1.0116x; 1.0035x over previous
.LBB0_406:
	v_cmp_le_u32_e32 vcc, v120, v124
	s_movk_i32 s10, 0x7fff
	s_mov_b32 s11, 0xffff0000
	s_waitcnt vmcnt(2)
	v_cndmask_b32_e32 v4, 0, v4, vcc
	v_cmp_lt_u32_e32 vcc, v120, v124
	v_bfe_u32 v8, v4, 16, 1
	v_add3_u32 v4, v4, v8, s10
	v_cndmask_b32_e32 v5, 0, v5, vcc
	v_bfe_u32 v8, v5, 16, 1
	v_lshrrev_b32_e32 v4, 16, v4
	v_add3_u32 v5, v5, v8, s10
	v_and_or_b32 v4, v5, s11, v4
	v_or_b32_e32 v5, 2, v120
	v_cmp_le_u32_e32 vcc, v5, v124
	v_lshl_add_u32 v119, v120, 1, s17
	s_movk_i32 s17, 0x110
	v_cndmask_b32_e32 v5, 0, v6, vcc
	v_or_b32_e32 v6, 3, v120
	v_cmp_le_u32_e32 vcc, v6, v124
	v_mad_u32_u24 v88, v118, s17, v119
	ds_read_b128 v[12:15], v88
	ds_read_b128 v[92:95], v88 offset:32
	v_cndmask_b32_e32 v6, 0, v7, vcc
	v_bfe_u32 v7, v5, 16, 1
	v_add3_u32 v5, v5, v7, s10
	v_bfe_u32 v7, v6, 16, 1
	v_lshrrev_b32_e32 v5, 16, v5
	v_add3_u32 v6, v6, v7, s10
	v_and_or_b32 v5, v6, s11, v5
	v_or_b32_e32 v6, 4, v120
	v_cmp_le_u32_e32 vcc, v6, v124
	v_or_b32_e32 v6, 5, v120
	v_lshlrev_b32_e32 v8, 2, v10
	v_cndmask_b32_e32 v0, 0, v0, vcc
	v_cmp_le_u32_e32 vcc, v6, v124
	v_bfe_u32 v6, v0, 16, 1
	v_add3_u32 v0, v0, v6, s10
	v_cndmask_b32_e32 v1, 0, v1, vcc
	v_bfe_u32 v6, v1, 16, 1
	v_lshrrev_b32_e32 v0, 16, v0
	v_add3_u32 v1, v1, v6, s10
	v_and_or_b32 v6, v1, s11, v0
	v_or_b32_e32 v0, 6, v120
	v_cmp_le_u32_e32 vcc, v0, v124
	v_or_b32_e32 v1, 7, v120
	v_or_b32_e32 v114, s18, v124
	v_cndmask_b32_e32 v0, 0, v2, vcc
	v_cmp_le_u32_e32 vcc, v1, v124
	v_bfe_u32 v2, v0, 16, 1
	v_add3_u32 v0, v0, v2, s10
	v_cndmask_b32_e32 v1, 0, v3, vcc
	v_bfe_u32 v2, v1, 16, 1
	v_lshrrev_b32_e32 v0, 16, v0
	v_add3_u32 v1, v1, v2, s10
	v_and_or_b32 v7, v1, s11, v0
	ds_read_b128 v[0:3], v88 offset:8704
	ds_read_b128 v[96:99], v88 offset:8736
	s_waitcnt lgkmcnt(1)
	v_mfma_f32_32x32x16_bf16 v[32:47], v[0:3], v[4:7], 0
	ds_read_b128 v[0:3], v88 offset:17408
	global_load_dword v68, v8, s[14:15]
	ds_read_b128 v[8:11], v88 offset:26112
	ds_read_b128 v[126:129], v88 offset:17440
	ds_read_b128 v[130:133], v88 offset:26144
	v_or_b32_e32 v88, 16, v120
	v_cmp_le_u32_e32 vcc, v88, v124
	s_movk_i32 s26, 0x1400
	v_mfma_f32_32x32x16_bf16 v[48:63], v[12:15], v[4:7], 0
	s_waitcnt vmcnt(1)
	v_cndmask_b32_e32 v84, 0, v84, vcc
	v_cmp_lt_u32_e32 vcc, v88, v124
	v_bfe_u32 v88, v84, 16, 1
	v_add3_u32 v84, v84, v88, s10
	v_cndmask_b32_e32 v85, 0, v85, vcc
	v_bfe_u32 v88, v85, 16, 1
	v_lshrrev_b32_e32 v84, 16, v84
	v_add3_u32 v85, v85, v88, s10
	v_and_or_b32 v134, v85, s11, v84
	v_or_b32_e32 v84, 18, v120
	v_cmp_le_u32_e32 vcc, v84, v124
	v_or_b32_e32 v85, 19, v120
	s_waitcnt lgkmcnt(3)
	v_mfma_f32_32x32x16_bf16 v[16:31], v[0:3], v[4:7], 0
	v_cndmask_b32_e32 v84, 0, v86, vcc
	v_cmp_le_u32_e32 vcc, v85, v124
	v_bfe_u32 v86, v84, 16, 1
	v_add3_u32 v84, v84, v86, s10
	v_cndmask_b32_e32 v85, 0, v87, vcc
	v_bfe_u32 v86, v85, 16, 1
	v_lshrrev_b32_e32 v84, 16, v84
	v_add3_u32 v85, v85, v86, s10
	v_and_or_b32 v135, v85, s11, v84
	v_or_b32_e32 v84, 20, v120
	v_cmp_le_u32_e32 vcc, v84, v124
	v_or_b32_e32 v84, 21, v120
	v_mov_b64_e32 v[0:1], s[22:23]
	v_cndmask_b32_e32 v80, 0, v80, vcc
	v_cmp_le_u32_e32 vcc, v84, v124
	v_bfe_u32 v84, v80, 16, 1
	v_add3_u32 v80, v80, v84, s10
	v_cndmask_b32_e32 v81, 0, v81, vcc
	v_bfe_u32 v84, v81, 16, 1
	v_lshrrev_b32_e32 v80, 16, v80
	v_add3_u32 v81, v81, v84, s10
	v_and_or_b32 v136, v81, s11, v80
	v_or_b32_e32 v80, 22, v120
	v_cmp_le_u32_e32 vcc, v80, v124
	v_or_b32_e32 v81, 23, v120
	v_mad_u64_u32 v[100:101], s[26:27], v114, s26, v[0:1]
	v_cndmask_b32_e32 v80, 0, v82, vcc
	v_cmp_le_u32_e32 vcc, v81, v124
	v_bfe_u32 v82, v80, 16, 1
	v_mov_b32_e32 v102, 0x1400
	v_cndmask_b32_e32 v81, 0, v83, vcc
	v_add3_u32 v80, v80, v82, s10
	v_bfe_u32 v82, v81, 16, 1
	s_mov_b32 s17, 0
	v_lshrrev_b32_e32 v80, 16, v80
	v_add3_u32 v81, v81, v82, s10
	v_mad_u32_u24 v101, s19, v102, v101
	v_mov_b32_e32 v121, 0
	v_and_or_b32 v137, v81, s11, v80
	v_lshl_add_u64 v[80:81], v[100:101], 0, s[16:17]
	v_lshl_add_u64 v[80:81], v[80:81], 0, v[120:121]
	v_mfma_f32_32x32x16_bf16 v[48:63], v[92:95], v[134:137], v[48:63]
	v_bfe_u32 v174, v224, 5, 1
	v_lshlrev_b32_e32 v174, 3, v174
	v_mov_b32_e32 v175, 0
	v_lshl_add_u64 v[172:173], v[80:81], 0, v[174:175]
	global_load_dwordx4 v[140:143], v[172:173], off offset:3072
	global_load_dwordx4 v[144:147], v[172:173], off offset:3104
	v_mul_u32_u24_e32 v118, 0x110, v118
	v_lshlrev_b32_e32 v88, 2, v115
	v_mov_b32_e32 v115, s19
	s_and_b64 vcc, exec, s[8:9]
	v_add_u32_e32 v121, v119, v118
	v_mfma_f32_32x32x16_bf16 v[32:47], v[96:99], v[134:137], v[32:47]
	global_load_dwordx4 v[148:151], v[172:173], off offset:3136
	global_load_dwordx4 v[152:155], v[172:173], off offset:3168
	global_load_dwordx4 v[156:159], v[172:173], off offset:3200
	global_load_dwordx4 v[160:163], v[172:173], off offset:3232
	global_load_dwordx4 v[164:167], v[172:173], off offset:3264
	global_load_dwordx4 v[168:171], v[172:173], off offset:3296
	s_nop 0
	s_waitcnt lgkmcnt(2)
	v_mfma_f32_32x32x16_bf16 v[0:15], v[8:11], v[4:7], 0
	s_waitcnt lgkmcnt(1)
	v_mfma_f32_32x32x16_bf16 v[16:31], v[126:129], v[134:137], v[16:31]
	s_waitcnt lgkmcnt(0)
	v_mfma_f32_32x32x16_bf16 v[0:15], v[130:133], v[134:137], v[0:15]
	s_cbranch_vccnz .LBB0_408
	v_or_b32_e32 v118, 32, v120
	v_cmp_le_u32_e32 vcc, v118, v124
	ds_read_b128 v[126:129], v121 offset:64
	s_nop 0
	v_cndmask_b32_e32 v76, 0, v76, vcc
	v_cmp_lt_u32_e32 vcc, v118, v124
	v_bfe_u32 v118, v76, 16, 1
	v_add3_u32 v76, v76, v118, s10
	v_cndmask_b32_e32 v77, 0, v77, vcc
	v_bfe_u32 v118, v77, 16, 1
	v_lshrrev_b32_e32 v76, 16, v76
	v_add3_u32 v77, v77, v118, s10
	v_and_or_b32 v76, v77, s11, v76
	v_or_b32_e32 v77, 34, v120
	v_cmp_le_u32_e32 vcc, v77, v124
	s_nop 1
	v_cndmask_b32_e32 v77, 0, v78, vcc
	v_or_b32_e32 v78, 35, v120
	v_cmp_le_u32_e32 vcc, v78, v124
	s_nop 1
	v_cndmask_b32_e32 v78, 0, v79, vcc
	v_bfe_u32 v79, v77, 16, 1
	v_add3_u32 v77, v77, v79, s10
	v_bfe_u32 v79, v78, 16, 1
	v_lshrrev_b32_e32 v77, 16, v77
	v_add3_u32 v78, v78, v79, s10
	v_and_or_b32 v77, v78, s11, v77
	v_or_b32_e32 v78, 36, v120
	v_cmp_le_u32_e32 vcc, v78, v124
	v_or_b32_e32 v78, 37, v120
	s_nop 0
	v_cndmask_b32_e32 v72, 0, v72, vcc
	v_cmp_le_u32_e32 vcc, v78, v124
	v_bfe_u32 v78, v72, 16, 1
	v_add3_u32 v72, v72, v78, s10
	v_cndmask_b32_e32 v73, 0, v73, vcc
	v_bfe_u32 v78, v73, 16, 1
	v_lshrrev_b32_e32 v72, 16, v72
	v_add3_u32 v73, v73, v78, s10
	v_and_or_b32 v78, v73, s11, v72
	v_or_b32_e32 v72, 38, v120
	v_cmp_le_u32_e32 vcc, v72, v124
	v_or_b32_e32 v73, 39, v120
	s_nop 0
	v_cndmask_b32_e32 v72, 0, v74, vcc
	v_cmp_le_u32_e32 vcc, v73, v124
	v_bfe_u32 v74, v72, 16, 1
	v_add3_u32 v72, v72, v74, s10
	v_cndmask_b32_e32 v73, 0, v75, vcc
	v_bfe_u32 v74, v73, 16, 1
	v_lshrrev_b32_e32 v72, 16, v72
	v_add3_u32 v73, v73, v74, s10
	v_and_or_b32 v79, v73, s11, v72
	ds_read_b128 v[72:75], v121 offset:8768
	s_waitcnt lgkmcnt(1)
	v_mfma_f32_32x32x16_bf16 v[48:63], v[126:129], v[76:79], v[48:63]
	s_waitcnt lgkmcnt(0)
	v_mfma_f32_32x32x16_bf16 v[32:47], v[72:75], v[76:79], v[32:47]
	ds_read_b128 v[72:75], v121 offset:17472
	ds_read_b128 v[126:129], v121 offset:26176
	s_waitcnt lgkmcnt(1)
	v_mfma_f32_32x32x16_bf16 v[16:31], v[72:75], v[76:79], v[16:31]
	s_waitcnt lgkmcnt(0)
	v_mfma_f32_32x32x16_bf16 v[0:15], v[126:129], v[76:79], v[0:15]

.LBB0_410:
	s_waitcnt vmcnt(7)
	v_permlane32_swap_b32_e32 v140, v142
	v_permlane32_swap_b32_e32 v141, v143
	v_lshlrev_b32_e32 v66, 16, v140
	v_and_b32_e32 v67, 0xffff0000, v140
	v_pk_mul_f32 v[70:71], v[66:67], v[66:67]
	s_mov_b32 s8, 0x3d372713
	v_lshlrev_b32_e32 v72, 16, v141
	v_and_b32_e32 v73, 0xffff0000, v141
	v_pk_fma_f32 v[70:71], v[70:71], s[8:9], 1.0 op_sel_hi:[1,0,0]
	v_pk_mul_f32 v[74:75], v[72:73], v[72:73]
	s_add_u32 s10, s34, 0xa000000
	v_pk_mul_f32 v[70:71], v[70:71], v[66:67]
	s_mov_b32 s34, 0xc0135761
	v_pk_fma_f32 v[74:75], v[74:75], s[8:9], 1.0 op_sel_hi:[1,0,0]
	v_pk_mul_f32 v[70:71], v[70:71], s[34:35] op_sel_hi:[1,0]
	v_pk_mul_f32 v[74:75], v[74:75], v[72:73]
	v_exp_f32_e32 v70, v70
	v_exp_f32_e32 v71, v71
	v_pk_mul_f32 v[74:75], v[74:75], s[34:35] op_sel_hi:[1,0]
	s_addc_u32 s11, s35, 0
	v_exp_f32_e32 v74, v74
	v_exp_f32_e32 v75, v75
	v_pk_add_f32 v[70:71], v[70:71], 1.0 op_sel_hi:[1,0]
	v_lshlrev_b64 v[64:65], 11, v[114:115]
	v_rcp_f32_e32 v70, v70
	v_rcp_f32_e32 v71, v71
	v_pk_add_f32 v[74:75], v[74:75], 1.0 op_sel_hi:[1,0]
	v_lshl_add_u64 v[64:65], s[10:11], 0, v[64:65]
	v_rcp_f32_e32 v74, v74
	v_rcp_f32_e32 v75, v75
	v_pk_mul_f32 v[66:67], v[70:71], v[66:67]
	v_pk_add_f32 v[48:49], v[68:69], v[48:49] op_sel_hi:[0,1]
	v_lshl_add_u64 v[64:65], v[64:65], 0, s[16:17]
	v_lshlrev_b32_e32 v122, 1, v88
	v_mov_b32_e32 v123, 0
	v_pk_mul_f32 v[48:49], v[66:67], v[48:49]
	v_pk_mul_f32 v[66:67], v[74:75], v[72:73]
	v_pk_add_f32 v[50:51], v[68:69], v[50:51] op_sel_hi:[0,1]
	v_lshl_add_u64 v[64:65], v[64:65], 0, v[122:123]
	v_bfe_u32 v138, v224, 5, 1
	v_lshlrev_b32_e32 v138, 3, v138
	v_mov_b32_e32 v139, 0
	v_lshl_add_u64 v[136:137], v[64:65], 0, v[138:139]
	v_pk_mul_f32 v[50:51], v[66:67], v[50:51]
	v_cvt_pk_bf16_f32 v128, v48, v49
	s_waitcnt vmcnt(7)
	v_lshlrev_b32_e32 v66, 16, v143
	v_cvt_pk_bf16_f32 v129, v50, v51
	v_lshlrev_b32_e32 v48, 16, v142
	v_and_b32_e32 v49, 0xffff0000, v142
	v_pk_mul_f32 v[50:51], v[48:49], v[48:49]
	v_and_b32_e32 v67, 0xffff0000, v143
	v_pk_fma_f32 v[50:51], v[50:51], s[8:9], 1.0 op_sel_hi:[1,0,0]
	v_pk_mul_f32 v[70:71], v[66:67], v[66:67]
	v_pk_mul_f32 v[50:51], v[50:51], v[48:49]
	v_pk_fma_f32 v[70:71], v[70:71], s[8:9], 1.0 op_sel_hi:[1,0,0]
	v_pk_mul_f32 v[50:51], v[50:51], s[34:35] op_sel_hi:[1,0]
	v_pk_mul_f32 v[70:71], v[70:71], v[66:67]
	v_exp_f32_e32 v50, v50
	v_exp_f32_e32 v51, v51
	v_pk_mul_f32 v[70:71], v[70:71], s[34:35] op_sel_hi:[1,0]
	v_pk_add_f32 v[32:33], v[68:69], v[32:33] op_sel_hi:[0,1]
	v_exp_f32_e32 v70, v70
	v_exp_f32_e32 v71, v71
	v_pk_add_f32 v[50:51], v[50:51], 1.0 op_sel_hi:[1,0]
	v_pk_add_f32 v[34:35], v[68:69], v[34:35] op_sel_hi:[0,1]
	v_rcp_f32_e32 v50, v50
	v_rcp_f32_e32 v51, v51
	v_pk_add_f32 v[70:71], v[70:71], 1.0 op_sel_hi:[1,0]
	v_pk_add_f32 v[16:17], v[68:69], v[16:17] op_sel_hi:[0,1]
	v_rcp_f32_e32 v70, v70
	v_rcp_f32_e32 v71, v71
	v_pk_mul_f32 v[48:49], v[50:51], v[48:49]
	v_pk_add_f32 v[50:51], v[68:69], v[52:53] op_sel_hi:[0,1]
	v_pk_mul_f32 v[48:49], v[48:49], v[50:51]
	v_pk_mul_f32 v[50:51], v[70:71], v[66:67]
	v_pk_add_f32 v[52:53], v[68:69], v[54:55] op_sel_hi:[0,1]
	v_pk_mul_f32 v[50:51], v[50:51], v[52:53]
	v_cvt_pk_bf16_f32 v130, v48, v49
	s_waitcnt vmcnt(6)
	v_permlane32_swap_b32_e32 v144, v146
	v_permlane32_swap_b32_e32 v145, v147
	v_lshlrev_b32_e32 v52, 16, v145
	v_cvt_pk_bf16_f32 v131, v50, v51
	s_nop 1
	v_permlane32_swap_b32_e32 v128, v130
	v_permlane32_swap_b32_e32 v129, v131
	global_store_dwordx4 v[136:137], v[128:131], off offset:1024
	v_lshlrev_b32_e32 v48, 16, v144
	v_and_b32_e32 v49, 0xffff0000, v144
	v_pk_mul_f32 v[50:51], v[48:49], v[48:49]
	v_and_b32_e32 v53, 0xffff0000, v145
	v_pk_fma_f32 v[50:51], v[50:51], s[8:9], 1.0 op_sel_hi:[1,0,0]
	v_pk_mul_f32 v[54:55], v[52:53], v[52:53]
	v_pk_mul_f32 v[50:51], v[50:51], v[48:49]
	v_pk_fma_f32 v[54:55], v[54:55], s[8:9], 1.0 op_sel_hi:[1,0,0]
	v_pk_mul_f32 v[50:51], v[50:51], s[34:35] op_sel_hi:[1,0]
	v_pk_mul_f32 v[54:55], v[54:55], v[52:53]
	v_exp_f32_e32 v50, v50
	v_exp_f32_e32 v51, v51
	v_pk_mul_f32 v[54:55], v[54:55], s[34:35] op_sel_hi:[1,0]
	v_pk_add_f32 v[18:19], v[68:69], v[18:19] op_sel_hi:[0,1]
	v_exp_f32_e32 v54, v54
	v_exp_f32_e32 v55, v55
	v_pk_add_f32 v[50:51], v[50:51], 1.0 op_sel_hi:[1,0]
	v_pk_add_f32 v[0:1], v[68:69], v[0:1] op_sel_hi:[0,1]
	v_rcp_f32_e32 v50, v50
	v_rcp_f32_e32 v51, v51
	v_pk_add_f32 v[54:55], v[54:55], 1.0 op_sel_hi:[1,0]
	v_pk_add_f32 v[2:3], v[68:69], v[2:3] op_sel_hi:[0,1]
	v_rcp_f32_e32 v54, v54
	v_rcp_f32_e32 v55, v55
	v_pk_mul_f32 v[48:49], v[50:51], v[48:49]
	v_pk_add_f32 v[50:51], v[68:69], v[56:57] op_sel_hi:[0,1]
	v_pk_mul_f32 v[48:49], v[48:49], v[50:51]
	v_pk_mul_f32 v[50:51], v[54:55], v[52:53]
	v_pk_add_f32 v[52:53], v[68:69], v[58:59] op_sel_hi:[0,1]
	v_pk_mul_f32 v[50:51], v[50:51], v[52:53]
	v_cvt_pk_bf16_f32 v132, v48, v49
	s_waitcnt vmcnt(7)
	v_lshlrev_b32_e32 v52, 16, v147
	v_cvt_pk_bf16_f32 v133, v50, v51
	v_lshlrev_b32_e32 v48, 16, v146
	v_and_b32_e32 v49, 0xffff0000, v146
	v_pk_mul_f32 v[50:51], v[48:49], v[48:49]
	v_and_b32_e32 v53, 0xffff0000, v147
	v_pk_fma_f32 v[50:51], v[50:51], s[8:9], 1.0 op_sel_hi:[1,0,0]
	v_pk_mul_f32 v[54:55], v[52:53], v[52:53]
	v_pk_mul_f32 v[50:51], v[50:51], v[48:49]
	v_pk_fma_f32 v[54:55], v[54:55], s[8:9], 1.0 op_sel_hi:[1,0,0]
	v_pk_mul_f32 v[50:51], v[50:51], s[34:35] op_sel_hi:[1,0]
	v_pk_mul_f32 v[54:55], v[54:55], v[52:53]
	v_exp_f32_e32 v50, v50
	v_exp_f32_e32 v51, v51
	v_pk_mul_f32 v[54:55], v[54:55], s[34:35] op_sel_hi:[1,0]
	s_andn2_b64 vcc, exec, s[12:13]
	v_exp_f32_e32 v54, v54
	v_exp_f32_e32 v55, v55
	v_pk_add_f32 v[50:51], v[50:51], 1.0 op_sel_hi:[1,0]
	v_mov_b32_e32 v76, 0
	v_rcp_f32_e32 v50, v50
	v_rcp_f32_e32 v51, v51
	v_pk_add_f32 v[54:55], v[54:55], 1.0 op_sel_hi:[1,0]
	v_mov_b32_e32 v77, 0
	v_rcp_f32_e32 v54, v54
	v_rcp_f32_e32 v55, v55
	v_pk_mul_f32 v[48:49], v[50:51], v[48:49]
	v_pk_add_f32 v[50:51], v[68:69], v[60:61] op_sel_hi:[0,1]
	v_pk_mul_f32 v[48:49], v[48:49], v[50:51]
	v_pk_mul_f32 v[50:51], v[54:55], v[52:53]
	v_pk_add_f32 v[52:53], v[68:69], v[62:63] op_sel_hi:[0,1]
	v_pk_mul_f32 v[50:51], v[50:51], v[52:53]
	v_cvt_pk_bf16_f32 v134, v48, v49
	s_waitcnt vmcnt(6)
	v_permlane32_swap_b32_e32 v148, v150
	v_permlane32_swap_b32_e32 v149, v151
	v_lshlrev_b32_e32 v52, 16, v149
	v_cvt_pk_bf16_f32 v135, v50, v51
	s_nop 1
	v_permlane32_swap_b32_e32 v132, v134
	v_permlane32_swap_b32_e32 v133, v135
	global_store_dwordx4 v[136:137], v[132:135], off offset:1056
	v_lshlrev_b32_e32 v48, 16, v148
	v_and_b32_e32 v49, 0xffff0000, v148
	v_pk_mul_f32 v[50:51], v[48:49], v[48:49]
	v_and_b32_e32 v53, 0xffff0000, v149
	v_pk_fma_f32 v[50:51], v[50:51], s[8:9], 1.0 op_sel_hi:[1,0,0]
	v_pk_mul_f32 v[54:55], v[52:53], v[52:53]
	v_pk_mul_f32 v[50:51], v[50:51], v[48:49]
	v_pk_fma_f32 v[54:55], v[54:55], s[8:9], 1.0 op_sel_hi:[1,0,0]
	v_pk_mul_f32 v[50:51], v[50:51], s[34:35] op_sel_hi:[1,0]
	v_pk_mul_f32 v[54:55], v[54:55], v[52:53]
	v_exp_f32_e32 v50, v50
	v_exp_f32_e32 v51, v51
	v_pk_mul_f32 v[54:55], v[54:55], s[34:35] op_sel_hi:[1,0]
	v_mov_b32_e32 v78, 0
	v_exp_f32_e32 v54, v54
	v_exp_f32_e32 v55, v55
	v_pk_add_f32 v[50:51], v[50:51], 1.0 op_sel_hi:[1,0]
	v_mov_b32_e32 v79, 0
	v_rcp_f32_e32 v50, v50
	v_rcp_f32_e32 v51, v51
	v_pk_add_f32 v[54:55], v[54:55], 1.0 op_sel_hi:[1,0]
	v_mov_b32_e32 v72, 0
	v_rcp_f32_e32 v54, v54
	v_rcp_f32_e32 v55, v55
	v_pk_mul_f32 v[48:49], v[50:51], v[48:49]
	v_mov_b32_e32 v73, 0
	v_pk_mul_f32 v[32:33], v[48:49], v[32:33]
	v_pk_mul_f32 v[48:49], v[54:55], v[52:53]
	v_cvt_pk_bf16_f32 v128, v32, v33
	v_mov_b32_e32 v74, 0
	v_pk_mul_f32 v[34:35], v[48:49], v[34:35]
	s_waitcnt vmcnt(7)
	v_lshlrev_b32_e32 v48, 16, v151
	v_cvt_pk_bf16_f32 v129, v34, v35
	v_lshlrev_b32_e32 v32, 16, v150
	v_and_b32_e32 v33, 0xffff0000, v150
	v_pk_mul_f32 v[34:35], v[32:33], v[32:33]
	v_and_b32_e32 v49, 0xffff0000, v151
	v_pk_fma_f32 v[34:35], v[34:35], s[8:9], 1.0 op_sel_hi:[1,0,0]
	v_pk_mul_f32 v[50:51], v[48:49], v[48:49]
	v_pk_mul_f32 v[34:35], v[34:35], v[32:33]
	v_pk_fma_f32 v[50:51], v[50:51], s[8:9], 1.0 op_sel_hi:[1,0,0]
	v_pk_mul_f32 v[34:35], v[34:35], s[34:35] op_sel_hi:[1,0]
	v_pk_mul_f32 v[50:51], v[50:51], v[48:49]
	v_exp_f32_e32 v34, v34
	v_exp_f32_e32 v35, v35
	v_pk_mul_f32 v[50:51], v[50:51], s[34:35] op_sel_hi:[1,0]
	v_mov_b32_e32 v75, 0
	v_exp_f32_e32 v50, v50
	v_exp_f32_e32 v51, v51
	v_pk_add_f32 v[34:35], v[34:35], 1.0 op_sel_hi:[1,0]
	v_pk_add_f32 v[50:51], v[50:51], 1.0 op_sel_hi:[1,0]
	v_rcp_f32_e32 v34, v34
	v_rcp_f32_e32 v35, v35
	v_rcp_f32_e32 v50, v50
	v_rcp_f32_e32 v51, v51
	v_pk_mul_f32 v[32:33], v[34:35], v[32:33]
	v_pk_add_f32 v[34:35], v[68:69], v[36:37] op_sel_hi:[0,1]
	v_pk_mul_f32 v[32:33], v[32:33], v[34:35]
	v_pk_mul_f32 v[34:35], v[50:51], v[48:49]
	v_pk_add_f32 v[36:37], v[68:69], v[38:39] op_sel_hi:[0,1]
	v_pk_mul_f32 v[34:35], v[34:35], v[36:37]
	v_cvt_pk_bf16_f32 v130, v32, v33
	s_waitcnt vmcnt(6)
	v_permlane32_swap_b32_e32 v152, v154
	v_permlane32_swap_b32_e32 v153, v155
	v_lshlrev_b32_e32 v36, 16, v153
	v_cvt_pk_bf16_f32 v131, v34, v35
	s_nop 1
	v_permlane32_swap_b32_e32 v128, v130
	v_permlane32_swap_b32_e32 v129, v131
	global_store_dwordx4 v[136:137], v[128:131], off offset:1088
	v_lshlrev_b32_e32 v32, 16, v152
	v_and_b32_e32 v33, 0xffff0000, v152
	v_pk_mul_f32 v[34:35], v[32:33], v[32:33]
	v_and_b32_e32 v37, 0xffff0000, v153
	v_pk_fma_f32 v[34:35], v[34:35], s[8:9], 1.0 op_sel_hi:[1,0,0]
	v_pk_mul_f32 v[38:39], v[36:37], v[36:37]
	v_pk_mul_f32 v[34:35], v[34:35], v[32:33]
	v_pk_fma_f32 v[38:39], v[38:39], s[8:9], 1.0 op_sel_hi:[1,0,0]
	v_pk_mul_f32 v[34:35], v[34:35], s[34:35] op_sel_hi:[1,0]
	v_pk_mul_f32 v[38:39], v[38:39], v[36:37]
	v_exp_f32_e32 v34, v34
	v_exp_f32_e32 v35, v35
	v_pk_mul_f32 v[38:39], v[38:39], s[34:35] op_sel_hi:[1,0]
	v_pk_add_f32 v[34:35], v[34:35], 1.0 op_sel_hi:[1,0]
	v_exp_f32_e32 v38, v38
	v_exp_f32_e32 v39, v39
	v_rcp_f32_e32 v34, v34
	v_rcp_f32_e32 v35, v35
	v_pk_add_f32 v[38:39], v[38:39], 1.0 op_sel_hi:[1,0]
	s_nop 0
	v_rcp_f32_e32 v38, v38
	v_rcp_f32_e32 v39, v39
	v_pk_mul_f32 v[32:33], v[34:35], v[32:33]
	v_pk_add_f32 v[34:35], v[68:69], v[40:41] op_sel_hi:[0,1]
	v_pk_mul_f32 v[32:33], v[32:33], v[34:35]
	v_pk_mul_f32 v[34:35], v[38:39], v[36:37]
	v_pk_add_f32 v[36:37], v[68:69], v[42:43] op_sel_hi:[0,1]
	v_pk_mul_f32 v[34:35], v[34:35], v[36:37]
	v_cvt_pk_bf16_f32 v132, v32, v33
	s_waitcnt vmcnt(7)
	v_lshlrev_b32_e32 v36, 16, v155
	v_cvt_pk_bf16_f32 v133, v34, v35
	v_lshlrev_b32_e32 v32, 16, v154
	v_and_b32_e32 v33, 0xffff0000, v154
	v_pk_mul_f32 v[34:35], v[32:33], v[32:33]
	v_and_b32_e32 v37, 0xffff0000, v155
	v_pk_fma_f32 v[34:35], v[34:35], s[8:9], 1.0 op_sel_hi:[1,0,0]
	v_pk_mul_f32 v[38:39], v[36:37], v[36:37]
	v_pk_mul_f32 v[34:35], v[34:35], v[32:33]
	v_pk_fma_f32 v[38:39], v[38:39], s[8:9], 1.0 op_sel_hi:[1,0,0]
	v_pk_mul_f32 v[34:35], v[34:35], s[34:35] op_sel_hi:[1,0]
	v_pk_mul_f32 v[38:39], v[38:39], v[36:37]
	v_exp_f32_e32 v34, v34
	v_exp_f32_e32 v35, v35
	v_pk_mul_f32 v[38:39], v[38:39], s[34:35] op_sel_hi:[1,0]
	v_pk_add_f32 v[34:35], v[34:35], 1.0 op_sel_hi:[1,0]
	v_exp_f32_e32 v38, v38
	v_exp_f32_e32 v39, v39
	v_rcp_f32_e32 v34, v34
	v_rcp_f32_e32 v35, v35
	v_pk_add_f32 v[38:39], v[38:39], 1.0 op_sel_hi:[1,0]
	s_nop 0
	v_rcp_f32_e32 v38, v38
	v_rcp_f32_e32 v39, v39
	v_pk_mul_f32 v[32:33], v[34:35], v[32:33]
	v_pk_add_f32 v[34:35], v[68:69], v[44:45] op_sel_hi:[0,1]
	v_pk_mul_f32 v[32:33], v[32:33], v[34:35]
	v_pk_mul_f32 v[34:35], v[38:39], v[36:37]
	v_pk_add_f32 v[36:37], v[68:69], v[46:47] op_sel_hi:[0,1]
	v_pk_mul_f32 v[34:35], v[34:35], v[36:37]
	v_cvt_pk_bf16_f32 v134, v32, v33
	s_waitcnt vmcnt(6)
	v_permlane32_swap_b32_e32 v156, v158
	v_permlane32_swap_b32_e32 v157, v159
	v_lshlrev_b32_e32 v36, 16, v157
	v_cvt_pk_bf16_f32 v135, v34, v35
	s_nop 1
	v_permlane32_swap_b32_e32 v132, v134
	v_permlane32_swap_b32_e32 v133, v135
	global_store_dwordx4 v[136:137], v[132:135], off offset:1120
	v_lshlrev_b32_e32 v32, 16, v156
	v_and_b32_e32 v33, 0xffff0000, v156
	v_pk_mul_f32 v[34:35], v[32:33], v[32:33]
	v_and_b32_e32 v37, 0xffff0000, v157
	v_pk_fma_f32 v[34:35], v[34:35], s[8:9], 1.0 op_sel_hi:[1,0,0]
	v_pk_mul_f32 v[38:39], v[36:37], v[36:37]
	v_pk_mul_f32 v[34:35], v[34:35], v[32:33]
	v_pk_fma_f32 v[38:39], v[38:39], s[8:9], 1.0 op_sel_hi:[1,0,0]
	v_pk_mul_f32 v[34:35], v[34:35], s[34:35] op_sel_hi:[1,0]
	v_pk_mul_f32 v[38:39], v[38:39], v[36:37]
	v_exp_f32_e32 v34, v34
	v_exp_f32_e32 v35, v35
	v_pk_mul_f32 v[38:39], v[38:39], s[34:35] op_sel_hi:[1,0]
	v_pk_add_f32 v[34:35], v[34:35], 1.0 op_sel_hi:[1,0]
	v_exp_f32_e32 v38, v38
	v_exp_f32_e32 v39, v39
	v_rcp_f32_e32 v34, v34
	v_rcp_f32_e32 v35, v35
	v_pk_add_f32 v[38:39], v[38:39], 1.0 op_sel_hi:[1,0]
	s_nop 0
	v_rcp_f32_e32 v38, v38
	v_rcp_f32_e32 v39, v39
	v_pk_mul_f32 v[32:33], v[34:35], v[32:33]
	s_nop 0
	v_pk_mul_f32 v[16:17], v[32:33], v[16:17]
	v_pk_mul_f32 v[32:33], v[38:39], v[36:37]
	v_cvt_pk_bf16_f32 v128, v16, v17
	s_nop 0
	v_pk_mul_f32 v[18:19], v[32:33], v[18:19]
	s_waitcnt vmcnt(7)
	v_lshlrev_b32_e32 v32, 16, v159
	v_cvt_pk_bf16_f32 v129, v18, v19
	v_lshlrev_b32_e32 v16, 16, v158
	v_and_b32_e32 v17, 0xffff0000, v158
	v_pk_mul_f32 v[18:19], v[16:17], v[16:17]
	v_and_b32_e32 v33, 0xffff0000, v159
	v_pk_fma_f32 v[18:19], v[18:19], s[8:9], 1.0 op_sel_hi:[1,0,0]
	v_pk_mul_f32 v[34:35], v[32:33], v[32:33]
	v_pk_mul_f32 v[18:19], v[18:19], v[16:17]
	v_pk_fma_f32 v[34:35], v[34:35], s[8:9], 1.0 op_sel_hi:[1,0,0]
	v_pk_mul_f32 v[18:19], v[18:19], s[34:35] op_sel_hi:[1,0]
	v_pk_mul_f32 v[34:35], v[34:35], v[32:33]
	v_exp_f32_e32 v18, v18
	v_exp_f32_e32 v19, v19
	v_pk_mul_f32 v[34:35], v[34:35], s[34:35] op_sel_hi:[1,0]
	v_pk_add_f32 v[18:19], v[18:19], 1.0 op_sel_hi:[1,0]
	v_exp_f32_e32 v34, v34
	v_exp_f32_e32 v35, v35
	v_rcp_f32_e32 v18, v18
	v_rcp_f32_e32 v19, v19
	v_pk_add_f32 v[34:35], v[34:35], 1.0 op_sel_hi:[1,0]
	s_nop 0
	v_rcp_f32_e32 v34, v34
	v_rcp_f32_e32 v35, v35
	v_pk_mul_f32 v[16:17], v[18:19], v[16:17]
	v_pk_add_f32 v[18:19], v[68:69], v[20:21] op_sel_hi:[0,1]
	v_pk_mul_f32 v[16:17], v[16:17], v[18:19]
	v_pk_mul_f32 v[18:19], v[34:35], v[32:33]
	v_pk_add_f32 v[20:21], v[68:69], v[22:23] op_sel_hi:[0,1]
	v_pk_mul_f32 v[18:19], v[18:19], v[20:21]
	v_cvt_pk_bf16_f32 v130, v16, v17
	s_waitcnt vmcnt(6)
	v_permlane32_swap_b32_e32 v160, v162
	v_permlane32_swap_b32_e32 v161, v163
	v_lshlrev_b32_e32 v20, 16, v161
	v_cvt_pk_bf16_f32 v131, v18, v19
	s_nop 1
	v_permlane32_swap_b32_e32 v128, v130
	v_permlane32_swap_b32_e32 v129, v131
	global_store_dwordx4 v[136:137], v[128:131], off offset:1152
	v_lshlrev_b32_e32 v16, 16, v160
	v_and_b32_e32 v17, 0xffff0000, v160
	v_pk_mul_f32 v[18:19], v[16:17], v[16:17]
	v_and_b32_e32 v21, 0xffff0000, v161
	v_pk_fma_f32 v[18:19], v[18:19], s[8:9], 1.0 op_sel_hi:[1,0,0]
	v_pk_mul_f32 v[22:23], v[20:21], v[20:21]
	v_pk_mul_f32 v[18:19], v[18:19], v[16:17]
	v_pk_fma_f32 v[22:23], v[22:23], s[8:9], 1.0 op_sel_hi:[1,0,0]
	v_pk_mul_f32 v[18:19], v[18:19], s[34:35] op_sel_hi:[1,0]
	v_pk_mul_f32 v[22:23], v[22:23], v[20:21]
	v_exp_f32_e32 v18, v18
	v_exp_f32_e32 v19, v19
	v_pk_mul_f32 v[22:23], v[22:23], s[34:35] op_sel_hi:[1,0]
	v_pk_add_f32 v[18:19], v[18:19], 1.0 op_sel_hi:[1,0]
	v_exp_f32_e32 v22, v22
	v_exp_f32_e32 v23, v23
	v_rcp_f32_e32 v18, v18
	v_rcp_f32_e32 v19, v19
	v_pk_add_f32 v[22:23], v[22:23], 1.0 op_sel_hi:[1,0]
	s_nop 0
	v_rcp_f32_e32 v22, v22
	v_rcp_f32_e32 v23, v23
	v_pk_mul_f32 v[16:17], v[18:19], v[16:17]
	v_pk_add_f32 v[18:19], v[68:69], v[24:25] op_sel_hi:[0,1]
	v_pk_mul_f32 v[16:17], v[16:17], v[18:19]
	v_pk_mul_f32 v[18:19], v[22:23], v[20:21]
	v_pk_add_f32 v[20:21], v[68:69], v[26:27] op_sel_hi:[0,1]
	v_pk_mul_f32 v[18:19], v[18:19], v[20:21]
	v_cvt_pk_bf16_f32 v132, v16, v17
	s_waitcnt vmcnt(7)
	v_lshlrev_b32_e32 v20, 16, v163
	v_cvt_pk_bf16_f32 v133, v18, v19
	v_lshlrev_b32_e32 v16, 16, v162
	v_and_b32_e32 v17, 0xffff0000, v162
	v_pk_mul_f32 v[18:19], v[16:17], v[16:17]
	v_and_b32_e32 v21, 0xffff0000, v163
	v_pk_fma_f32 v[18:19], v[18:19], s[8:9], 1.0 op_sel_hi:[1,0,0]
	v_pk_mul_f32 v[22:23], v[20:21], v[20:21]
	v_pk_mul_f32 v[18:19], v[18:19], v[16:17]
	v_pk_fma_f32 v[22:23], v[22:23], s[8:9], 1.0 op_sel_hi:[1,0,0]
	v_pk_mul_f32 v[18:19], v[18:19], s[34:35] op_sel_hi:[1,0]
	v_pk_mul_f32 v[22:23], v[22:23], v[20:21]
	v_exp_f32_e32 v18, v18
	v_exp_f32_e32 v19, v19
	v_pk_mul_f32 v[22:23], v[22:23], s[34:35] op_sel_hi:[1,0]
	v_pk_add_f32 v[18:19], v[18:19], 1.0 op_sel_hi:[1,0]
	v_exp_f32_e32 v22, v22
	v_exp_f32_e32 v23, v23
	v_rcp_f32_e32 v18, v18
	v_rcp_f32_e32 v19, v19
	v_pk_add_f32 v[22:23], v[22:23], 1.0 op_sel_hi:[1,0]
	s_nop 0
	v_rcp_f32_e32 v22, v22
	v_rcp_f32_e32 v23, v23
	v_pk_mul_f32 v[16:17], v[18:19], v[16:17]
	v_pk_add_f32 v[18:19], v[68:69], v[28:29] op_sel_hi:[0,1]
	v_pk_mul_f32 v[16:17], v[16:17], v[18:19]
	v_pk_mul_f32 v[18:19], v[22:23], v[20:21]
	v_pk_add_f32 v[20:21], v[68:69], v[30:31] op_sel_hi:[0,1]
	v_pk_mul_f32 v[18:19], v[18:19], v[20:21]
	v_cvt_pk_bf16_f32 v134, v16, v17
	s_waitcnt vmcnt(6)
	v_permlane32_swap_b32_e32 v164, v166
	v_permlane32_swap_b32_e32 v165, v167
	v_lshlrev_b32_e32 v20, 16, v165
	v_cvt_pk_bf16_f32 v135, v18, v19
	s_nop 1
	v_permlane32_swap_b32_e32 v132, v134
	v_permlane32_swap_b32_e32 v133, v135
	global_store_dwordx4 v[136:137], v[132:135], off offset:1184
	v_lshlrev_b32_e32 v16, 16, v164
	v_and_b32_e32 v17, 0xffff0000, v164
	v_pk_mul_f32 v[18:19], v[16:17], v[16:17]
	v_and_b32_e32 v21, 0xffff0000, v165
	v_pk_fma_f32 v[18:19], v[18:19], s[8:9], 1.0 op_sel_hi:[1,0,0]
	v_pk_mul_f32 v[22:23], v[20:21], v[20:21]
	v_pk_mul_f32 v[18:19], v[18:19], v[16:17]
	v_pk_fma_f32 v[22:23], v[22:23], s[8:9], 1.0 op_sel_hi:[1,0,0]
	v_pk_mul_f32 v[18:19], v[18:19], s[34:35] op_sel_hi:[1,0]
	v_pk_mul_f32 v[22:23], v[22:23], v[20:21]
	v_exp_f32_e32 v18, v18
	v_exp_f32_e32 v19, v19
	v_pk_mul_f32 v[22:23], v[22:23], s[34:35] op_sel_hi:[1,0]
	v_pk_add_f32 v[18:19], v[18:19], 1.0 op_sel_hi:[1,0]
	v_exp_f32_e32 v22, v22
	v_exp_f32_e32 v23, v23
	v_rcp_f32_e32 v18, v18
	v_rcp_f32_e32 v19, v19
	v_pk_add_f32 v[22:23], v[22:23], 1.0 op_sel_hi:[1,0]
	s_nop 0
	v_rcp_f32_e32 v22, v22
	v_rcp_f32_e32 v23, v23
	v_pk_mul_f32 v[16:17], v[18:19], v[16:17]
	s_nop 0
	v_pk_mul_f32 v[0:1], v[16:17], v[0:1]
	v_pk_mul_f32 v[16:17], v[22:23], v[20:21]
	v_cvt_pk_bf16_f32 v128, v0, v1
	s_nop 0
	v_pk_mul_f32 v[2:3], v[16:17], v[2:3]
	s_waitcnt vmcnt(7)
	v_lshlrev_b32_e32 v16, 16, v167
	v_cvt_pk_bf16_f32 v129, v2, v3
	v_lshlrev_b32_e32 v0, 16, v166
	v_and_b32_e32 v1, 0xffff0000, v166
	v_pk_mul_f32 v[2:3], v[0:1], v[0:1]
	v_and_b32_e32 v17, 0xffff0000, v167
	v_pk_fma_f32 v[2:3], v[2:3], s[8:9], 1.0 op_sel_hi:[1,0,0]
	v_pk_mul_f32 v[18:19], v[16:17], v[16:17]
	v_pk_mul_f32 v[2:3], v[2:3], v[0:1]
	v_pk_fma_f32 v[18:19], v[18:19], s[8:9], 1.0 op_sel_hi:[1,0,0]
	v_pk_mul_f32 v[2:3], v[2:3], s[34:35] op_sel_hi:[1,0]
	v_pk_mul_f32 v[18:19], v[18:19], v[16:17]
	v_exp_f32_e32 v2, v2
	v_exp_f32_e32 v3, v3
	v_pk_mul_f32 v[18:19], v[18:19], s[34:35] op_sel_hi:[1,0]
	v_pk_add_f32 v[2:3], v[2:3], 1.0 op_sel_hi:[1,0]
	v_exp_f32_e32 v18, v18
	v_exp_f32_e32 v19, v19
	v_rcp_f32_e32 v2, v2
	v_rcp_f32_e32 v3, v3
	v_pk_add_f32 v[18:19], v[18:19], 1.0 op_sel_hi:[1,0]
	s_nop 0
	v_rcp_f32_e32 v18, v18
	v_rcp_f32_e32 v19, v19
	v_pk_mul_f32 v[0:1], v[2:3], v[0:1]
	v_pk_add_f32 v[2:3], v[68:69], v[4:5] op_sel_hi:[0,1]
	v_pk_mul_f32 v[0:1], v[0:1], v[2:3]
	v_pk_mul_f32 v[2:3], v[18:19], v[16:17]
	v_pk_add_f32 v[4:5], v[68:69], v[6:7] op_sel_hi:[0,1]
	v_pk_mul_f32 v[2:3], v[2:3], v[4:5]
	v_cvt_pk_bf16_f32 v130, v0, v1
	s_waitcnt vmcnt(6)
	v_permlane32_swap_b32_e32 v168, v170
	v_permlane32_swap_b32_e32 v169, v171
	v_lshlrev_b32_e32 v4, 16, v169
	v_cvt_pk_bf16_f32 v131, v2, v3
	s_nop 1
	v_permlane32_swap_b32_e32 v128, v130
	v_permlane32_swap_b32_e32 v129, v131
	global_store_dwordx4 v[136:137], v[128:131], off offset:1216
	v_lshlrev_b32_e32 v0, 16, v168
	v_and_b32_e32 v1, 0xffff0000, v168
	v_pk_mul_f32 v[2:3], v[0:1], v[0:1]
	v_and_b32_e32 v5, 0xffff0000, v169
	v_pk_fma_f32 v[2:3], v[2:3], s[8:9], 1.0 op_sel_hi:[1,0,0]
	v_pk_mul_f32 v[6:7], v[4:5], v[4:5]
	v_pk_mul_f32 v[2:3], v[2:3], v[0:1]
	v_pk_fma_f32 v[6:7], v[6:7], s[8:9], 1.0 op_sel_hi:[1,0,0]
	v_pk_mul_f32 v[2:3], v[2:3], s[34:35] op_sel_hi:[1,0]
	v_pk_mul_f32 v[6:7], v[6:7], v[4:5]
	v_exp_f32_e32 v2, v2
	v_exp_f32_e32 v3, v3
	v_pk_mul_f32 v[6:7], v[6:7], s[34:35] op_sel_hi:[1,0]
	v_pk_add_f32 v[2:3], v[2:3], 1.0 op_sel_hi:[1,0]
	v_exp_f32_e32 v6, v6
	v_exp_f32_e32 v7, v7
	v_rcp_f32_e32 v2, v2
	v_rcp_f32_e32 v3, v3
	v_pk_add_f32 v[6:7], v[6:7], 1.0 op_sel_hi:[1,0]
	s_nop 0
	v_rcp_f32_e32 v6, v6
	v_rcp_f32_e32 v7, v7
	v_pk_mul_f32 v[0:1], v[2:3], v[0:1]
	v_pk_add_f32 v[2:3], v[68:69], v[8:9] op_sel_hi:[0,1]
	v_pk_mul_f32 v[0:1], v[0:1], v[2:3]
	v_pk_mul_f32 v[2:3], v[6:7], v[4:5]
	v_pk_add_f32 v[4:5], v[68:69], v[10:11] op_sel_hi:[0,1]
	v_pk_mul_f32 v[2:3], v[2:3], v[4:5]
	v_cvt_pk_bf16_f32 v132, v0, v1
	s_waitcnt vmcnt(7)
	v_lshlrev_b32_e32 v4, 16, v171
	v_cvt_pk_bf16_f32 v133, v2, v3
	v_lshlrev_b32_e32 v0, 16, v170
	v_and_b32_e32 v1, 0xffff0000, v170
	v_pk_mul_f32 v[2:3], v[0:1], v[0:1]
	v_and_b32_e32 v5, 0xffff0000, v171
	v_pk_fma_f32 v[2:3], v[2:3], s[8:9], 1.0 op_sel_hi:[1,0,0]
	v_pk_mul_f32 v[6:7], v[4:5], v[4:5]
	v_pk_mul_f32 v[2:3], v[2:3], v[0:1]
	v_pk_fma_f32 v[6:7], v[6:7], s[8:9], 1.0 op_sel_hi:[1,0,0]
	v_pk_mul_f32 v[2:3], v[2:3], s[34:35] op_sel_hi:[1,0]
	v_pk_mul_f32 v[6:7], v[6:7], v[4:5]
	v_exp_f32_e32 v2, v2
	v_exp_f32_e32 v3, v3
	v_pk_mul_f32 v[6:7], v[6:7], s[34:35] op_sel_hi:[1,0]
	v_cndmask_b32_e64 v10, 0, 1, s[12:13]
	v_exp_f32_e32 v6, v6
	v_exp_f32_e32 v7, v7
	v_pk_add_f32 v[2:3], v[2:3], 1.0 op_sel_hi:[1,0]
	v_cmp_ne_u32_e64 s[8:9], 1, v10
	v_rcp_f32_e32 v2, v2
	v_rcp_f32_e32 v3, v3
	v_pk_add_f32 v[6:7], v[6:7], 1.0 op_sel_hi:[1,0]
	v_pk_mul_f32 v[0:1], v[2:3], v[0:1]
	v_rcp_f32_e32 v6, v6
	v_rcp_f32_e32 v7, v7
	v_pk_add_f32 v[2:3], v[68:69], v[12:13] op_sel_hi:[0,1]
	v_pk_mul_f32 v[0:1], v[0:1], v[2:3]
	v_pk_mul_f32 v[2:3], v[6:7], v[4:5]
	v_pk_add_f32 v[4:5], v[68:69], v[14:15] op_sel_hi:[0,1]
	v_cvt_pk_bf16_f32 v134, v0, v1
	v_pk_mul_f32 v[2:3], v[2:3], v[4:5]
	s_nop 0
	v_cvt_pk_bf16_f32 v135, v2, v3
	s_nop 1
	v_permlane32_swap_b32_e32 v132, v134
	v_permlane32_swap_b32_e32 v133, v135
	global_store_dwordx4 v[136:137], v[132:135], off offset:1248
	v_mov_b32_e32 v0, 0x60
	v_bitop3_b32 v0, v124, s37, v0 bitop3:0xde
	v_lshlrev_b32_e32 v0, 9, v0
	v_mov_b32_e32 v1, v123
	v_lshl_add_u64 v[8:9], v[90:91], 0, v[0:1]
	global_load_dwordx4 v[0:3], v[8:9], off offset:16
	global_load_dwordx4 v[4:7], v[8:9], off
	global_load_dwordx4 v[112:115], v[8:9], off offset:80
	global_load_dwordx4 v[116:119], v[8:9], off offset:64
	global_load_dwordx4 v[104:107], v[8:9], off offset:144
	global_load_dwordx4 v[108:111], v[8:9], off offset:128
	global_load_dwordx4 v[96:99], v[8:9], off offset:208
	global_load_dwordx4 v[100:103], v[8:9], off offset:192
	global_load_dwordx4 v[88:91], v[8:9], off offset:272
	global_load_dwordx4 v[92:95], v[8:9], off offset:256
	global_load_dwordx4 v[80:83], v[8:9], off offset:336
	global_load_dwordx4 v[84:87], v[8:9], off offset:320
	s_cbranch_vccnz .LBB0_412
	global_load_dwordx4 v[76:79], v[8:9], off offset:384
	global_load_dwordx4 v[72:75], v[8:9], off offset:400

.LBB0_414:
	s_movk_i32 s12, 0x7fff
	s_waitcnt vmcnt(8)
	v_bfe_u32 v68, v116, 16, 1
	v_add3_u32 v68, v116, v68, s12
	v_bfe_u32 v116, v117, 16, 1
	s_mov_b32 s13, 0xffff0000
	v_lshrrev_b32_e32 v68, 16, v68
	v_add3_u32 v116, v117, v116, s12
	v_and_or_b32 v116, v116, s13, v68
	v_bfe_u32 v68, v118, 16, 1
	v_add3_u32 v68, v118, v68, s12
	v_bfe_u32 v117, v119, 16, 1
	v_lshrrev_b32_e32 v68, 16, v68
	v_add3_u32 v117, v119, v117, s12
	v_and_or_b32 v117, v117, s13, v68
	v_bfe_u32 v68, v112, 16, 1
	v_add3_u32 v68, v112, v68, s12
	v_bfe_u32 v112, v113, 16, 1
	v_lshrrev_b32_e32 v68, 16, v68
	v_add3_u32 v112, v113, v112, s12
	v_and_or_b32 v118, v112, s13, v68
	v_bfe_u32 v68, v114, 16, 1
	v_add3_u32 v68, v114, v68, s12
	v_bfe_u32 v112, v115, 16, 1
	v_lshrrev_b32_e32 v68, 16, v68
	v_add3_u32 v112, v115, v112, s12
	v_and_or_b32 v119, v112, s13, v68
	s_waitcnt vmcnt(6)
	v_bfe_u32 v68, v108, 16, 1
	v_bfe_u32 v8, v4, 16, 1
	v_add3_u32 v68, v108, v68, s12
	v_bfe_u32 v108, v109, 16, 1
	v_add3_u32 v4, v4, v8, s12
	v_bfe_u32 v8, v5, 16, 1
	v_lshrrev_b32_e32 v68, 16, v68
	v_add3_u32 v108, v109, v108, s12
	v_lshrrev_b32_e32 v4, 16, v4
	v_add3_u32 v5, v5, v8, s12
	v_and_or_b32 v108, v108, s13, v68
	v_bfe_u32 v68, v110, 16, 1
	v_and_or_b32 v4, v5, s13, v4
	v_bfe_u32 v5, v6, 16, 1
	v_add3_u32 v68, v110, v68, s12
	v_bfe_u32 v109, v111, 16, 1
	v_add3_u32 v5, v6, v5, s12
	v_bfe_u32 v6, v7, 16, 1
	v_lshrrev_b32_e32 v68, 16, v68
	v_add3_u32 v109, v111, v109, s12
	v_lshrrev_b32_e32 v5, 16, v5
	v_add3_u32 v6, v7, v6, s12
	v_and_or_b32 v109, v109, s13, v68
	v_bfe_u32 v68, v104, 16, 1
	v_and_or_b32 v5, v6, s13, v5
	v_bfe_u32 v6, v0, 16, 1
	v_add3_u32 v68, v104, v68, s12
	v_bfe_u32 v104, v105, 16, 1
	v_add3_u32 v0, v0, v6, s12
	v_bfe_u32 v6, v1, 16, 1
	ds_read_b128 v[8:11], v121
	ds_read_b128 v[126:129], v121 offset:32
	v_lshrrev_b32_e32 v68, 16, v68
	v_add3_u32 v104, v105, v104, s12
	v_lshrrev_b32_e32 v0, 16, v0
	v_add3_u32 v1, v1, v6, s12
	v_and_or_b32 v110, v104, s13, v68
	v_bfe_u32 v68, v106, 16, 1
	v_and_or_b32 v6, v1, s13, v0
	v_bfe_u32 v0, v2, 16, 1
	v_add3_u32 v68, v106, v68, s12
	v_bfe_u32 v104, v107, 16, 1
	v_add3_u32 v0, v2, v0, s12
	v_bfe_u32 v1, v3, 16, 1
	v_lshrrev_b32_e32 v68, 16, v68
	v_add3_u32 v104, v107, v104, s12
	v_lshrrev_b32_e32 v0, 16, v0
	v_add3_u32 v1, v3, v1, s12
	v_and_or_b32 v111, v104, s13, v68
	s_waitcnt vmcnt(4)
	v_bfe_u32 v68, v100, 16, 1
	v_and_or_b32 v7, v1, s13, v0
	ds_read_b128 v[0:3], v121 offset:8704
	ds_read_b128 v[130:133], v121 offset:8736
	v_add3_u32 v68, v100, v68, s12
	v_bfe_u32 v100, v101, 16, 1
	v_lshrrev_b32_e32 v68, 16, v68
	v_add3_u32 v100, v101, v100, s12
	v_and_or_b32 v100, v100, s13, v68
	v_bfe_u32 v68, v102, 16, 1
	v_add3_u32 v68, v102, v68, s12
	v_bfe_u32 v101, v103, 16, 1
	s_waitcnt lgkmcnt(3)
	v_mfma_f32_32x32x16_bf16 v[48:63], v[8:11], v[4:7], 0
	v_lshrrev_b32_e32 v68, 16, v68
	v_add3_u32 v101, v103, v101, s12
	v_and_or_b32 v101, v101, s13, v68
	v_bfe_u32 v68, v96, 16, 1
	v_add3_u32 v68, v96, v68, s12
	v_bfe_u32 v96, v97, 16, 1
	v_lshrrev_b32_e32 v68, 16, v68
	s_waitcnt lgkmcnt(1)
	v_mfma_f32_32x32x16_bf16 v[32:47], v[0:3], v[4:7], 0
	ds_read_b128 v[0:3], v121 offset:17408
	ds_read_b128 v[134:137], v121 offset:17440
	v_add3_u32 v96, v97, v96, s12
	v_and_or_b32 v102, v96, s13, v68
	v_bfe_u32 v68, v98, 16, 1
	v_add3_u32 v68, v98, v68, s12
	v_bfe_u32 v96, v99, 16, 1
	v_lshrrev_b32_e32 v68, 16, v68
	s_waitcnt lgkmcnt(1)
	v_mfma_f32_32x32x16_bf16 v[16:31], v[0:3], v[4:7], 0
	ds_read_b128 v[0:3], v121 offset:26112
	ds_read_b128 v[138:141], v121 offset:26144
	v_add3_u32 v96, v99, v96, s12
	ds_read_b128 v[112:115], v121 offset:64
	ds_read_b128 v[104:107], v121 offset:96
	v_and_or_b32 v103, v96, s13, v68
	v_or_b32_e32 v68, 64, v120
	v_cmp_le_u32_e32 vcc, v68, v125
	s_waitcnt lgkmcnt(3)
	v_mfma_f32_32x32x16_bf16 v[0:15], v[0:3], v[4:7], 0
	s_waitcnt vmcnt(2)
	v_cndmask_b32_e32 v92, 0, v92, vcc
	v_cmp_lt_u32_e32 vcc, v68, v125
	s_nop 1
	v_cndmask_b32_e32 v68, 0, v93, vcc
	v_bfe_u32 v93, v92, 16, 1
	v_mfma_f32_32x32x16_bf16 v[48:63], v[126:129], v[116:119], v[48:63]
	v_add3_u32 v92, v92, v93, s12
	v_bfe_u32 v93, v68, 16, 1
	v_lshrrev_b32_e32 v92, 16, v92
	v_add3_u32 v68, v68, v93, s12
	v_and_or_b32 v92, v68, s13, v92
	v_or_b32_e32 v68, 0x42, v120
	v_cmp_le_u32_e32 vcc, v68, v125
	v_mfma_f32_32x32x16_bf16 v[32:47], v[130:133], v[116:119], v[32:47]
	v_or_b32_e32 v93, 0x43, v120
	v_cndmask_b32_e32 v68, 0, v94, vcc
	v_cmp_le_u32_e32 vcc, v93, v125
	v_bfe_u32 v94, v68, 16, 1
	v_add3_u32 v68, v68, v94, s12
	v_cndmask_b32_e32 v93, 0, v95, vcc
	v_bfe_u32 v94, v93, 16, 1
	v_mfma_f32_32x32x16_bf16 v[16:31], v[134:137], v[116:119], v[16:31]
	v_lshrrev_b32_e32 v68, 16, v68
	v_add3_u32 v93, v93, v94, s12
	v_and_or_b32 v93, v93, s13, v68
	v_or_b32_e32 v68, 0x44, v120
	v_cmp_le_u32_e32 vcc, v68, v125
	s_waitcnt lgkmcnt(2)
	v_mfma_f32_32x32x16_bf16 v[0:15], v[138:141], v[116:119], v[0:15]
	v_cndmask_b32_e32 v68, 0, v88, vcc
	v_or_b32_e32 v88, 0x45, v120
	v_cmp_le_u32_e32 vcc, v88, v125
	s_nop 1
	v_cndmask_b32_e32 v88, 0, v89, vcc
	v_bfe_u32 v89, v68, 16, 1
	s_waitcnt lgkmcnt(1)
	v_mfma_f32_32x32x16_bf16 v[48:63], v[112:115], v[108:111], v[48:63]
	ds_read_b128 v[112:115], v121 offset:8768
	ds_read_b128 v[116:119], v121 offset:8800
	v_add3_u32 v68, v68, v89, s12
	v_bfe_u32 v89, v88, 16, 1
	v_lshrrev_b32_e32 v68, 16, v68
	v_add3_u32 v88, v88, v89, s12
	v_and_or_b32 v94, v88, s13, v68
	v_or_b32_e32 v68, 0x46, v120
	s_waitcnt lgkmcnt(1)
	v_mfma_f32_32x32x16_bf16 v[32:47], v[112:115], v[108:111], v[32:47]
	ds_read_b128 v[112:115], v121 offset:17472
	ds_read_b128 v[126:129], v121 offset:17504
	v_cmp_le_u32_e32 vcc, v68, v125
	v_or_b32_e32 v88, 0x47, v120
	s_nop 0
	v_cndmask_b32_e32 v68, 0, v90, vcc
	v_cmp_le_u32_e32 vcc, v88, v125
	v_bfe_u32 v89, v68, 16, 1
	s_waitcnt lgkmcnt(1)
	v_mfma_f32_32x32x16_bf16 v[16:31], v[112:115], v[108:111], v[16:31]
	ds_read_b128 v[112:115], v121 offset:26176
	ds_read_b128 v[130:133], v121 offset:26208
	ds_read_b128 v[96:99], v121 offset:128
	v_cndmask_b32_e32 v88, 0, v91, vcc
	v_add3_u32 v68, v68, v89, s12
	v_bfe_u32 v89, v88, 16, 1
	v_lshrrev_b32_e32 v68, 16, v68
	v_add3_u32 v88, v88, v89, s12
	v_mfma_f32_32x32x16_bf16 v[48:63], v[104:107], v[100:103], v[48:63]
	v_and_or_b32 v95, v88, s13, v68
	ds_read_b128 v[88:91], v121 offset:160
	v_xor_b32_e32 v68, 32, v124
	v_add_lshl_u32 v68, v68, s37, 2
	v_mov_b64_e32 v[104:105], s[22:23]
	s_waitcnt lgkmcnt(3)
	v_mfma_f32_32x32x16_bf16 v[0:15], v[112:115], v[108:111], v[0:15]
	v_or_b32_e32 v110, s18, v125
	v_mov_b32_e32 v111, s19
	s_waitcnt lgkmcnt(1)
	v_mfma_f32_32x32x16_bf16 v[48:63], v[96:99], v[92:95], v[48:63]
	ds_read_b128 v[96:99], v121 offset:8832
	v_mfma_f32_32x32x16_bf16 v[32:47], v[116:119], v[100:103], v[32:47]
	v_mfma_f32_32x32x16_bf16 v[16:31], v[126:129], v[100:103], v[16:31]
	v_mfma_f32_32x32x16_bf16 v[0:15], v[130:133], v[100:103], v[0:15]
	ds_read_b128 v[100:103], v121 offset:17536
	ds_read_b128 v[114:117], v121 offset:8864
	global_load_dword v68, v68, s[14:15] offset:256
	s_movk_i32 s14, 0x1400
	s_waitcnt lgkmcnt(2)
	v_mfma_f32_32x32x16_bf16 v[32:47], v[96:99], v[92:95], v[32:47]
	ds_read_b128 v[96:99], v121 offset:26240
	ds_read_b128 v[126:129], v121 offset:17568
	ds_read_b128 v[130:133], v121 offset:26272
	s_waitcnt lgkmcnt(4)
	v_mfma_f32_32x32x16_bf16 v[16:31], v[100:103], v[92:95], v[16:31]
	v_mad_u64_u32 v[100:101], s[14:15], v110, s14, v[104:105]
	v_mov_b32_e32 v102, 0x1400
	v_mad_u32_u24 v101, s19, v102, v101
	v_lshl_add_u64 v[100:101], v[100:101], 0, s[16:17]
	s_waitcnt lgkmcnt(2)
	v_mfma_f32_32x32x16_bf16 v[0:15], v[96:99], v[92:95], v[0:15]
	v_or_b32_e32 v92, 0x50, v120
	v_cmp_le_u32_e32 vcc, v92, v125
	s_waitcnt vmcnt(1)
	s_nop 0
	v_cndmask_b32_e32 v84, 0, v84, vcc
	v_cmp_lt_u32_e32 vcc, v92, v125
	v_bfe_u32 v92, v84, 16, 1
	v_add3_u32 v84, v84, v92, s12
	v_cndmask_b32_e32 v85, 0, v85, vcc
	v_bfe_u32 v92, v85, 16, 1
	v_lshrrev_b32_e32 v84, 16, v84
	v_add3_u32 v85, v85, v92, s12
	v_and_or_b32 v134, v85, s13, v84
	v_or_b32_e32 v84, 0x52, v120
	v_cmp_le_u32_e32 vcc, v84, v125
	v_or_b32_e32 v85, 0x53, v120
	s_nop 0
	v_cndmask_b32_e32 v84, 0, v86, vcc
	v_cmp_le_u32_e32 vcc, v85, v125
	v_bfe_u32 v86, v84, 16, 1
	v_add3_u32 v84, v84, v86, s12
	v_cndmask_b32_e32 v85, 0, v87, vcc
	v_bfe_u32 v86, v85, 16, 1
	v_lshrrev_b32_e32 v84, 16, v84
	v_add3_u32 v85, v85, v86, s12
	v_and_or_b32 v135, v85, s13, v84
	v_or_b32_e32 v84, 0x54, v120
	v_cmp_le_u32_e32 vcc, v84, v125
	v_or_b32_e32 v84, 0x55, v120
	s_nop 0
	v_cndmask_b32_e32 v80, 0, v80, vcc
	v_cmp_le_u32_e32 vcc, v84, v125
	v_bfe_u32 v84, v80, 16, 1
	v_add3_u32 v80, v80, v84, s12
	v_cndmask_b32_e32 v81, 0, v81, vcc
	v_bfe_u32 v84, v81, 16, 1
	v_lshrrev_b32_e32 v80, 16, v80
	v_add3_u32 v81, v81, v84, s12
	v_and_or_b32 v136, v81, s13, v80
	v_or_b32_e32 v80, 0x56, v120
	v_cmp_le_u32_e32 vcc, v80, v125
	v_or_b32_e32 v81, 0x57, v120
	s_nop 0
	v_cndmask_b32_e32 v80, 0, v82, vcc
	v_cmp_le_u32_e32 vcc, v81, v125
	v_bfe_u32 v82, v80, 16, 1
	v_add3_u32 v80, v80, v82, s12
	v_cndmask_b32_e32 v81, 0, v83, vcc
	v_bfe_u32 v82, v81, 16, 1
	v_lshrrev_b32_e32 v80, 16, v80
	v_add3_u32 v81, v81, v82, s12
	v_and_or_b32 v137, v81, s13, v80
	v_mov_b32_e32 v81, 0
	v_mov_b32_e32 v80, v122
	v_lshl_add_u64 v[80:81], v[100:101], 0, v[80:81]
	v_mfma_f32_32x32x16_bf16 v[48:63], v[88:91], v[134:137], v[48:63]
	v_bfe_u32 v174, v224, 5, 1
	v_lshlrev_b32_e32 v174, 3, v174
	v_mov_b32_e32 v175, 0
	v_lshl_add_u64 v[172:173], v[80:81], 0, v[174:175]
	global_load_dwordx4 v[140:143], v[172:173], off offset:3072
	global_load_dwordx4 v[144:147], v[172:173], off offset:3104
	global_load_dwordx4 v[148:151], v[172:173], off offset:3136
	global_load_dwordx4 v[152:155], v[172:173], off offset:3168
	global_load_dwordx4 v[156:159], v[172:173], off offset:3200
	global_load_dwordx4 v[160:163], v[172:173], off offset:3232
	global_load_dwordx4 v[164:167], v[172:173], off offset:3264
	global_load_dwordx4 v[168:171], v[172:173], off offset:3296
	s_nop 0
	s_and_b64 vcc, exec, s[8:9]
	v_mfma_f32_32x32x16_bf16 v[32:47], v[114:117], v[134:137], v[32:47]
	s_waitcnt lgkmcnt(1)
	v_mfma_f32_32x32x16_bf16 v[16:31], v[126:129], v[134:137], v[16:31]
	s_waitcnt lgkmcnt(0)
	v_mfma_f32_32x32x16_bf16 v[0:15], v[130:133], v[134:137], v[0:15]
	s_cbranch_vccnz .LBB0_416
	v_or_b32_e32 v114, 0x60, v120
	v_cmp_le_u32_e32 vcc, v114, v125
	s_nop 1
	v_cndmask_b32_e32 v76, 0, v76, vcc
	v_cmp_lt_u32_e32 vcc, v114, v125
	v_bfe_u32 v114, v76, 16, 1
	v_add3_u32 v76, v76, v114, s12
	v_cndmask_b32_e32 v77, 0, v77, vcc
	v_bfe_u32 v114, v77, 16, 1
	v_lshrrev_b32_e32 v76, 16, v76
	v_add3_u32 v77, v77, v114, s12
	v_and_or_b32 v76, v77, s13, v76
	v_or_b32_e32 v77, 0x62, v120
	v_cmp_le_u32_e32 vcc, v77, v125
	ds_read_b128 v[114:117], v121 offset:192
	s_nop 0
	v_cndmask_b32_e32 v77, 0, v78, vcc
	v_or_b32_e32 v78, 0x63, v120
	v_cmp_le_u32_e32 vcc, v78, v125
	s_nop 1
	v_cndmask_b32_e32 v78, 0, v79, vcc
	v_bfe_u32 v79, v77, 16, 1
	v_add3_u32 v77, v77, v79, s12
	v_bfe_u32 v79, v78, 16, 1
	v_lshrrev_b32_e32 v77, 16, v77
	v_add3_u32 v78, v78, v79, s12
	v_and_or_b32 v77, v78, s13, v77
	v_or_b32_e32 v78, 0x64, v120
	v_cmp_le_u32_e32 vcc, v78, v125
	v_or_b32_e32 v78, 0x65, v120
	s_nop 0
	v_cndmask_b32_e32 v72, 0, v72, vcc
	v_cmp_le_u32_e32 vcc, v78, v125
	v_bfe_u32 v78, v72, 16, 1
	v_add3_u32 v72, v72, v78, s12
	v_cndmask_b32_e32 v73, 0, v73, vcc
	v_bfe_u32 v78, v73, 16, 1
	v_lshrrev_b32_e32 v72, 16, v72
	v_add3_u32 v73, v73, v78, s12
	v_and_or_b32 v78, v73, s13, v72
	v_or_b32_e32 v72, 0x66, v120
	v_cmp_le_u32_e32 vcc, v72, v125
	v_or_b32_e32 v73, 0x67, v120
	s_nop 0
	v_cndmask_b32_e32 v72, 0, v74, vcc
	v_cmp_le_u32_e32 vcc, v73, v125
	v_bfe_u32 v74, v72, 16, 1
	v_add3_u32 v72, v72, v74, s12
	v_cndmask_b32_e32 v73, 0, v75, vcc
	v_bfe_u32 v74, v73, 16, 1
	v_lshrrev_b32_e32 v72, 16, v72
	v_add3_u32 v73, v73, v74, s12
	v_and_or_b32 v79, v73, s13, v72
	ds_read_b128 v[72:75], v121 offset:8896
	s_waitcnt lgkmcnt(1)
	v_mfma_f32_32x32x16_bf16 v[48:63], v[114:117], v[76:79], v[48:63]
	s_waitcnt lgkmcnt(0)
	v_mfma_f32_32x32x16_bf16 v[32:47], v[72:75], v[76:79], v[32:47]
	ds_read_b128 v[72:75], v121 offset:17600
	ds_read_b128 v[114:117], v121 offset:26304
	s_waitcnt lgkmcnt(1)
	v_mfma_f32_32x32x16_bf16 v[16:31], v[72:75], v[76:79], v[16:31]
	s_waitcnt lgkmcnt(0)
	v_mfma_f32_32x32x16_bf16 v[0:15], v[114:117], v[76:79], v[0:15]

.LBB0_418:
	s_waitcnt vmcnt(7)
	v_permlane32_swap_b32_e32 v140, v142
	v_permlane32_swap_b32_e32 v141, v143
	v_lshlrev_b32_e32 v66, 16, v140
	v_and_b32_e32 v67, 0xffff0000, v140
	v_pk_mul_f32 v[70:71], v[66:67], v[66:67]
	s_mov_b32 s8, 0x3d372713
	v_lshlrev_b32_e32 v72, 16, v141
	v_and_b32_e32 v73, 0xffff0000, v141
	v_lshlrev_b64 v[64:65], 11, v[110:111]
	v_pk_fma_f32 v[70:71], v[70:71], s[8:9], 1.0 op_sel_hi:[1,0,0]
	v_pk_mul_f32 v[74:75], v[72:73], v[72:73]
	v_lshl_add_u64 v[64:65], s[10:11], 0, v[64:65]
	v_pk_mul_f32 v[70:71], v[70:71], v[66:67]
	s_mov_b32 s10, 0xc0135761
	v_pk_fma_f32 v[74:75], v[74:75], s[8:9], 1.0 op_sel_hi:[1,0,0]
	v_pk_mul_f32 v[70:71], v[70:71], s[10:11] op_sel_hi:[1,0]
	v_pk_mul_f32 v[74:75], v[74:75], v[72:73]
	v_exp_f32_e32 v70, v70
	v_exp_f32_e32 v71, v71
	v_pk_mul_f32 v[74:75], v[74:75], s[10:11] op_sel_hi:[1,0]
	v_pk_add_f32 v[48:49], v[68:69], v[48:49] op_sel_hi:[0,1]
	v_exp_f32_e32 v74, v74
	v_exp_f32_e32 v75, v75
	v_pk_add_f32 v[70:71], v[70:71], 1.0 op_sel_hi:[1,0]
	v_lshl_add_u64 v[64:65], v[64:65], 0, s[16:17]
	v_rcp_f32_e32 v70, v70
	v_rcp_f32_e32 v71, v71
	v_pk_add_f32 v[74:75], v[74:75], 1.0 op_sel_hi:[1,0]
	v_mov_b32_e32 v123, 0
	v_rcp_f32_e32 v74, v74
	v_rcp_f32_e32 v75, v75
	v_pk_mul_f32 v[66:67], v[70:71], v[66:67]
	v_pk_add_f32 v[50:51], v[68:69], v[50:51] op_sel_hi:[0,1]
	v_pk_mul_f32 v[48:49], v[66:67], v[48:49]
	v_pk_mul_f32 v[66:67], v[74:75], v[72:73]
	v_lshl_add_u64 v[64:65], v[64:65], 0, v[122:123]
	v_bfe_u32 v138, v224, 5, 1
	v_lshlrev_b32_e32 v138, 3, v138
	v_mov_b32_e32 v139, 0
	v_lshl_add_u64 v[136:137], v[64:65], 0, v[138:139]
	v_pk_mul_f32 v[50:51], v[66:67], v[50:51]
	v_cvt_pk_bf16_f32 v128, v48, v49
	s_waitcnt vmcnt(7)
	v_lshlrev_b32_e32 v66, 16, v143
	v_cvt_pk_bf16_f32 v129, v50, v51
	v_lshlrev_b32_e32 v48, 16, v142
	v_and_b32_e32 v49, 0xffff0000, v142
	v_pk_mul_f32 v[50:51], v[48:49], v[48:49]
	v_and_b32_e32 v67, 0xffff0000, v143
	v_pk_fma_f32 v[50:51], v[50:51], s[8:9], 1.0 op_sel_hi:[1,0,0]
	v_pk_mul_f32 v[70:71], v[66:67], v[66:67]
	v_pk_mul_f32 v[50:51], v[50:51], v[48:49]
	v_pk_fma_f32 v[70:71], v[70:71], s[8:9], 1.0 op_sel_hi:[1,0,0]
	v_pk_mul_f32 v[50:51], v[50:51], s[10:11] op_sel_hi:[1,0]
	v_pk_mul_f32 v[70:71], v[70:71], v[66:67]
	v_exp_f32_e32 v50, v50
	v_exp_f32_e32 v51, v51
	v_pk_mul_f32 v[70:71], v[70:71], s[10:11] op_sel_hi:[1,0]
	v_pk_add_f32 v[32:33], v[68:69], v[32:33] op_sel_hi:[0,1]
	v_exp_f32_e32 v70, v70
	v_exp_f32_e32 v71, v71
	v_pk_add_f32 v[50:51], v[50:51], 1.0 op_sel_hi:[1,0]
	v_pk_add_f32 v[34:35], v[68:69], v[34:35] op_sel_hi:[0,1]
	v_rcp_f32_e32 v50, v50
	v_rcp_f32_e32 v51, v51
	v_pk_add_f32 v[70:71], v[70:71], 1.0 op_sel_hi:[1,0]
	v_pk_add_f32 v[16:17], v[68:69], v[16:17] op_sel_hi:[0,1]
	v_rcp_f32_e32 v70, v70
	v_rcp_f32_e32 v71, v71
	v_pk_mul_f32 v[48:49], v[50:51], v[48:49]
	v_pk_add_f32 v[50:51], v[68:69], v[52:53] op_sel_hi:[0,1]
	v_pk_mul_f32 v[48:49], v[48:49], v[50:51]
	v_pk_mul_f32 v[50:51], v[70:71], v[66:67]
	v_pk_add_f32 v[52:53], v[68:69], v[54:55] op_sel_hi:[0,1]
	v_pk_mul_f32 v[50:51], v[50:51], v[52:53]
	v_cvt_pk_bf16_f32 v130, v48, v49
	s_waitcnt vmcnt(6)
	v_permlane32_swap_b32_e32 v144, v146
	v_permlane32_swap_b32_e32 v145, v147
	v_lshlrev_b32_e32 v52, 16, v145
	v_cvt_pk_bf16_f32 v131, v50, v51
	s_nop 1
	v_permlane32_swap_b32_e32 v128, v130
	v_permlane32_swap_b32_e32 v129, v131
	global_store_dwordx4 v[136:137], v[128:131], off offset:1024
	v_lshlrev_b32_e32 v48, 16, v144
	v_and_b32_e32 v49, 0xffff0000, v144
	v_pk_mul_f32 v[50:51], v[48:49], v[48:49]
	v_and_b32_e32 v53, 0xffff0000, v145
	v_pk_fma_f32 v[50:51], v[50:51], s[8:9], 1.0 op_sel_hi:[1,0,0]
	v_pk_mul_f32 v[54:55], v[52:53], v[52:53]
	v_pk_mul_f32 v[50:51], v[50:51], v[48:49]
	v_pk_fma_f32 v[54:55], v[54:55], s[8:9], 1.0 op_sel_hi:[1,0,0]
	v_pk_mul_f32 v[50:51], v[50:51], s[10:11] op_sel_hi:[1,0]
	v_pk_mul_f32 v[54:55], v[54:55], v[52:53]
	v_exp_f32_e32 v50, v50
	v_exp_f32_e32 v51, v51
	v_pk_mul_f32 v[54:55], v[54:55], s[10:11] op_sel_hi:[1,0]
	v_pk_add_f32 v[18:19], v[68:69], v[18:19] op_sel_hi:[0,1]
	v_exp_f32_e32 v54, v54
	v_exp_f32_e32 v55, v55
	v_pk_add_f32 v[50:51], v[50:51], 1.0 op_sel_hi:[1,0]
	v_pk_add_f32 v[0:1], v[68:69], v[0:1] op_sel_hi:[0,1]
	v_rcp_f32_e32 v50, v50
	v_rcp_f32_e32 v51, v51
	v_pk_add_f32 v[54:55], v[54:55], 1.0 op_sel_hi:[1,0]
	v_pk_add_f32 v[2:3], v[68:69], v[2:3] op_sel_hi:[0,1]
	v_rcp_f32_e32 v54, v54
	v_rcp_f32_e32 v55, v55
	v_pk_mul_f32 v[48:49], v[50:51], v[48:49]
	v_pk_add_f32 v[50:51], v[68:69], v[56:57] op_sel_hi:[0,1]
	v_pk_mul_f32 v[48:49], v[48:49], v[50:51]
	v_pk_mul_f32 v[50:51], v[54:55], v[52:53]
	v_pk_add_f32 v[52:53], v[68:69], v[58:59] op_sel_hi:[0,1]
	v_pk_mul_f32 v[50:51], v[50:51], v[52:53]
	v_cvt_pk_bf16_f32 v132, v48, v49
	s_waitcnt vmcnt(7)
	v_lshlrev_b32_e32 v52, 16, v147
	v_cvt_pk_bf16_f32 v133, v50, v51
	v_lshlrev_b32_e32 v48, 16, v146
	v_and_b32_e32 v49, 0xffff0000, v146
	v_pk_mul_f32 v[50:51], v[48:49], v[48:49]
	v_and_b32_e32 v53, 0xffff0000, v147
	v_pk_fma_f32 v[50:51], v[50:51], s[8:9], 1.0 op_sel_hi:[1,0,0]
	v_pk_mul_f32 v[54:55], v[52:53], v[52:53]
	v_pk_mul_f32 v[50:51], v[50:51], v[48:49]
	v_pk_fma_f32 v[54:55], v[54:55], s[8:9], 1.0 op_sel_hi:[1,0,0]
	v_pk_mul_f32 v[50:51], v[50:51], s[10:11] op_sel_hi:[1,0]
	v_pk_mul_f32 v[54:55], v[54:55], v[52:53]
	v_exp_f32_e32 v50, v50
	v_exp_f32_e32 v51, v51
	v_pk_mul_f32 v[54:55], v[54:55], s[10:11] op_sel_hi:[1,0]
	v_pk_add_f32 v[50:51], v[50:51], 1.0 op_sel_hi:[1,0]
	v_exp_f32_e32 v54, v54
	v_exp_f32_e32 v55, v55
	v_rcp_f32_e32 v50, v50
	v_rcp_f32_e32 v51, v51
	v_pk_add_f32 v[54:55], v[54:55], 1.0 op_sel_hi:[1,0]
	s_nop 0
	v_rcp_f32_e32 v54, v54
	v_rcp_f32_e32 v55, v55
	v_pk_mul_f32 v[48:49], v[50:51], v[48:49]
	v_pk_add_f32 v[50:51], v[68:69], v[60:61] op_sel_hi:[0,1]
	v_pk_mul_f32 v[48:49], v[48:49], v[50:51]
	v_pk_mul_f32 v[50:51], v[54:55], v[52:53]
	v_pk_add_f32 v[52:53], v[68:69], v[62:63] op_sel_hi:[0,1]
	v_pk_mul_f32 v[50:51], v[50:51], v[52:53]
	v_cvt_pk_bf16_f32 v134, v48, v49
	s_waitcnt vmcnt(6)
	v_permlane32_swap_b32_e32 v148, v150
	v_permlane32_swap_b32_e32 v149, v151
	v_lshlrev_b32_e32 v52, 16, v149
	v_cvt_pk_bf16_f32 v135, v50, v51
	s_nop 1
	v_permlane32_swap_b32_e32 v132, v134
	v_permlane32_swap_b32_e32 v133, v135
	global_store_dwordx4 v[136:137], v[132:135], off offset:1056
	v_lshlrev_b32_e32 v48, 16, v148
	v_and_b32_e32 v49, 0xffff0000, v148
	v_pk_mul_f32 v[50:51], v[48:49], v[48:49]
	v_and_b32_e32 v53, 0xffff0000, v149
	v_pk_fma_f32 v[50:51], v[50:51], s[8:9], 1.0 op_sel_hi:[1,0,0]
	v_pk_mul_f32 v[54:55], v[52:53], v[52:53]
	v_pk_mul_f32 v[50:51], v[50:51], v[48:49]
	v_pk_fma_f32 v[54:55], v[54:55], s[8:9], 1.0 op_sel_hi:[1,0,0]
	v_pk_mul_f32 v[50:51], v[50:51], s[10:11] op_sel_hi:[1,0]
	v_pk_mul_f32 v[54:55], v[54:55], v[52:53]
	v_exp_f32_e32 v50, v50
	v_exp_f32_e32 v51, v51
	v_pk_mul_f32 v[54:55], v[54:55], s[10:11] op_sel_hi:[1,0]
	v_pk_add_f32 v[50:51], v[50:51], 1.0 op_sel_hi:[1,0]
	v_exp_f32_e32 v54, v54
	v_exp_f32_e32 v55, v55
	v_rcp_f32_e32 v50, v50
	v_rcp_f32_e32 v51, v51
	v_pk_add_f32 v[54:55], v[54:55], 1.0 op_sel_hi:[1,0]
	s_nop 0
	v_rcp_f32_e32 v54, v54
	v_rcp_f32_e32 v55, v55
	v_pk_mul_f32 v[48:49], v[50:51], v[48:49]
	s_nop 0
	v_pk_mul_f32 v[32:33], v[48:49], v[32:33]
	v_pk_mul_f32 v[48:49], v[54:55], v[52:53]
	v_cvt_pk_bf16_f32 v128, v32, v33
	s_nop 0
	v_pk_mul_f32 v[34:35], v[48:49], v[34:35]
	s_waitcnt vmcnt(7)
	v_lshlrev_b32_e32 v48, 16, v151
	v_cvt_pk_bf16_f32 v129, v34, v35
	v_lshlrev_b32_e32 v32, 16, v150
	v_and_b32_e32 v33, 0xffff0000, v150
	v_pk_mul_f32 v[34:35], v[32:33], v[32:33]
	v_and_b32_e32 v49, 0xffff0000, v151
	v_pk_fma_f32 v[34:35], v[34:35], s[8:9], 1.0 op_sel_hi:[1,0,0]
	v_pk_mul_f32 v[50:51], v[48:49], v[48:49]
	v_pk_mul_f32 v[34:35], v[34:35], v[32:33]
	v_pk_fma_f32 v[50:51], v[50:51], s[8:9], 1.0 op_sel_hi:[1,0,0]
	v_pk_mul_f32 v[34:35], v[34:35], s[10:11] op_sel_hi:[1,0]
	v_pk_mul_f32 v[50:51], v[50:51], v[48:49]
	v_exp_f32_e32 v34, v34
	v_exp_f32_e32 v35, v35
	v_pk_mul_f32 v[50:51], v[50:51], s[10:11] op_sel_hi:[1,0]
	v_pk_add_f32 v[34:35], v[34:35], 1.0 op_sel_hi:[1,0]
	v_exp_f32_e32 v50, v50
	v_exp_f32_e32 v51, v51
	v_rcp_f32_e32 v34, v34
	v_rcp_f32_e32 v35, v35
	v_pk_add_f32 v[50:51], v[50:51], 1.0 op_sel_hi:[1,0]
	s_nop 0
	v_rcp_f32_e32 v50, v50
	v_rcp_f32_e32 v51, v51
	v_pk_mul_f32 v[32:33], v[34:35], v[32:33]
	v_pk_add_f32 v[34:35], v[68:69], v[36:37] op_sel_hi:[0,1]
	v_pk_mul_f32 v[32:33], v[32:33], v[34:35]
	v_pk_mul_f32 v[34:35], v[50:51], v[48:49]
	v_pk_add_f32 v[36:37], v[68:69], v[38:39] op_sel_hi:[0,1]
	v_pk_mul_f32 v[34:35], v[34:35], v[36:37]
	v_cvt_pk_bf16_f32 v130, v32, v33
	s_waitcnt vmcnt(6)
	v_permlane32_swap_b32_e32 v152, v154
	v_permlane32_swap_b32_e32 v153, v155
	v_lshlrev_b32_e32 v36, 16, v153
	v_cvt_pk_bf16_f32 v131, v34, v35
	s_nop 1
	v_permlane32_swap_b32_e32 v128, v130
	v_permlane32_swap_b32_e32 v129, v131
	global_store_dwordx4 v[136:137], v[128:131], off offset:1088
	v_lshlrev_b32_e32 v32, 16, v152
	v_and_b32_e32 v33, 0xffff0000, v152
	v_pk_mul_f32 v[34:35], v[32:33], v[32:33]
	v_and_b32_e32 v37, 0xffff0000, v153
	v_pk_fma_f32 v[34:35], v[34:35], s[8:9], 1.0 op_sel_hi:[1,0,0]
	v_pk_mul_f32 v[38:39], v[36:37], v[36:37]
	v_pk_mul_f32 v[34:35], v[34:35], v[32:33]
	v_pk_fma_f32 v[38:39], v[38:39], s[8:9], 1.0 op_sel_hi:[1,0,0]
	v_pk_mul_f32 v[34:35], v[34:35], s[10:11] op_sel_hi:[1,0]
	v_pk_mul_f32 v[38:39], v[38:39], v[36:37]
	v_exp_f32_e32 v34, v34
	v_exp_f32_e32 v35, v35
	v_pk_mul_f32 v[38:39], v[38:39], s[10:11] op_sel_hi:[1,0]
	v_pk_add_f32 v[34:35], v[34:35], 1.0 op_sel_hi:[1,0]
	v_exp_f32_e32 v38, v38
	v_exp_f32_e32 v39, v39
	v_rcp_f32_e32 v34, v34
	v_rcp_f32_e32 v35, v35
	v_pk_add_f32 v[38:39], v[38:39], 1.0 op_sel_hi:[1,0]
	s_nop 0
	v_rcp_f32_e32 v38, v38
	v_rcp_f32_e32 v39, v39
	v_pk_mul_f32 v[32:33], v[34:35], v[32:33]
	v_pk_add_f32 v[34:35], v[68:69], v[40:41] op_sel_hi:[0,1]
	v_pk_mul_f32 v[32:33], v[32:33], v[34:35]
	v_pk_mul_f32 v[34:35], v[38:39], v[36:37]
	v_pk_add_f32 v[36:37], v[68:69], v[42:43] op_sel_hi:[0,1]
	v_pk_mul_f32 v[34:35], v[34:35], v[36:37]
	v_cvt_pk_bf16_f32 v132, v32, v33
	s_waitcnt vmcnt(7)
	v_lshlrev_b32_e32 v36, 16, v155
	v_cvt_pk_bf16_f32 v133, v34, v35
	v_lshlrev_b32_e32 v32, 16, v154
	v_and_b32_e32 v33, 0xffff0000, v154
	v_pk_mul_f32 v[34:35], v[32:33], v[32:33]
	v_and_b32_e32 v37, 0xffff0000, v155
	v_pk_fma_f32 v[34:35], v[34:35], s[8:9], 1.0 op_sel_hi:[1,0,0]
	v_pk_mul_f32 v[38:39], v[36:37], v[36:37]
	v_pk_mul_f32 v[34:35], v[34:35], v[32:33]
	v_pk_fma_f32 v[38:39], v[38:39], s[8:9], 1.0 op_sel_hi:[1,0,0]
	v_pk_mul_f32 v[34:35], v[34:35], s[10:11] op_sel_hi:[1,0]
	v_pk_mul_f32 v[38:39], v[38:39], v[36:37]
	v_exp_f32_e32 v34, v34
	v_exp_f32_e32 v35, v35
	v_pk_mul_f32 v[38:39], v[38:39], s[10:11] op_sel_hi:[1,0]
	v_pk_add_f32 v[34:35], v[34:35], 1.0 op_sel_hi:[1,0]
	v_exp_f32_e32 v38, v38
	v_exp_f32_e32 v39, v39
	v_rcp_f32_e32 v34, v34
	v_rcp_f32_e32 v35, v35
	v_pk_add_f32 v[38:39], v[38:39], 1.0 op_sel_hi:[1,0]
	s_nop 0
	v_rcp_f32_e32 v38, v38
	v_rcp_f32_e32 v39, v39
	v_pk_mul_f32 v[32:33], v[34:35], v[32:33]
	v_pk_add_f32 v[34:35], v[68:69], v[44:45] op_sel_hi:[0,1]
	v_pk_mul_f32 v[32:33], v[32:33], v[34:35]
	v_pk_mul_f32 v[34:35], v[38:39], v[36:37]
	v_pk_add_f32 v[36:37], v[68:69], v[46:47] op_sel_hi:[0,1]
	v_pk_mul_f32 v[34:35], v[34:35], v[36:37]
	v_cvt_pk_bf16_f32 v134, v32, v33
	s_waitcnt vmcnt(6)
	v_permlane32_swap_b32_e32 v156, v158
	v_permlane32_swap_b32_e32 v157, v159
	v_lshlrev_b32_e32 v36, 16, v157
	v_cvt_pk_bf16_f32 v135, v34, v35
	s_nop 1
	v_permlane32_swap_b32_e32 v132, v134
	v_permlane32_swap_b32_e32 v133, v135
	global_store_dwordx4 v[136:137], v[132:135], off offset:1120
	v_lshlrev_b32_e32 v32, 16, v156
	v_and_b32_e32 v33, 0xffff0000, v156
	v_pk_mul_f32 v[34:35], v[32:33], v[32:33]
	v_and_b32_e32 v37, 0xffff0000, v157
	v_pk_fma_f32 v[34:35], v[34:35], s[8:9], 1.0 op_sel_hi:[1,0,0]
	v_pk_mul_f32 v[38:39], v[36:37], v[36:37]
	v_pk_mul_f32 v[34:35], v[34:35], v[32:33]
	v_pk_fma_f32 v[38:39], v[38:39], s[8:9], 1.0 op_sel_hi:[1,0,0]
	v_pk_mul_f32 v[34:35], v[34:35], s[10:11] op_sel_hi:[1,0]
	v_pk_mul_f32 v[38:39], v[38:39], v[36:37]
	v_exp_f32_e32 v34, v34
	v_exp_f32_e32 v35, v35
	v_pk_mul_f32 v[38:39], v[38:39], s[10:11] op_sel_hi:[1,0]
	v_pk_add_f32 v[34:35], v[34:35], 1.0 op_sel_hi:[1,0]
	v_exp_f32_e32 v38, v38
	v_exp_f32_e32 v39, v39
	v_rcp_f32_e32 v34, v34
	v_rcp_f32_e32 v35, v35
	v_pk_add_f32 v[38:39], v[38:39], 1.0 op_sel_hi:[1,0]
	s_nop 0
	v_rcp_f32_e32 v38, v38
	v_rcp_f32_e32 v39, v39
	v_pk_mul_f32 v[32:33], v[34:35], v[32:33]
	s_nop 0
	v_pk_mul_f32 v[16:17], v[32:33], v[16:17]
	v_pk_mul_f32 v[32:33], v[38:39], v[36:37]
	v_cvt_pk_bf16_f32 v128, v16, v17
	s_nop 0
	v_pk_mul_f32 v[18:19], v[32:33], v[18:19]
	s_waitcnt vmcnt(7)
	v_lshlrev_b32_e32 v32, 16, v159
	v_cvt_pk_bf16_f32 v129, v18, v19
	v_lshlrev_b32_e32 v16, 16, v158
	v_and_b32_e32 v17, 0xffff0000, v158
	v_pk_mul_f32 v[18:19], v[16:17], v[16:17]
	v_and_b32_e32 v33, 0xffff0000, v159
	v_pk_fma_f32 v[18:19], v[18:19], s[8:9], 1.0 op_sel_hi:[1,0,0]
	v_pk_mul_f32 v[34:35], v[32:33], v[32:33]
	v_pk_mul_f32 v[18:19], v[18:19], v[16:17]
	v_pk_fma_f32 v[34:35], v[34:35], s[8:9], 1.0 op_sel_hi:[1,0,0]
	v_pk_mul_f32 v[18:19], v[18:19], s[10:11] op_sel_hi:[1,0]
	v_pk_mul_f32 v[34:35], v[34:35], v[32:33]
	v_exp_f32_e32 v18, v18
	v_exp_f32_e32 v19, v19
	v_pk_mul_f32 v[34:35], v[34:35], s[10:11] op_sel_hi:[1,0]
	v_pk_add_f32 v[18:19], v[18:19], 1.0 op_sel_hi:[1,0]
	v_exp_f32_e32 v34, v34
	v_exp_f32_e32 v35, v35
	v_rcp_f32_e32 v18, v18
	v_rcp_f32_e32 v19, v19
	v_pk_add_f32 v[34:35], v[34:35], 1.0 op_sel_hi:[1,0]
	s_nop 0
	v_rcp_f32_e32 v34, v34
	v_rcp_f32_e32 v35, v35
	v_pk_mul_f32 v[16:17], v[18:19], v[16:17]
	v_pk_add_f32 v[18:19], v[68:69], v[20:21] op_sel_hi:[0,1]
	v_pk_mul_f32 v[16:17], v[16:17], v[18:19]
	v_pk_mul_f32 v[18:19], v[34:35], v[32:33]
	v_pk_add_f32 v[20:21], v[68:69], v[22:23] op_sel_hi:[0,1]
	v_pk_mul_f32 v[18:19], v[18:19], v[20:21]
	v_cvt_pk_bf16_f32 v130, v16, v17
	s_waitcnt vmcnt(6)
	v_permlane32_swap_b32_e32 v160, v162
	v_permlane32_swap_b32_e32 v161, v163
	v_lshlrev_b32_e32 v20, 16, v161
	v_cvt_pk_bf16_f32 v131, v18, v19
	s_nop 1
	v_permlane32_swap_b32_e32 v128, v130
	v_permlane32_swap_b32_e32 v129, v131
	global_store_dwordx4 v[136:137], v[128:131], off offset:1152
	v_lshlrev_b32_e32 v16, 16, v160
	v_and_b32_e32 v17, 0xffff0000, v160
	v_pk_mul_f32 v[18:19], v[16:17], v[16:17]
	v_and_b32_e32 v21, 0xffff0000, v161
	v_pk_fma_f32 v[18:19], v[18:19], s[8:9], 1.0 op_sel_hi:[1,0,0]
	v_pk_mul_f32 v[22:23], v[20:21], v[20:21]
	v_pk_mul_f32 v[18:19], v[18:19], v[16:17]
	v_pk_fma_f32 v[22:23], v[22:23], s[8:9], 1.0 op_sel_hi:[1,0,0]
	v_pk_mul_f32 v[18:19], v[18:19], s[10:11] op_sel_hi:[1,0]
	v_pk_mul_f32 v[22:23], v[22:23], v[20:21]
	v_exp_f32_e32 v18, v18
	v_exp_f32_e32 v19, v19
	v_pk_mul_f32 v[22:23], v[22:23], s[10:11] op_sel_hi:[1,0]
	v_pk_add_f32 v[18:19], v[18:19], 1.0 op_sel_hi:[1,0]
	v_exp_f32_e32 v22, v22
	v_exp_f32_e32 v23, v23
	v_rcp_f32_e32 v18, v18
	v_rcp_f32_e32 v19, v19
	v_pk_add_f32 v[22:23], v[22:23], 1.0 op_sel_hi:[1,0]
	s_nop 0
	v_rcp_f32_e32 v22, v22
	v_rcp_f32_e32 v23, v23
	v_pk_mul_f32 v[16:17], v[18:19], v[16:17]
	v_pk_add_f32 v[18:19], v[68:69], v[24:25] op_sel_hi:[0,1]
	v_pk_mul_f32 v[16:17], v[16:17], v[18:19]
	v_pk_mul_f32 v[18:19], v[22:23], v[20:21]
	v_pk_add_f32 v[20:21], v[68:69], v[26:27] op_sel_hi:[0,1]
	v_pk_mul_f32 v[18:19], v[18:19], v[20:21]
	v_cvt_pk_bf16_f32 v132, v16, v17
	s_waitcnt vmcnt(7)
	v_lshlrev_b32_e32 v20, 16, v163
	v_cvt_pk_bf16_f32 v133, v18, v19
	v_lshlrev_b32_e32 v16, 16, v162
	v_and_b32_e32 v17, 0xffff0000, v162
	v_pk_mul_f32 v[18:19], v[16:17], v[16:17]
	v_and_b32_e32 v21, 0xffff0000, v163
	v_pk_fma_f32 v[18:19], v[18:19], s[8:9], 1.0 op_sel_hi:[1,0,0]
	v_pk_mul_f32 v[22:23], v[20:21], v[20:21]
	v_pk_mul_f32 v[18:19], v[18:19], v[16:17]
	v_pk_fma_f32 v[22:23], v[22:23], s[8:9], 1.0 op_sel_hi:[1,0,0]
	v_pk_mul_f32 v[18:19], v[18:19], s[10:11] op_sel_hi:[1,0]
	v_pk_mul_f32 v[22:23], v[22:23], v[20:21]
	v_exp_f32_e32 v18, v18
	v_exp_f32_e32 v19, v19
	v_pk_mul_f32 v[22:23], v[22:23], s[10:11] op_sel_hi:[1,0]
	v_pk_add_f32 v[18:19], v[18:19], 1.0 op_sel_hi:[1,0]
	v_exp_f32_e32 v22, v22
	v_exp_f32_e32 v23, v23
	v_rcp_f32_e32 v18, v18
	v_rcp_f32_e32 v19, v19
	v_pk_add_f32 v[22:23], v[22:23], 1.0 op_sel_hi:[1,0]
	s_nop 0
	v_rcp_f32_e32 v22, v22
	v_rcp_f32_e32 v23, v23
	v_pk_mul_f32 v[16:17], v[18:19], v[16:17]
	v_pk_add_f32 v[18:19], v[68:69], v[28:29] op_sel_hi:[0,1]
	v_pk_mul_f32 v[16:17], v[16:17], v[18:19]
	v_pk_mul_f32 v[18:19], v[22:23], v[20:21]
	v_pk_add_f32 v[20:21], v[68:69], v[30:31] op_sel_hi:[0,1]
	v_pk_mul_f32 v[18:19], v[18:19], v[20:21]
	v_cvt_pk_bf16_f32 v134, v16, v17
	s_waitcnt vmcnt(6)
	v_permlane32_swap_b32_e32 v164, v166
	v_permlane32_swap_b32_e32 v165, v167
	v_lshlrev_b32_e32 v20, 16, v165
	v_cvt_pk_bf16_f32 v135, v18, v19
	s_nop 1
	v_permlane32_swap_b32_e32 v132, v134
	v_permlane32_swap_b32_e32 v133, v135
	global_store_dwordx4 v[136:137], v[132:135], off offset:1184
	v_lshlrev_b32_e32 v16, 16, v164
	v_and_b32_e32 v17, 0xffff0000, v164
	v_pk_mul_f32 v[18:19], v[16:17], v[16:17]
	v_and_b32_e32 v21, 0xffff0000, v165
	v_pk_fma_f32 v[18:19], v[18:19], s[8:9], 1.0 op_sel_hi:[1,0,0]
	v_pk_mul_f32 v[22:23], v[20:21], v[20:21]
	v_pk_mul_f32 v[18:19], v[18:19], v[16:17]
	v_pk_fma_f32 v[22:23], v[22:23], s[8:9], 1.0 op_sel_hi:[1,0,0]
	v_pk_mul_f32 v[18:19], v[18:19], s[10:11] op_sel_hi:[1,0]
	v_pk_mul_f32 v[22:23], v[22:23], v[20:21]
	v_exp_f32_e32 v18, v18
	v_exp_f32_e32 v19, v19
	v_pk_mul_f32 v[22:23], v[22:23], s[10:11] op_sel_hi:[1,0]
	v_pk_add_f32 v[18:19], v[18:19], 1.0 op_sel_hi:[1,0]
	v_exp_f32_e32 v22, v22
	v_exp_f32_e32 v23, v23
	v_rcp_f32_e32 v18, v18
	v_rcp_f32_e32 v19, v19
	v_pk_add_f32 v[22:23], v[22:23], 1.0 op_sel_hi:[1,0]
	s_nop 0
	v_rcp_f32_e32 v22, v22
	v_rcp_f32_e32 v23, v23
	v_pk_mul_f32 v[16:17], v[18:19], v[16:17]
	s_nop 0
	v_pk_mul_f32 v[0:1], v[16:17], v[0:1]
	v_pk_mul_f32 v[16:17], v[22:23], v[20:21]
	v_cvt_pk_bf16_f32 v128, v0, v1
	s_nop 0
	v_pk_mul_f32 v[2:3], v[16:17], v[2:3]
	s_waitcnt vmcnt(7)
	v_lshlrev_b32_e32 v16, 16, v167
	v_cvt_pk_bf16_f32 v129, v2, v3
	v_lshlrev_b32_e32 v0, 16, v166
	v_and_b32_e32 v1, 0xffff0000, v166
	v_pk_mul_f32 v[2:3], v[0:1], v[0:1]
	v_and_b32_e32 v17, 0xffff0000, v167
	v_pk_fma_f32 v[2:3], v[2:3], s[8:9], 1.0 op_sel_hi:[1,0,0]
	v_pk_mul_f32 v[18:19], v[16:17], v[16:17]
	v_pk_mul_f32 v[2:3], v[2:3], v[0:1]
	v_pk_fma_f32 v[18:19], v[18:19], s[8:9], 1.0 op_sel_hi:[1,0,0]
	v_pk_mul_f32 v[2:3], v[2:3], s[10:11] op_sel_hi:[1,0]
	v_pk_mul_f32 v[18:19], v[18:19], v[16:17]
	v_exp_f32_e32 v2, v2
	v_exp_f32_e32 v3, v3
	v_pk_mul_f32 v[18:19], v[18:19], s[10:11] op_sel_hi:[1,0]
	v_pk_add_f32 v[2:3], v[2:3], 1.0 op_sel_hi:[1,0]
	v_exp_f32_e32 v18, v18
	v_exp_f32_e32 v19, v19
	v_rcp_f32_e32 v2, v2
	v_rcp_f32_e32 v3, v3
	v_pk_add_f32 v[18:19], v[18:19], 1.0 op_sel_hi:[1,0]
	s_nop 0
	v_rcp_f32_e32 v18, v18
	v_rcp_f32_e32 v19, v19
	v_pk_mul_f32 v[0:1], v[2:3], v[0:1]
	v_pk_add_f32 v[2:3], v[68:69], v[4:5] op_sel_hi:[0,1]
	v_pk_mul_f32 v[0:1], v[0:1], v[2:3]
	v_pk_mul_f32 v[2:3], v[18:19], v[16:17]
	v_pk_add_f32 v[4:5], v[68:69], v[6:7] op_sel_hi:[0,1]
	v_pk_mul_f32 v[2:3], v[2:3], v[4:5]
	v_cvt_pk_bf16_f32 v130, v0, v1
	s_waitcnt vmcnt(6)
	v_permlane32_swap_b32_e32 v168, v170
	v_permlane32_swap_b32_e32 v169, v171
	v_lshlrev_b32_e32 v4, 16, v169
	v_cvt_pk_bf16_f32 v131, v2, v3
	s_nop 1
	v_permlane32_swap_b32_e32 v128, v130
	v_permlane32_swap_b32_e32 v129, v131
	global_store_dwordx4 v[136:137], v[128:131], off offset:1216
	v_lshlrev_b32_e32 v0, 16, v168
	v_and_b32_e32 v1, 0xffff0000, v168
	v_pk_mul_f32 v[2:3], v[0:1], v[0:1]
	v_and_b32_e32 v5, 0xffff0000, v169
	v_pk_fma_f32 v[2:3], v[2:3], s[8:9], 1.0 op_sel_hi:[1,0,0]
	v_pk_mul_f32 v[6:7], v[4:5], v[4:5]
	v_pk_mul_f32 v[2:3], v[2:3], v[0:1]
	v_pk_fma_f32 v[6:7], v[6:7], s[8:9], 1.0 op_sel_hi:[1,0,0]
	v_pk_mul_f32 v[2:3], v[2:3], s[10:11] op_sel_hi:[1,0]
	v_pk_mul_f32 v[6:7], v[6:7], v[4:5]
	v_exp_f32_e32 v2, v2
	v_exp_f32_e32 v3, v3
	v_pk_mul_f32 v[6:7], v[6:7], s[10:11] op_sel_hi:[1,0]
	v_pk_add_f32 v[2:3], v[2:3], 1.0 op_sel_hi:[1,0]
	v_exp_f32_e32 v6, v6
	v_exp_f32_e32 v7, v7
	v_rcp_f32_e32 v2, v2
	v_rcp_f32_e32 v3, v3
	v_pk_add_f32 v[6:7], v[6:7], 1.0 op_sel_hi:[1,0]
	s_nop 0
	v_rcp_f32_e32 v6, v6
	v_rcp_f32_e32 v7, v7
	v_pk_mul_f32 v[0:1], v[2:3], v[0:1]
	v_pk_add_f32 v[2:3], v[68:69], v[8:9] op_sel_hi:[0,1]
	v_pk_mul_f32 v[0:1], v[0:1], v[2:3]
	v_pk_mul_f32 v[2:3], v[6:7], v[4:5]
	v_pk_add_f32 v[4:5], v[68:69], v[10:11] op_sel_hi:[0,1]
	v_pk_mul_f32 v[2:3], v[2:3], v[4:5]
	v_cvt_pk_bf16_f32 v132, v0, v1
	s_waitcnt vmcnt(7)
	v_lshlrev_b32_e32 v4, 16, v171
	v_cvt_pk_bf16_f32 v133, v2, v3
	v_lshlrev_b32_e32 v0, 16, v170
	v_and_b32_e32 v1, 0xffff0000, v170
	v_pk_mul_f32 v[2:3], v[0:1], v[0:1]
	v_and_b32_e32 v5, 0xffff0000, v171
	v_pk_fma_f32 v[2:3], v[2:3], s[8:9], 1.0 op_sel_hi:[1,0,0]
	v_pk_mul_f32 v[6:7], v[4:5], v[4:5]
	v_pk_mul_f32 v[2:3], v[2:3], v[0:1]
	v_pk_fma_f32 v[6:7], v[6:7], s[8:9], 1.0 op_sel_hi:[1,0,0]
	v_pk_mul_f32 v[2:3], v[2:3], s[10:11] op_sel_hi:[1,0]
	v_pk_mul_f32 v[6:7], v[6:7], v[4:5]
	v_exp_f32_e32 v2, v2
	v_exp_f32_e32 v3, v3
	v_pk_mul_f32 v[6:7], v[6:7], s[10:11] op_sel_hi:[1,0]
	v_pk_add_f32 v[2:3], v[2:3], 1.0 op_sel_hi:[1,0]
	v_exp_f32_e32 v6, v6
	v_exp_f32_e32 v7, v7
	v_rcp_f32_e32 v2, v2
	v_rcp_f32_e32 v3, v3
	v_pk_add_f32 v[6:7], v[6:7], 1.0 op_sel_hi:[1,0]
	s_nop 0
	v_rcp_f32_e32 v6, v6
	v_rcp_f32_e32 v7, v7
	v_pk_mul_f32 v[0:1], v[2:3], v[0:1]
	v_pk_add_f32 v[2:3], v[68:69], v[12:13] op_sel_hi:[0,1]
	v_pk_mul_f32 v[0:1], v[0:1], v[2:3]
	v_pk_mul_f32 v[2:3], v[6:7], v[4:5]
	v_pk_add_f32 v[4:5], v[68:69], v[14:15] op_sel_hi:[0,1]
	v_pk_mul_f32 v[2:3], v[2:3], v[4:5]
	v_cvt_pk_bf16_f32 v134, v0, v1
	s_nop 0
	v_cvt_pk_bf16_f32 v135, v2, v3
	s_nop 1
	v_permlane32_swap_b32_e32 v132, v134
	v_permlane32_swap_b32_e32 v133, v135
	global_store_dwordx4 v[136:137], v[132:135], off offset:1248
	s_barrier

.LBB0_1276:
	v_cmp_le_u32_e32 vcc, v120, v124
	s_movk_i32 s12, 0x7fff
	s_mov_b32 s13, 0xffff0000
	s_waitcnt vmcnt(2)
	v_cndmask_b32_e32 v4, 0, v4, vcc
	v_cmp_lt_u32_e32 vcc, v120, v124
	v_bfe_u32 v8, v4, 16, 1
	v_add3_u32 v4, v4, v8, s12
	v_cndmask_b32_e32 v5, 0, v5, vcc
	v_bfe_u32 v8, v5, 16, 1
	v_lshrrev_b32_e32 v4, 16, v4
	v_add3_u32 v5, v5, v8, s12
	v_and_or_b32 v4, v5, s13, v4
	v_or_b32_e32 v5, 2, v120
	v_cmp_le_u32_e32 vcc, v5, v124
	v_lshl_add_u32 v119, v120, 1, s26
	s_movk_i32 s16, 0x110
	v_cndmask_b32_e32 v5, 0, v6, vcc
	v_or_b32_e32 v6, 3, v120
	v_cmp_le_u32_e32 vcc, v6, v124
	v_mad_u32_u24 v88, v118, s16, v119
	ds_read_b128 v[12:15], v88
	ds_read_b128 v[92:95], v88 offset:32
	v_cndmask_b32_e32 v6, 0, v7, vcc
	v_bfe_u32 v7, v5, 16, 1
	v_add3_u32 v5, v5, v7, s12
	v_bfe_u32 v7, v6, 16, 1
	v_lshrrev_b32_e32 v5, 16, v5
	v_add3_u32 v6, v6, v7, s12
	v_and_or_b32 v5, v6, s13, v5
	v_or_b32_e32 v6, 4, v120
	v_cmp_le_u32_e32 vcc, v6, v124
	v_or_b32_e32 v6, 5, v120
	v_lshlrev_b32_e32 v8, 2, v10
	v_cndmask_b32_e32 v0, 0, v0, vcc
	v_cmp_le_u32_e32 vcc, v6, v124
	v_bfe_u32 v6, v0, 16, 1
	v_add3_u32 v0, v0, v6, s12
	v_cndmask_b32_e32 v1, 0, v1, vcc
	v_bfe_u32 v6, v1, 16, 1
	v_lshrrev_b32_e32 v0, 16, v0
	v_add3_u32 v1, v1, v6, s12
	v_and_or_b32 v6, v1, s13, v0
	v_or_b32_e32 v0, 6, v120
	v_cmp_le_u32_e32 vcc, v0, v124
	v_or_b32_e32 v1, 7, v120
	v_or_b32_e32 v114, s40, v124
	v_cndmask_b32_e32 v0, 0, v2, vcc
	v_cmp_le_u32_e32 vcc, v1, v124
	v_bfe_u32 v2, v0, 16, 1
	v_add3_u32 v0, v0, v2, s12
	v_cndmask_b32_e32 v1, 0, v3, vcc
	v_bfe_u32 v2, v1, 16, 1
	v_lshrrev_b32_e32 v0, 16, v0
	v_add3_u32 v1, v1, v2, s12
	v_and_or_b32 v7, v1, s13, v0
	ds_read_b128 v[0:3], v88 offset:8704
	ds_read_b128 v[96:99], v88 offset:8736
	s_waitcnt lgkmcnt(1)
	v_mfma_f32_32x32x16_bf16 v[32:47], v[0:3], v[4:7], 0
	ds_read_b128 v[0:3], v88 offset:17408
	global_load_dword v68, v8, s[18:19] offset:2048
	ds_read_b128 v[8:11], v88 offset:26112
	ds_read_b128 v[126:129], v88 offset:17440
	ds_read_b128 v[130:133], v88 offset:26144
	v_or_b32_e32 v88, 16, v120
	v_cmp_le_u32_e32 vcc, v88, v124
	s_movk_i32 s16, 0x1400
	v_mfma_f32_32x32x16_bf16 v[48:63], v[12:15], v[4:7], 0
	s_waitcnt vmcnt(1)
	v_cndmask_b32_e32 v84, 0, v84, vcc
	v_cmp_lt_u32_e32 vcc, v88, v124
	v_bfe_u32 v88, v84, 16, 1
	v_add3_u32 v84, v84, v88, s12
	v_cndmask_b32_e32 v85, 0, v85, vcc
	v_bfe_u32 v88, v85, 16, 1
	v_lshrrev_b32_e32 v84, 16, v84
	v_add3_u32 v85, v85, v88, s12
	v_and_or_b32 v134, v85, s13, v84
	v_or_b32_e32 v84, 18, v120
	v_cmp_le_u32_e32 vcc, v84, v124
	v_or_b32_e32 v85, 19, v120
	s_waitcnt lgkmcnt(3)
	v_mfma_f32_32x32x16_bf16 v[16:31], v[0:3], v[4:7], 0
	v_cndmask_b32_e32 v84, 0, v86, vcc
	v_cmp_le_u32_e32 vcc, v85, v124
	v_bfe_u32 v86, v84, 16, 1
	v_add3_u32 v84, v84, v86, s12
	v_cndmask_b32_e32 v85, 0, v87, vcc
	v_bfe_u32 v86, v85, 16, 1
	v_lshrrev_b32_e32 v84, 16, v84
	v_add3_u32 v85, v85, v86, s12
	v_and_or_b32 v135, v85, s13, v84
	v_or_b32_e32 v84, 20, v120
	v_cmp_le_u32_e32 vcc, v84, v124
	v_or_b32_e32 v84, 21, v120
	v_mov_b64_e32 v[0:1], s[20:21]
	v_cndmask_b32_e32 v80, 0, v80, vcc
	v_cmp_le_u32_e32 vcc, v84, v124
	v_bfe_u32 v84, v80, 16, 1
	v_add3_u32 v80, v80, v84, s12
	v_cndmask_b32_e32 v81, 0, v81, vcc
	v_bfe_u32 v84, v81, 16, 1
	v_lshrrev_b32_e32 v80, 16, v80
	v_add3_u32 v81, v81, v84, s12
	v_and_or_b32 v136, v81, s13, v80
	v_or_b32_e32 v80, 22, v120
	v_cmp_le_u32_e32 vcc, v80, v124
	v_or_b32_e32 v81, 23, v120
	v_mad_u64_u32 v[100:101], s[16:17], v114, s16, v[0:1]
	v_cndmask_b32_e32 v80, 0, v82, vcc
	v_cmp_le_u32_e32 vcc, v81, v124
	v_bfe_u32 v82, v80, 16, 1
	v_mov_b32_e32 v102, 0x1400
	v_cndmask_b32_e32 v81, 0, v83, vcc
	v_add3_u32 v80, v80, v82, s12
	v_bfe_u32 v82, v81, 16, 1
	v_lshrrev_b32_e32 v80, 16, v80
	v_add3_u32 v81, v81, v82, s12
	v_mad_u32_u24 v101, s41, v102, v101
	v_mov_b32_e32 v121, 0
	v_and_or_b32 v137, v81, s13, v80
	v_lshl_add_u64 v[80:81], v[100:101], 0, s[38:39]
	v_lshl_add_u64 v[80:81], v[80:81], 0, v[120:121]
	v_mfma_f32_32x32x16_bf16 v[48:63], v[92:95], v[134:137], v[48:63]
	v_bfe_u32 v174, v224, 5, 1
	v_lshlrev_b32_e32 v174, 3, v174
	v_mov_b32_e32 v175, 0
	v_lshl_add_u64 v[172:173], v[80:81], 0, v[174:175]
	global_load_dwordx4 v[140:143], v[172:173], off offset:3072
	global_load_dwordx4 v[144:147], v[172:173], off offset:3104
	v_mul_u32_u24_e32 v118, 0x110, v118
	v_lshlrev_b32_e32 v88, 2, v115
	v_mov_b32_e32 v115, s41
	s_and_b64 vcc, exec, s[10:11]
	v_add_u32_e32 v121, v119, v118
	v_mfma_f32_32x32x16_bf16 v[32:47], v[96:99], v[134:137], v[32:47]
	global_load_dwordx4 v[148:151], v[172:173], off offset:3136
	global_load_dwordx4 v[152:155], v[172:173], off offset:3168
	global_load_dwordx4 v[156:159], v[172:173], off offset:3200
	global_load_dwordx4 v[160:163], v[172:173], off offset:3232
	global_load_dwordx4 v[164:167], v[172:173], off offset:3264
	global_load_dwordx4 v[168:171], v[172:173], off offset:3296
	s_nop 0
	s_waitcnt lgkmcnt(2)
	v_mfma_f32_32x32x16_bf16 v[0:15], v[8:11], v[4:7], 0
	s_waitcnt lgkmcnt(1)
	v_mfma_f32_32x32x16_bf16 v[16:31], v[126:129], v[134:137], v[16:31]
	s_waitcnt lgkmcnt(0)
	v_mfma_f32_32x32x16_bf16 v[0:15], v[130:133], v[134:137], v[0:15]
	s_cbranch_vccnz .LBB0_1278
	v_or_b32_e32 v118, 32, v120
	v_cmp_le_u32_e32 vcc, v118, v124
	ds_read_b128 v[126:129], v121 offset:64
	s_nop 0
	v_cndmask_b32_e32 v76, 0, v76, vcc
	v_cmp_lt_u32_e32 vcc, v118, v124
	v_bfe_u32 v118, v76, 16, 1
	v_add3_u32 v76, v76, v118, s12
	v_cndmask_b32_e32 v77, 0, v77, vcc
	v_bfe_u32 v118, v77, 16, 1
	v_lshrrev_b32_e32 v76, 16, v76
	v_add3_u32 v77, v77, v118, s12
	v_and_or_b32 v76, v77, s13, v76
	v_or_b32_e32 v77, 34, v120
	v_cmp_le_u32_e32 vcc, v77, v124
	s_nop 1
	v_cndmask_b32_e32 v77, 0, v78, vcc
	v_or_b32_e32 v78, 35, v120
	v_cmp_le_u32_e32 vcc, v78, v124
	s_nop 1
	v_cndmask_b32_e32 v78, 0, v79, vcc
	v_bfe_u32 v79, v77, 16, 1
	v_add3_u32 v77, v77, v79, s12
	v_bfe_u32 v79, v78, 16, 1
	v_lshrrev_b32_e32 v77, 16, v77
	v_add3_u32 v78, v78, v79, s12
	v_and_or_b32 v77, v78, s13, v77
	v_or_b32_e32 v78, 36, v120
	v_cmp_le_u32_e32 vcc, v78, v124
	v_or_b32_e32 v78, 37, v120
	s_nop 0
	v_cndmask_b32_e32 v72, 0, v72, vcc
	v_cmp_le_u32_e32 vcc, v78, v124
	v_bfe_u32 v78, v72, 16, 1
	v_add3_u32 v72, v72, v78, s12
	v_cndmask_b32_e32 v73, 0, v73, vcc
	v_bfe_u32 v78, v73, 16, 1
	v_lshrrev_b32_e32 v72, 16, v72
	v_add3_u32 v73, v73, v78, s12
	v_and_or_b32 v78, v73, s13, v72
	v_or_b32_e32 v72, 38, v120
	v_cmp_le_u32_e32 vcc, v72, v124
	v_or_b32_e32 v73, 39, v120
	s_nop 0
	v_cndmask_b32_e32 v72, 0, v74, vcc
	v_cmp_le_u32_e32 vcc, v73, v124
	v_bfe_u32 v74, v72, 16, 1
	v_add3_u32 v72, v72, v74, s12
	v_cndmask_b32_e32 v73, 0, v75, vcc
	v_bfe_u32 v74, v73, 16, 1
	v_lshrrev_b32_e32 v72, 16, v72
	v_add3_u32 v73, v73, v74, s12
	v_and_or_b32 v79, v73, s13, v72
	ds_read_b128 v[72:75], v121 offset:8768
	s_waitcnt lgkmcnt(1)
	v_mfma_f32_32x32x16_bf16 v[48:63], v[126:129], v[76:79], v[48:63]
	s_waitcnt lgkmcnt(0)
	v_mfma_f32_32x32x16_bf16 v[32:47], v[72:75], v[76:79], v[32:47]
	ds_read_b128 v[72:75], v121 offset:17472
	ds_read_b128 v[126:129], v121 offset:26176
	s_waitcnt lgkmcnt(1)
	v_mfma_f32_32x32x16_bf16 v[16:31], v[72:75], v[76:79], v[16:31]
	s_waitcnt lgkmcnt(0)
	v_mfma_f32_32x32x16_bf16 v[0:15], v[126:129], v[76:79], v[0:15]

.LBB0_1280:
	s_waitcnt vmcnt(7)
	v_permlane32_swap_b32_e32 v140, v142
	v_permlane32_swap_b32_e32 v141, v143
	v_lshlrev_b32_e32 v66, 16, v140
	v_and_b32_e32 v67, 0xffff0000, v140
	v_pk_mul_f32 v[70:71], v[66:67], v[66:67]
	s_mov_b32 s10, 0x3d372713
	v_lshlrev_b32_e32 v72, 16, v141
	v_and_b32_e32 v73, 0xffff0000, v141
	v_pk_fma_f32 v[70:71], v[70:71], s[10:11], 1.0 op_sel_hi:[1,0,0]
	v_pk_mul_f32 v[74:75], v[72:73], v[72:73]
	v_pk_mul_f32 v[70:71], v[70:71], v[66:67]
	s_mov_b32 s16, 0xc0135761
	v_pk_fma_f32 v[74:75], v[74:75], s[10:11], 1.0 op_sel_hi:[1,0,0]
	v_pk_mul_f32 v[70:71], v[70:71], s[16:17] op_sel_hi:[1,0]
	v_pk_mul_f32 v[74:75], v[74:75], v[72:73]
	v_exp_f32_e32 v70, v70
	v_exp_f32_e32 v71, v71
	v_pk_mul_f32 v[74:75], v[74:75], s[16:17] op_sel_hi:[1,0]
	s_add_u32 s12, s36, 0xa000000
	v_exp_f32_e32 v74, v74
	v_exp_f32_e32 v75, v75
	v_pk_add_f32 v[70:71], v[70:71], 1.0 op_sel_hi:[1,0]
	s_addc_u32 s13, s37, 0
	v_rcp_f32_e32 v70, v70
	v_rcp_f32_e32 v71, v71
	v_pk_add_f32 v[74:75], v[74:75], 1.0 op_sel_hi:[1,0]
	v_lshlrev_b64 v[64:65], 11, v[114:115]
	v_rcp_f32_e32 v74, v74
	v_rcp_f32_e32 v75, v75
	v_lshl_add_u64 v[64:65], s[12:13], 0, v[64:65]
	v_pk_mul_f32 v[66:67], v[70:71], v[66:67]
	v_pk_add_f32 v[48:49], v[68:69], v[48:49] op_sel_hi:[0,1]
	v_lshl_add_u64 v[64:65], v[64:65], 0, s[38:39]
	v_lshlrev_b32_e32 v122, 1, v88
	v_mov_b32_e32 v123, 0
	v_pk_mul_f32 v[48:49], v[66:67], v[48:49]
	v_pk_mul_f32 v[66:67], v[74:75], v[72:73]
	v_pk_add_f32 v[50:51], v[68:69], v[50:51] op_sel_hi:[0,1]
	v_lshl_add_u64 v[64:65], v[64:65], 0, v[122:123]
	v_bfe_u32 v138, v224, 5, 1
	v_lshlrev_b32_e32 v138, 3, v138
	v_mov_b32_e32 v139, 0
	v_lshl_add_u64 v[136:137], v[64:65], 0, v[138:139]
	v_pk_mul_f32 v[50:51], v[66:67], v[50:51]
	v_cvt_pk_bf16_f32 v128, v48, v49
	s_waitcnt vmcnt(7)
	v_lshlrev_b32_e32 v66, 16, v143
	v_cvt_pk_bf16_f32 v129, v50, v51
	v_lshlrev_b32_e32 v48, 16, v142
	v_and_b32_e32 v49, 0xffff0000, v142
	v_pk_mul_f32 v[50:51], v[48:49], v[48:49]
	v_and_b32_e32 v67, 0xffff0000, v143
	v_pk_fma_f32 v[50:51], v[50:51], s[10:11], 1.0 op_sel_hi:[1,0,0]
	v_pk_mul_f32 v[70:71], v[66:67], v[66:67]
	v_pk_mul_f32 v[50:51], v[50:51], v[48:49]
	v_pk_fma_f32 v[70:71], v[70:71], s[10:11], 1.0 op_sel_hi:[1,0,0]
	v_pk_mul_f32 v[50:51], v[50:51], s[16:17] op_sel_hi:[1,0]
	v_pk_mul_f32 v[70:71], v[70:71], v[66:67]
	v_exp_f32_e32 v50, v50
	v_exp_f32_e32 v51, v51
	v_pk_mul_f32 v[70:71], v[70:71], s[16:17] op_sel_hi:[1,0]
	v_pk_add_f32 v[32:33], v[68:69], v[32:33] op_sel_hi:[0,1]
	v_exp_f32_e32 v70, v70
	v_exp_f32_e32 v71, v71
	v_pk_add_f32 v[50:51], v[50:51], 1.0 op_sel_hi:[1,0]
	v_pk_add_f32 v[34:35], v[68:69], v[34:35] op_sel_hi:[0,1]
	v_rcp_f32_e32 v50, v50
	v_rcp_f32_e32 v51, v51
	v_pk_add_f32 v[70:71], v[70:71], 1.0 op_sel_hi:[1,0]
	v_pk_add_f32 v[16:17], v[68:69], v[16:17] op_sel_hi:[0,1]
	v_rcp_f32_e32 v70, v70
	v_rcp_f32_e32 v71, v71
	v_pk_mul_f32 v[48:49], v[50:51], v[48:49]
	v_pk_add_f32 v[50:51], v[68:69], v[52:53] op_sel_hi:[0,1]
	v_pk_mul_f32 v[48:49], v[48:49], v[50:51]
	v_pk_mul_f32 v[50:51], v[70:71], v[66:67]
	v_pk_add_f32 v[52:53], v[68:69], v[54:55] op_sel_hi:[0,1]
	v_pk_mul_f32 v[50:51], v[50:51], v[52:53]
	v_cvt_pk_bf16_f32 v130, v48, v49
	s_waitcnt vmcnt(6)
	v_permlane32_swap_b32_e32 v144, v146
	v_permlane32_swap_b32_e32 v145, v147
	v_lshlrev_b32_e32 v52, 16, v145
	v_cvt_pk_bf16_f32 v131, v50, v51
	s_nop 1
	v_permlane32_swap_b32_e32 v128, v130
	v_permlane32_swap_b32_e32 v129, v131
	global_store_dwordx4 v[136:137], v[128:131], off offset:1024
	v_lshlrev_b32_e32 v48, 16, v144
	v_and_b32_e32 v49, 0xffff0000, v144
	v_pk_mul_f32 v[50:51], v[48:49], v[48:49]
	v_and_b32_e32 v53, 0xffff0000, v145
	v_pk_fma_f32 v[50:51], v[50:51], s[10:11], 1.0 op_sel_hi:[1,0,0]
	v_pk_mul_f32 v[54:55], v[52:53], v[52:53]
	v_pk_mul_f32 v[50:51], v[50:51], v[48:49]
	v_pk_fma_f32 v[54:55], v[54:55], s[10:11], 1.0 op_sel_hi:[1,0,0]
	v_pk_mul_f32 v[50:51], v[50:51], s[16:17] op_sel_hi:[1,0]
	v_pk_mul_f32 v[54:55], v[54:55], v[52:53]
	v_exp_f32_e32 v50, v50
	v_exp_f32_e32 v51, v51
	v_pk_mul_f32 v[54:55], v[54:55], s[16:17] op_sel_hi:[1,0]
	v_pk_add_f32 v[18:19], v[68:69], v[18:19] op_sel_hi:[0,1]
	v_exp_f32_e32 v54, v54
	v_exp_f32_e32 v55, v55
	v_pk_add_f32 v[50:51], v[50:51], 1.0 op_sel_hi:[1,0]
	v_pk_add_f32 v[0:1], v[68:69], v[0:1] op_sel_hi:[0,1]
	v_rcp_f32_e32 v50, v50
	v_rcp_f32_e32 v51, v51
	v_pk_add_f32 v[54:55], v[54:55], 1.0 op_sel_hi:[1,0]
	v_pk_add_f32 v[2:3], v[68:69], v[2:3] op_sel_hi:[0,1]
	v_rcp_f32_e32 v54, v54
	v_rcp_f32_e32 v55, v55
	v_pk_mul_f32 v[48:49], v[50:51], v[48:49]
	v_pk_add_f32 v[50:51], v[68:69], v[56:57] op_sel_hi:[0,1]
	v_pk_mul_f32 v[48:49], v[48:49], v[50:51]
	v_pk_mul_f32 v[50:51], v[54:55], v[52:53]
	v_pk_add_f32 v[52:53], v[68:69], v[58:59] op_sel_hi:[0,1]
	v_pk_mul_f32 v[50:51], v[50:51], v[52:53]
	v_cvt_pk_bf16_f32 v132, v48, v49
	s_waitcnt vmcnt(7)
	v_lshlrev_b32_e32 v52, 16, v147
	v_cvt_pk_bf16_f32 v133, v50, v51
	v_lshlrev_b32_e32 v48, 16, v146
	v_and_b32_e32 v49, 0xffff0000, v146
	v_pk_mul_f32 v[50:51], v[48:49], v[48:49]
	v_and_b32_e32 v53, 0xffff0000, v147
	v_pk_fma_f32 v[50:51], v[50:51], s[10:11], 1.0 op_sel_hi:[1,0,0]
	v_pk_mul_f32 v[54:55], v[52:53], v[52:53]
	v_pk_mul_f32 v[50:51], v[50:51], v[48:49]
	v_pk_fma_f32 v[54:55], v[54:55], s[10:11], 1.0 op_sel_hi:[1,0,0]
	v_pk_mul_f32 v[50:51], v[50:51], s[16:17] op_sel_hi:[1,0]
	v_pk_mul_f32 v[54:55], v[54:55], v[52:53]
	v_exp_f32_e32 v50, v50
	v_exp_f32_e32 v51, v51
	v_pk_mul_f32 v[54:55], v[54:55], s[16:17] op_sel_hi:[1,0]
	s_andn2_b64 vcc, exec, s[14:15]
	v_exp_f32_e32 v54, v54
	v_exp_f32_e32 v55, v55
	v_pk_add_f32 v[50:51], v[50:51], 1.0 op_sel_hi:[1,0]
	v_mov_b32_e32 v76, 0
	v_rcp_f32_e32 v50, v50
	v_rcp_f32_e32 v51, v51
	v_pk_add_f32 v[54:55], v[54:55], 1.0 op_sel_hi:[1,0]
	v_mov_b32_e32 v77, 0
	v_rcp_f32_e32 v54, v54
	v_rcp_f32_e32 v55, v55
	v_pk_mul_f32 v[48:49], v[50:51], v[48:49]
	v_pk_add_f32 v[50:51], v[68:69], v[60:61] op_sel_hi:[0,1]
	v_pk_mul_f32 v[48:49], v[48:49], v[50:51]
	v_pk_mul_f32 v[50:51], v[54:55], v[52:53]
	v_pk_add_f32 v[52:53], v[68:69], v[62:63] op_sel_hi:[0,1]
	v_pk_mul_f32 v[50:51], v[50:51], v[52:53]
	v_cvt_pk_bf16_f32 v134, v48, v49
	s_waitcnt vmcnt(6)
	v_permlane32_swap_b32_e32 v148, v150
	v_permlane32_swap_b32_e32 v149, v151
	v_lshlrev_b32_e32 v52, 16, v149
	v_cvt_pk_bf16_f32 v135, v50, v51
	s_nop 1
	v_permlane32_swap_b32_e32 v132, v134
	v_permlane32_swap_b32_e32 v133, v135
	global_store_dwordx4 v[136:137], v[132:135], off offset:1056
	v_lshlrev_b32_e32 v48, 16, v148
	v_and_b32_e32 v49, 0xffff0000, v148
	v_pk_mul_f32 v[50:51], v[48:49], v[48:49]
	v_and_b32_e32 v53, 0xffff0000, v149
	v_pk_fma_f32 v[50:51], v[50:51], s[10:11], 1.0 op_sel_hi:[1,0,0]
	v_pk_mul_f32 v[54:55], v[52:53], v[52:53]
	v_pk_mul_f32 v[50:51], v[50:51], v[48:49]
	v_pk_fma_f32 v[54:55], v[54:55], s[10:11], 1.0 op_sel_hi:[1,0,0]
	v_pk_mul_f32 v[50:51], v[50:51], s[16:17] op_sel_hi:[1,0]
	v_pk_mul_f32 v[54:55], v[54:55], v[52:53]
	v_exp_f32_e32 v50, v50
	v_exp_f32_e32 v51, v51
	v_pk_mul_f32 v[54:55], v[54:55], s[16:17] op_sel_hi:[1,0]
	v_mov_b32_e32 v78, 0
	v_exp_f32_e32 v54, v54
	v_exp_f32_e32 v55, v55
	v_pk_add_f32 v[50:51], v[50:51], 1.0 op_sel_hi:[1,0]
	v_mov_b32_e32 v79, 0
	v_rcp_f32_e32 v50, v50
	v_rcp_f32_e32 v51, v51
	v_pk_add_f32 v[54:55], v[54:55], 1.0 op_sel_hi:[1,0]
	v_mov_b32_e32 v72, 0
	v_rcp_f32_e32 v54, v54
	v_rcp_f32_e32 v55, v55
	v_pk_mul_f32 v[48:49], v[50:51], v[48:49]
	v_mov_b32_e32 v73, 0
	v_pk_mul_f32 v[32:33], v[48:49], v[32:33]
	v_pk_mul_f32 v[48:49], v[54:55], v[52:53]
	v_cvt_pk_bf16_f32 v128, v32, v33
	v_mov_b32_e32 v74, 0
	v_pk_mul_f32 v[34:35], v[48:49], v[34:35]
	s_waitcnt vmcnt(7)
	v_lshlrev_b32_e32 v48, 16, v151
	v_cvt_pk_bf16_f32 v129, v34, v35
	v_lshlrev_b32_e32 v32, 16, v150
	v_and_b32_e32 v33, 0xffff0000, v150
	v_pk_mul_f32 v[34:35], v[32:33], v[32:33]
	v_and_b32_e32 v49, 0xffff0000, v151
	v_pk_fma_f32 v[34:35], v[34:35], s[10:11], 1.0 op_sel_hi:[1,0,0]
	v_pk_mul_f32 v[50:51], v[48:49], v[48:49]
	v_pk_mul_f32 v[34:35], v[34:35], v[32:33]
	v_pk_fma_f32 v[50:51], v[50:51], s[10:11], 1.0 op_sel_hi:[1,0,0]
	v_pk_mul_f32 v[34:35], v[34:35], s[16:17] op_sel_hi:[1,0]
	v_pk_mul_f32 v[50:51], v[50:51], v[48:49]
	v_exp_f32_e32 v34, v34
	v_exp_f32_e32 v35, v35
	v_pk_mul_f32 v[50:51], v[50:51], s[16:17] op_sel_hi:[1,0]
	v_mov_b32_e32 v75, 0
	v_exp_f32_e32 v50, v50
	v_exp_f32_e32 v51, v51
	v_pk_add_f32 v[34:35], v[34:35], 1.0 op_sel_hi:[1,0]
	v_pk_add_f32 v[50:51], v[50:51], 1.0 op_sel_hi:[1,0]
	v_rcp_f32_e32 v34, v34
	v_rcp_f32_e32 v35, v35
	v_rcp_f32_e32 v50, v50
	v_rcp_f32_e32 v51, v51
	v_pk_mul_f32 v[32:33], v[34:35], v[32:33]
	v_pk_add_f32 v[34:35], v[68:69], v[36:37] op_sel_hi:[0,1]
	v_pk_mul_f32 v[32:33], v[32:33], v[34:35]
	v_pk_mul_f32 v[34:35], v[50:51], v[48:49]
	v_pk_add_f32 v[36:37], v[68:69], v[38:39] op_sel_hi:[0,1]
	v_pk_mul_f32 v[34:35], v[34:35], v[36:37]
	v_cvt_pk_bf16_f32 v130, v32, v33
	s_waitcnt vmcnt(6)
	v_permlane32_swap_b32_e32 v152, v154
	v_permlane32_swap_b32_e32 v153, v155
	v_lshlrev_b32_e32 v36, 16, v153
	v_cvt_pk_bf16_f32 v131, v34, v35
	s_nop 1
	v_permlane32_swap_b32_e32 v128, v130
	v_permlane32_swap_b32_e32 v129, v131
	global_store_dwordx4 v[136:137], v[128:131], off offset:1088
	v_lshlrev_b32_e32 v32, 16, v152
	v_and_b32_e32 v33, 0xffff0000, v152
	v_pk_mul_f32 v[34:35], v[32:33], v[32:33]
	v_and_b32_e32 v37, 0xffff0000, v153
	v_pk_fma_f32 v[34:35], v[34:35], s[10:11], 1.0 op_sel_hi:[1,0,0]
	v_pk_mul_f32 v[38:39], v[36:37], v[36:37]
	v_pk_mul_f32 v[34:35], v[34:35], v[32:33]
	v_pk_fma_f32 v[38:39], v[38:39], s[10:11], 1.0 op_sel_hi:[1,0,0]
	v_pk_mul_f32 v[34:35], v[34:35], s[16:17] op_sel_hi:[1,0]
	v_pk_mul_f32 v[38:39], v[38:39], v[36:37]
	v_exp_f32_e32 v34, v34
	v_exp_f32_e32 v35, v35
	v_pk_mul_f32 v[38:39], v[38:39], s[16:17] op_sel_hi:[1,0]
	v_pk_add_f32 v[34:35], v[34:35], 1.0 op_sel_hi:[1,0]
	v_exp_f32_e32 v38, v38
	v_exp_f32_e32 v39, v39
	v_rcp_f32_e32 v34, v34
	v_rcp_f32_e32 v35, v35
	v_pk_add_f32 v[38:39], v[38:39], 1.0 op_sel_hi:[1,0]
	s_nop 0
	v_rcp_f32_e32 v38, v38
	v_rcp_f32_e32 v39, v39
	v_pk_mul_f32 v[32:33], v[34:35], v[32:33]
	v_pk_add_f32 v[34:35], v[68:69], v[40:41] op_sel_hi:[0,1]
	v_pk_mul_f32 v[32:33], v[32:33], v[34:35]
	v_pk_mul_f32 v[34:35], v[38:39], v[36:37]
	v_pk_add_f32 v[36:37], v[68:69], v[42:43] op_sel_hi:[0,1]
	v_pk_mul_f32 v[34:35], v[34:35], v[36:37]
	v_cvt_pk_bf16_f32 v132, v32, v33
	s_waitcnt vmcnt(7)
	v_lshlrev_b32_e32 v36, 16, v155
	v_cvt_pk_bf16_f32 v133, v34, v35
	v_lshlrev_b32_e32 v32, 16, v154
	v_and_b32_e32 v33, 0xffff0000, v154
	v_pk_mul_f32 v[34:35], v[32:33], v[32:33]
	v_and_b32_e32 v37, 0xffff0000, v155
	v_pk_fma_f32 v[34:35], v[34:35], s[10:11], 1.0 op_sel_hi:[1,0,0]
	v_pk_mul_f32 v[38:39], v[36:37], v[36:37]
	v_pk_mul_f32 v[34:35], v[34:35], v[32:33]
	v_pk_fma_f32 v[38:39], v[38:39], s[10:11], 1.0 op_sel_hi:[1,0,0]
	v_pk_mul_f32 v[34:35], v[34:35], s[16:17] op_sel_hi:[1,0]
	v_pk_mul_f32 v[38:39], v[38:39], v[36:37]
	v_exp_f32_e32 v34, v34
	v_exp_f32_e32 v35, v35
	v_pk_mul_f32 v[38:39], v[38:39], s[16:17] op_sel_hi:[1,0]
	v_pk_add_f32 v[34:35], v[34:35], 1.0 op_sel_hi:[1,0]
	v_exp_f32_e32 v38, v38
	v_exp_f32_e32 v39, v39
	v_rcp_f32_e32 v34, v34
	v_rcp_f32_e32 v35, v35
	v_pk_add_f32 v[38:39], v[38:39], 1.0 op_sel_hi:[1,0]
	s_nop 0
	v_rcp_f32_e32 v38, v38
	v_rcp_f32_e32 v39, v39
	v_pk_mul_f32 v[32:33], v[34:35], v[32:33]
	v_pk_add_f32 v[34:35], v[68:69], v[44:45] op_sel_hi:[0,1]
	v_pk_mul_f32 v[32:33], v[32:33], v[34:35]
	v_pk_mul_f32 v[34:35], v[38:39], v[36:37]
	v_pk_add_f32 v[36:37], v[68:69], v[46:47] op_sel_hi:[0,1]
	v_pk_mul_f32 v[34:35], v[34:35], v[36:37]
	v_cvt_pk_bf16_f32 v134, v32, v33
	s_waitcnt vmcnt(6)
	v_permlane32_swap_b32_e32 v156, v158
	v_permlane32_swap_b32_e32 v157, v159
	v_lshlrev_b32_e32 v36, 16, v157
	v_cvt_pk_bf16_f32 v135, v34, v35
	s_nop 1
	v_permlane32_swap_b32_e32 v132, v134
	v_permlane32_swap_b32_e32 v133, v135
	global_store_dwordx4 v[136:137], v[132:135], off offset:1120
	v_lshlrev_b32_e32 v32, 16, v156
	v_and_b32_e32 v33, 0xffff0000, v156
	v_pk_mul_f32 v[34:35], v[32:33], v[32:33]
	v_and_b32_e32 v37, 0xffff0000, v157
	v_pk_fma_f32 v[34:35], v[34:35], s[10:11], 1.0 op_sel_hi:[1,0,0]
	v_pk_mul_f32 v[38:39], v[36:37], v[36:37]
	v_pk_mul_f32 v[34:35], v[34:35], v[32:33]
	v_pk_fma_f32 v[38:39], v[38:39], s[10:11], 1.0 op_sel_hi:[1,0,0]
	v_pk_mul_f32 v[34:35], v[34:35], s[16:17] op_sel_hi:[1,0]
	v_pk_mul_f32 v[38:39], v[38:39], v[36:37]
	v_exp_f32_e32 v34, v34
	v_exp_f32_e32 v35, v35
	v_pk_mul_f32 v[38:39], v[38:39], s[16:17] op_sel_hi:[1,0]
	v_pk_add_f32 v[34:35], v[34:35], 1.0 op_sel_hi:[1,0]
	v_exp_f32_e32 v38, v38
	v_exp_f32_e32 v39, v39
	v_rcp_f32_e32 v34, v34
	v_rcp_f32_e32 v35, v35
	v_pk_add_f32 v[38:39], v[38:39], 1.0 op_sel_hi:[1,0]
	s_nop 0
	v_rcp_f32_e32 v38, v38
	v_rcp_f32_e32 v39, v39
	v_pk_mul_f32 v[32:33], v[34:35], v[32:33]
	s_nop 0
	v_pk_mul_f32 v[16:17], v[32:33], v[16:17]
	v_pk_mul_f32 v[32:33], v[38:39], v[36:37]
	v_cvt_pk_bf16_f32 v128, v16, v17
	s_nop 0
	v_pk_mul_f32 v[18:19], v[32:33], v[18:19]
	s_waitcnt vmcnt(7)
	v_lshlrev_b32_e32 v32, 16, v159
	v_cvt_pk_bf16_f32 v129, v18, v19
	v_lshlrev_b32_e32 v16, 16, v158
	v_and_b32_e32 v17, 0xffff0000, v158
	v_pk_mul_f32 v[18:19], v[16:17], v[16:17]
	v_and_b32_e32 v33, 0xffff0000, v159
	v_pk_fma_f32 v[18:19], v[18:19], s[10:11], 1.0 op_sel_hi:[1,0,0]
	v_pk_mul_f32 v[34:35], v[32:33], v[32:33]
	v_pk_mul_f32 v[18:19], v[18:19], v[16:17]
	v_pk_fma_f32 v[34:35], v[34:35], s[10:11], 1.0 op_sel_hi:[1,0,0]
	v_pk_mul_f32 v[18:19], v[18:19], s[16:17] op_sel_hi:[1,0]
	v_pk_mul_f32 v[34:35], v[34:35], v[32:33]
	v_exp_f32_e32 v18, v18
	v_exp_f32_e32 v19, v19
	v_pk_mul_f32 v[34:35], v[34:35], s[16:17] op_sel_hi:[1,0]
	v_pk_add_f32 v[18:19], v[18:19], 1.0 op_sel_hi:[1,0]
	v_exp_f32_e32 v34, v34
	v_exp_f32_e32 v35, v35
	v_rcp_f32_e32 v18, v18
	v_rcp_f32_e32 v19, v19
	v_pk_add_f32 v[34:35], v[34:35], 1.0 op_sel_hi:[1,0]
	s_nop 0
	v_rcp_f32_e32 v34, v34
	v_rcp_f32_e32 v35, v35
	v_pk_mul_f32 v[16:17], v[18:19], v[16:17]
	v_pk_add_f32 v[18:19], v[68:69], v[20:21] op_sel_hi:[0,1]
	v_pk_mul_f32 v[16:17], v[16:17], v[18:19]
	v_pk_mul_f32 v[18:19], v[34:35], v[32:33]
	v_pk_add_f32 v[20:21], v[68:69], v[22:23] op_sel_hi:[0,1]
	v_pk_mul_f32 v[18:19], v[18:19], v[20:21]
	v_cvt_pk_bf16_f32 v130, v16, v17
	s_waitcnt vmcnt(6)
	v_permlane32_swap_b32_e32 v160, v162
	v_permlane32_swap_b32_e32 v161, v163
	v_lshlrev_b32_e32 v20, 16, v161
	v_cvt_pk_bf16_f32 v131, v18, v19
	s_nop 1
	v_permlane32_swap_b32_e32 v128, v130
	v_permlane32_swap_b32_e32 v129, v131
	global_store_dwordx4 v[136:137], v[128:131], off offset:1152
	v_lshlrev_b32_e32 v16, 16, v160
	v_and_b32_e32 v17, 0xffff0000, v160
	v_pk_mul_f32 v[18:19], v[16:17], v[16:17]
	v_and_b32_e32 v21, 0xffff0000, v161
	v_pk_fma_f32 v[18:19], v[18:19], s[10:11], 1.0 op_sel_hi:[1,0,0]
	v_pk_mul_f32 v[22:23], v[20:21], v[20:21]
	v_pk_mul_f32 v[18:19], v[18:19], v[16:17]
	v_pk_fma_f32 v[22:23], v[22:23], s[10:11], 1.0 op_sel_hi:[1,0,0]
	v_pk_mul_f32 v[18:19], v[18:19], s[16:17] op_sel_hi:[1,0]
	v_pk_mul_f32 v[22:23], v[22:23], v[20:21]
	v_exp_f32_e32 v18, v18
	v_exp_f32_e32 v19, v19
	v_pk_mul_f32 v[22:23], v[22:23], s[16:17] op_sel_hi:[1,0]
	v_pk_add_f32 v[18:19], v[18:19], 1.0 op_sel_hi:[1,0]
	v_exp_f32_e32 v22, v22
	v_exp_f32_e32 v23, v23
	v_rcp_f32_e32 v18, v18
	v_rcp_f32_e32 v19, v19
	v_pk_add_f32 v[22:23], v[22:23], 1.0 op_sel_hi:[1,0]
	s_nop 0
	v_rcp_f32_e32 v22, v22
	v_rcp_f32_e32 v23, v23
	v_pk_mul_f32 v[16:17], v[18:19], v[16:17]
	v_pk_add_f32 v[18:19], v[68:69], v[24:25] op_sel_hi:[0,1]
	v_pk_mul_f32 v[16:17], v[16:17], v[18:19]
	v_pk_mul_f32 v[18:19], v[22:23], v[20:21]
	v_pk_add_f32 v[20:21], v[68:69], v[26:27] op_sel_hi:[0,1]
	v_pk_mul_f32 v[18:19], v[18:19], v[20:21]
	v_cvt_pk_bf16_f32 v132, v16, v17
	s_waitcnt vmcnt(7)
	v_lshlrev_b32_e32 v20, 16, v163
	v_cvt_pk_bf16_f32 v133, v18, v19
	v_lshlrev_b32_e32 v16, 16, v162
	v_and_b32_e32 v17, 0xffff0000, v162
	v_pk_mul_f32 v[18:19], v[16:17], v[16:17]
	v_and_b32_e32 v21, 0xffff0000, v163
	v_pk_fma_f32 v[18:19], v[18:19], s[10:11], 1.0 op_sel_hi:[1,0,0]
	v_pk_mul_f32 v[22:23], v[20:21], v[20:21]
	v_pk_mul_f32 v[18:19], v[18:19], v[16:17]
	v_pk_fma_f32 v[22:23], v[22:23], s[10:11], 1.0 op_sel_hi:[1,0,0]
	v_pk_mul_f32 v[18:19], v[18:19], s[16:17] op_sel_hi:[1,0]
	v_pk_mul_f32 v[22:23], v[22:23], v[20:21]
	v_exp_f32_e32 v18, v18
	v_exp_f32_e32 v19, v19
	v_pk_mul_f32 v[22:23], v[22:23], s[16:17] op_sel_hi:[1,0]
	v_pk_add_f32 v[18:19], v[18:19], 1.0 op_sel_hi:[1,0]
	v_exp_f32_e32 v22, v22
	v_exp_f32_e32 v23, v23
	v_rcp_f32_e32 v18, v18
	v_rcp_f32_e32 v19, v19
	v_pk_add_f32 v[22:23], v[22:23], 1.0 op_sel_hi:[1,0]
	s_nop 0
	v_rcp_f32_e32 v22, v22
	v_rcp_f32_e32 v23, v23
	v_pk_mul_f32 v[16:17], v[18:19], v[16:17]
	v_pk_add_f32 v[18:19], v[68:69], v[28:29] op_sel_hi:[0,1]
	v_pk_mul_f32 v[16:17], v[16:17], v[18:19]
	v_pk_mul_f32 v[18:19], v[22:23], v[20:21]
	v_pk_add_f32 v[20:21], v[68:69], v[30:31] op_sel_hi:[0,1]
	v_pk_mul_f32 v[18:19], v[18:19], v[20:21]
	v_cvt_pk_bf16_f32 v134, v16, v17
	s_waitcnt vmcnt(6)
	v_permlane32_swap_b32_e32 v164, v166
	v_permlane32_swap_b32_e32 v165, v167
	v_lshlrev_b32_e32 v20, 16, v165
	v_cvt_pk_bf16_f32 v135, v18, v19
	s_nop 1
	v_permlane32_swap_b32_e32 v132, v134
	v_permlane32_swap_b32_e32 v133, v135
	global_store_dwordx4 v[136:137], v[132:135], off offset:1184
	v_lshlrev_b32_e32 v16, 16, v164
	v_and_b32_e32 v17, 0xffff0000, v164
	v_pk_mul_f32 v[18:19], v[16:17], v[16:17]
	v_and_b32_e32 v21, 0xffff0000, v165
	v_pk_fma_f32 v[18:19], v[18:19], s[10:11], 1.0 op_sel_hi:[1,0,0]
	v_pk_mul_f32 v[22:23], v[20:21], v[20:21]
	v_pk_mul_f32 v[18:19], v[18:19], v[16:17]
	v_pk_fma_f32 v[22:23], v[22:23], s[10:11], 1.0 op_sel_hi:[1,0,0]
	v_pk_mul_f32 v[18:19], v[18:19], s[16:17] op_sel_hi:[1,0]
	v_pk_mul_f32 v[22:23], v[22:23], v[20:21]
	v_exp_f32_e32 v18, v18
	v_exp_f32_e32 v19, v19
	v_pk_mul_f32 v[22:23], v[22:23], s[16:17] op_sel_hi:[1,0]
	v_pk_add_f32 v[18:19], v[18:19], 1.0 op_sel_hi:[1,0]
	v_exp_f32_e32 v22, v22
	v_exp_f32_e32 v23, v23
	v_rcp_f32_e32 v18, v18
	v_rcp_f32_e32 v19, v19
	v_pk_add_f32 v[22:23], v[22:23], 1.0 op_sel_hi:[1,0]
	s_nop 0
	v_rcp_f32_e32 v22, v22
	v_rcp_f32_e32 v23, v23
	v_pk_mul_f32 v[16:17], v[18:19], v[16:17]
	s_nop 0
	v_pk_mul_f32 v[0:1], v[16:17], v[0:1]
	v_pk_mul_f32 v[16:17], v[22:23], v[20:21]
	v_cvt_pk_bf16_f32 v128, v0, v1
	s_nop 0
	v_pk_mul_f32 v[2:3], v[16:17], v[2:3]
	s_waitcnt vmcnt(7)
	v_lshlrev_b32_e32 v16, 16, v167
	v_cvt_pk_bf16_f32 v129, v2, v3
	v_lshlrev_b32_e32 v0, 16, v166
	v_and_b32_e32 v1, 0xffff0000, v166
	v_pk_mul_f32 v[2:3], v[0:1], v[0:1]
	v_and_b32_e32 v17, 0xffff0000, v167
	v_pk_fma_f32 v[2:3], v[2:3], s[10:11], 1.0 op_sel_hi:[1,0,0]
	v_pk_mul_f32 v[18:19], v[16:17], v[16:17]
	v_pk_mul_f32 v[2:3], v[2:3], v[0:1]
	v_pk_fma_f32 v[18:19], v[18:19], s[10:11], 1.0 op_sel_hi:[1,0,0]
	v_pk_mul_f32 v[2:3], v[2:3], s[16:17] op_sel_hi:[1,0]
	v_pk_mul_f32 v[18:19], v[18:19], v[16:17]
	v_exp_f32_e32 v2, v2
	v_exp_f32_e32 v3, v3
	v_pk_mul_f32 v[18:19], v[18:19], s[16:17] op_sel_hi:[1,0]
	v_pk_add_f32 v[2:3], v[2:3], 1.0 op_sel_hi:[1,0]
	v_exp_f32_e32 v18, v18
	v_exp_f32_e32 v19, v19
	v_rcp_f32_e32 v2, v2
	v_rcp_f32_e32 v3, v3
	v_pk_add_f32 v[18:19], v[18:19], 1.0 op_sel_hi:[1,0]
	s_nop 0
	v_rcp_f32_e32 v18, v18
	v_rcp_f32_e32 v19, v19
	v_pk_mul_f32 v[0:1], v[2:3], v[0:1]
	v_pk_add_f32 v[2:3], v[68:69], v[4:5] op_sel_hi:[0,1]
	v_pk_mul_f32 v[0:1], v[0:1], v[2:3]
	v_pk_mul_f32 v[2:3], v[18:19], v[16:17]
	v_pk_add_f32 v[4:5], v[68:69], v[6:7] op_sel_hi:[0,1]
	v_pk_mul_f32 v[2:3], v[2:3], v[4:5]
	v_cvt_pk_bf16_f32 v130, v0, v1
	s_waitcnt vmcnt(6)
	v_permlane32_swap_b32_e32 v168, v170
	v_permlane32_swap_b32_e32 v169, v171
	v_lshlrev_b32_e32 v4, 16, v169
	v_cvt_pk_bf16_f32 v131, v2, v3
	s_nop 1
	v_permlane32_swap_b32_e32 v128, v130
	v_permlane32_swap_b32_e32 v129, v131
	global_store_dwordx4 v[136:137], v[128:131], off offset:1216
	v_lshlrev_b32_e32 v0, 16, v168
	v_and_b32_e32 v1, 0xffff0000, v168
	v_pk_mul_f32 v[2:3], v[0:1], v[0:1]
	v_and_b32_e32 v5, 0xffff0000, v169
	v_pk_fma_f32 v[2:3], v[2:3], s[10:11], 1.0 op_sel_hi:[1,0,0]
	v_pk_mul_f32 v[6:7], v[4:5], v[4:5]
	v_pk_mul_f32 v[2:3], v[2:3], v[0:1]
	v_pk_fma_f32 v[6:7], v[6:7], s[10:11], 1.0 op_sel_hi:[1,0,0]
	v_pk_mul_f32 v[2:3], v[2:3], s[16:17] op_sel_hi:[1,0]
	v_pk_mul_f32 v[6:7], v[6:7], v[4:5]
	v_exp_f32_e32 v2, v2
	v_exp_f32_e32 v3, v3
	v_pk_mul_f32 v[6:7], v[6:7], s[16:17] op_sel_hi:[1,0]
	v_pk_add_f32 v[2:3], v[2:3], 1.0 op_sel_hi:[1,0]
	v_exp_f32_e32 v6, v6
	v_exp_f32_e32 v7, v7
	v_rcp_f32_e32 v2, v2
	v_rcp_f32_e32 v3, v3
	v_pk_add_f32 v[6:7], v[6:7], 1.0 op_sel_hi:[1,0]
	s_nop 0
	v_rcp_f32_e32 v6, v6
	v_rcp_f32_e32 v7, v7
	v_pk_mul_f32 v[0:1], v[2:3], v[0:1]
	v_pk_add_f32 v[2:3], v[68:69], v[8:9] op_sel_hi:[0,1]
	v_pk_mul_f32 v[0:1], v[0:1], v[2:3]
	v_pk_mul_f32 v[2:3], v[6:7], v[4:5]
	v_pk_add_f32 v[4:5], v[68:69], v[10:11] op_sel_hi:[0,1]
	v_pk_mul_f32 v[2:3], v[2:3], v[4:5]
	v_cvt_pk_bf16_f32 v132, v0, v1
	s_waitcnt vmcnt(7)
	v_lshlrev_b32_e32 v4, 16, v171
	v_cvt_pk_bf16_f32 v133, v2, v3
	v_lshlrev_b32_e32 v0, 16, v170
	v_and_b32_e32 v1, 0xffff0000, v170
	v_pk_mul_f32 v[2:3], v[0:1], v[0:1]
	v_and_b32_e32 v5, 0xffff0000, v171
	v_pk_fma_f32 v[2:3], v[2:3], s[10:11], 1.0 op_sel_hi:[1,0,0]
	v_pk_mul_f32 v[6:7], v[4:5], v[4:5]
	v_pk_mul_f32 v[2:3], v[2:3], v[0:1]
	v_pk_fma_f32 v[6:7], v[6:7], s[10:11], 1.0 op_sel_hi:[1,0,0]
	v_pk_mul_f32 v[2:3], v[2:3], s[16:17] op_sel_hi:[1,0]
	v_pk_mul_f32 v[6:7], v[6:7], v[4:5]
	v_exp_f32_e32 v2, v2
	v_exp_f32_e32 v3, v3
	v_pk_mul_f32 v[6:7], v[6:7], s[16:17] op_sel_hi:[1,0]
	v_cndmask_b32_e64 v10, 0, 1, s[14:15]
	v_exp_f32_e32 v6, v6
	v_exp_f32_e32 v7, v7
	v_pk_add_f32 v[2:3], v[2:3], 1.0 op_sel_hi:[1,0]
	v_cmp_ne_u32_e64 s[10:11], 1, v10
	v_rcp_f32_e32 v2, v2
	v_rcp_f32_e32 v3, v3
	v_pk_add_f32 v[6:7], v[6:7], 1.0 op_sel_hi:[1,0]
	v_pk_mul_f32 v[0:1], v[2:3], v[0:1]
	v_rcp_f32_e32 v6, v6
	v_rcp_f32_e32 v7, v7
	v_pk_add_f32 v[2:3], v[68:69], v[12:13] op_sel_hi:[0,1]
	v_pk_mul_f32 v[0:1], v[0:1], v[2:3]
	v_pk_mul_f32 v[2:3], v[6:7], v[4:5]
	v_pk_add_f32 v[4:5], v[68:69], v[14:15] op_sel_hi:[0,1]
	v_cvt_pk_bf16_f32 v134, v0, v1
	v_pk_mul_f32 v[2:3], v[2:3], v[4:5]
	s_nop 0
	v_cvt_pk_bf16_f32 v135, v2, v3
	s_nop 1
	v_permlane32_swap_b32_e32 v132, v134
	v_permlane32_swap_b32_e32 v133, v135
	global_store_dwordx4 v[136:137], v[132:135], off offset:1248
	v_mov_b32_e32 v0, 0x60
	v_bitop3_b32 v0, v124, s43, v0 bitop3:0xde
	v_lshlrev_b32_e32 v0, 9, v0
	v_mov_b32_e32 v1, v123
	v_lshl_add_u64 v[8:9], v[90:91], 0, v[0:1]
	global_load_dwordx4 v[0:3], v[8:9], off offset:16
	global_load_dwordx4 v[4:7], v[8:9], off
	global_load_dwordx4 v[112:115], v[8:9], off offset:80
	global_load_dwordx4 v[116:119], v[8:9], off offset:64
	global_load_dwordx4 v[104:107], v[8:9], off offset:144
	global_load_dwordx4 v[108:111], v[8:9], off offset:128
	global_load_dwordx4 v[96:99], v[8:9], off offset:208
	global_load_dwordx4 v[100:103], v[8:9], off offset:192
	global_load_dwordx4 v[88:91], v[8:9], off offset:272
	global_load_dwordx4 v[92:95], v[8:9], off offset:256
	global_load_dwordx4 v[80:83], v[8:9], off offset:336
	global_load_dwordx4 v[84:87], v[8:9], off offset:320
	s_cbranch_vccnz .LBB0_1282
	global_load_dwordx4 v[76:79], v[8:9], off offset:384
	global_load_dwordx4 v[72:75], v[8:9], off offset:400

.LBB0_1284:
	s_movk_i32 s14, 0x7fff
	s_waitcnt vmcnt(8)
	v_bfe_u32 v68, v116, 16, 1
	v_add3_u32 v68, v116, v68, s14
	v_bfe_u32 v116, v117, 16, 1
	s_mov_b32 s15, 0xffff0000
	v_lshrrev_b32_e32 v68, 16, v68
	v_add3_u32 v116, v117, v116, s14
	v_and_or_b32 v116, v116, s15, v68
	v_bfe_u32 v68, v118, 16, 1
	v_add3_u32 v68, v118, v68, s14
	v_bfe_u32 v117, v119, 16, 1
	v_lshrrev_b32_e32 v68, 16, v68
	v_add3_u32 v117, v119, v117, s14
	v_and_or_b32 v117, v117, s15, v68
	v_bfe_u32 v68, v112, 16, 1
	v_add3_u32 v68, v112, v68, s14
	v_bfe_u32 v112, v113, 16, 1
	v_lshrrev_b32_e32 v68, 16, v68
	v_add3_u32 v112, v113, v112, s14
	v_and_or_b32 v118, v112, s15, v68
	v_bfe_u32 v68, v114, 16, 1
	v_add3_u32 v68, v114, v68, s14
	v_bfe_u32 v112, v115, 16, 1
	v_lshrrev_b32_e32 v68, 16, v68
	v_add3_u32 v112, v115, v112, s14
	v_and_or_b32 v119, v112, s15, v68
	s_waitcnt vmcnt(6)
	v_bfe_u32 v68, v108, 16, 1
	v_bfe_u32 v8, v4, 16, 1
	v_add3_u32 v68, v108, v68, s14
	v_bfe_u32 v108, v109, 16, 1
	v_add3_u32 v4, v4, v8, s14
	v_bfe_u32 v8, v5, 16, 1
	v_lshrrev_b32_e32 v68, 16, v68
	v_add3_u32 v108, v109, v108, s14
	v_lshrrev_b32_e32 v4, 16, v4
	v_add3_u32 v5, v5, v8, s14
	v_and_or_b32 v108, v108, s15, v68
	v_bfe_u32 v68, v110, 16, 1
	v_and_or_b32 v4, v5, s15, v4
	v_bfe_u32 v5, v6, 16, 1
	v_add3_u32 v68, v110, v68, s14
	v_bfe_u32 v109, v111, 16, 1
	v_add3_u32 v5, v6, v5, s14
	v_bfe_u32 v6, v7, 16, 1
	v_lshrrev_b32_e32 v68, 16, v68
	v_add3_u32 v109, v111, v109, s14
	v_lshrrev_b32_e32 v5, 16, v5
	v_add3_u32 v6, v7, v6, s14
	v_and_or_b32 v109, v109, s15, v68
	v_bfe_u32 v68, v104, 16, 1
	v_and_or_b32 v5, v6, s15, v5
	v_bfe_u32 v6, v0, 16, 1
	v_add3_u32 v68, v104, v68, s14
	v_bfe_u32 v104, v105, 16, 1
	v_add3_u32 v0, v0, v6, s14
	v_bfe_u32 v6, v1, 16, 1
	ds_read_b128 v[8:11], v121
	ds_read_b128 v[126:129], v121 offset:32
	v_lshrrev_b32_e32 v68, 16, v68
	v_add3_u32 v104, v105, v104, s14
	v_lshrrev_b32_e32 v0, 16, v0
	v_add3_u32 v1, v1, v6, s14
	v_and_or_b32 v110, v104, s15, v68
	v_bfe_u32 v68, v106, 16, 1
	v_and_or_b32 v6, v1, s15, v0
	v_bfe_u32 v0, v2, 16, 1
	v_add3_u32 v68, v106, v68, s14
	v_bfe_u32 v104, v107, 16, 1
	v_add3_u32 v0, v2, v0, s14
	v_bfe_u32 v1, v3, 16, 1
	v_lshrrev_b32_e32 v68, 16, v68
	v_add3_u32 v104, v107, v104, s14
	v_lshrrev_b32_e32 v0, 16, v0
	v_add3_u32 v1, v3, v1, s14
	v_and_or_b32 v111, v104, s15, v68
	s_waitcnt vmcnt(4)
	v_bfe_u32 v68, v100, 16, 1
	v_and_or_b32 v7, v1, s15, v0
	ds_read_b128 v[0:3], v121 offset:8704
	ds_read_b128 v[130:133], v121 offset:8736
	v_add3_u32 v68, v100, v68, s14
	v_bfe_u32 v100, v101, 16, 1
	v_lshrrev_b32_e32 v68, 16, v68
	v_add3_u32 v100, v101, v100, s14
	v_and_or_b32 v100, v100, s15, v68
	v_bfe_u32 v68, v102, 16, 1
	v_add3_u32 v68, v102, v68, s14
	v_bfe_u32 v101, v103, 16, 1
	s_waitcnt lgkmcnt(3)
	v_mfma_f32_32x32x16_bf16 v[48:63], v[8:11], v[4:7], 0
	v_lshrrev_b32_e32 v68, 16, v68
	v_add3_u32 v101, v103, v101, s14
	v_and_or_b32 v101, v101, s15, v68
	v_bfe_u32 v68, v96, 16, 1
	v_add3_u32 v68, v96, v68, s14
	v_bfe_u32 v96, v97, 16, 1
	v_lshrrev_b32_e32 v68, 16, v68
	s_waitcnt lgkmcnt(1)
	v_mfma_f32_32x32x16_bf16 v[32:47], v[0:3], v[4:7], 0
	ds_read_b128 v[0:3], v121 offset:17408
	ds_read_b128 v[134:137], v121 offset:17440
	v_add3_u32 v96, v97, v96, s14
	v_and_or_b32 v102, v96, s15, v68
	v_bfe_u32 v68, v98, 16, 1
	v_add3_u32 v68, v98, v68, s14
	v_bfe_u32 v96, v99, 16, 1
	v_lshrrev_b32_e32 v68, 16, v68
	s_waitcnt lgkmcnt(1)
	v_mfma_f32_32x32x16_bf16 v[16:31], v[0:3], v[4:7], 0
	ds_read_b128 v[0:3], v121 offset:26112
	ds_read_b128 v[138:141], v121 offset:26144
	v_add3_u32 v96, v99, v96, s14
	ds_read_b128 v[112:115], v121 offset:64
	ds_read_b128 v[104:107], v121 offset:96
	v_and_or_b32 v103, v96, s15, v68
	v_or_b32_e32 v68, 64, v120
	v_cmp_le_u32_e32 vcc, v68, v125
	s_waitcnt lgkmcnt(3)
	v_mfma_f32_32x32x16_bf16 v[0:15], v[0:3], v[4:7], 0
	s_movk_i32 s16, 0x1400
	s_waitcnt vmcnt(2)
	v_cndmask_b32_e32 v92, 0, v92, vcc
	v_cmp_lt_u32_e32 vcc, v68, v125
	s_nop 1
	v_cndmask_b32_e32 v68, 0, v93, vcc
	v_bfe_u32 v93, v92, 16, 1
	v_mfma_f32_32x32x16_bf16 v[48:63], v[126:129], v[116:119], v[48:63]
	v_add3_u32 v92, v92, v93, s14
	v_bfe_u32 v93, v68, 16, 1
	v_lshrrev_b32_e32 v92, 16, v92
	v_add3_u32 v68, v68, v93, s14
	v_and_or_b32 v92, v68, s15, v92
	v_or_b32_e32 v68, 0x42, v120
	v_cmp_le_u32_e32 vcc, v68, v125
	v_mfma_f32_32x32x16_bf16 v[32:47], v[130:133], v[116:119], v[32:47]
	v_or_b32_e32 v93, 0x43, v120
	v_cndmask_b32_e32 v68, 0, v94, vcc
	v_cmp_le_u32_e32 vcc, v93, v125
	v_bfe_u32 v94, v68, 16, 1
	v_add3_u32 v68, v68, v94, s14
	v_cndmask_b32_e32 v93, 0, v95, vcc
	v_bfe_u32 v94, v93, 16, 1
	v_mfma_f32_32x32x16_bf16 v[16:31], v[134:137], v[116:119], v[16:31]
	v_lshrrev_b32_e32 v68, 16, v68
	v_add3_u32 v93, v93, v94, s14
	v_and_or_b32 v93, v93, s15, v68
	v_or_b32_e32 v68, 0x44, v120
	v_cmp_le_u32_e32 vcc, v68, v125
	s_waitcnt lgkmcnt(2)
	v_mfma_f32_32x32x16_bf16 v[0:15], v[138:141], v[116:119], v[0:15]
	v_cndmask_b32_e32 v68, 0, v88, vcc
	v_or_b32_e32 v88, 0x45, v120
	v_cmp_le_u32_e32 vcc, v88, v125
	s_nop 1
	v_cndmask_b32_e32 v88, 0, v89, vcc
	v_bfe_u32 v89, v68, 16, 1
	s_waitcnt lgkmcnt(1)
	v_mfma_f32_32x32x16_bf16 v[48:63], v[112:115], v[108:111], v[48:63]
	ds_read_b128 v[112:115], v121 offset:8768
	ds_read_b128 v[116:119], v121 offset:8800
	v_add3_u32 v68, v68, v89, s14
	v_bfe_u32 v89, v88, 16, 1
	v_lshrrev_b32_e32 v68, 16, v68
	v_add3_u32 v88, v88, v89, s14
	v_and_or_b32 v94, v88, s15, v68
	v_or_b32_e32 v68, 0x46, v120
	s_waitcnt lgkmcnt(1)
	v_mfma_f32_32x32x16_bf16 v[32:47], v[112:115], v[108:111], v[32:47]
	ds_read_b128 v[112:115], v121 offset:17472
	ds_read_b128 v[126:129], v121 offset:17504
	v_cmp_le_u32_e32 vcc, v68, v125
	v_or_b32_e32 v88, 0x47, v120
	s_nop 0
	v_cndmask_b32_e32 v68, 0, v90, vcc
	v_cmp_le_u32_e32 vcc, v88, v125
	v_bfe_u32 v89, v68, 16, 1
	s_waitcnt lgkmcnt(1)
	v_mfma_f32_32x32x16_bf16 v[16:31], v[112:115], v[108:111], v[16:31]
	ds_read_b128 v[112:115], v121 offset:26176
	ds_read_b128 v[130:133], v121 offset:26208
	ds_read_b128 v[96:99], v121 offset:128
	v_cndmask_b32_e32 v88, 0, v91, vcc
	v_add3_u32 v68, v68, v89, s14
	v_bfe_u32 v89, v88, 16, 1
	v_lshrrev_b32_e32 v68, 16, v68
	v_add3_u32 v88, v88, v89, s14
	v_mfma_f32_32x32x16_bf16 v[48:63], v[104:107], v[100:103], v[48:63]
	v_and_or_b32 v95, v88, s15, v68
	ds_read_b128 v[88:91], v121 offset:160
	v_xor_b32_e32 v68, 32, v124
	v_add_lshl_u32 v68, v68, s43, 2
	v_mov_b64_e32 v[104:105], s[20:21]
	s_waitcnt lgkmcnt(3)
	v_mfma_f32_32x32x16_bf16 v[0:15], v[112:115], v[108:111], v[0:15]
	v_or_b32_e32 v110, s40, v125
	v_mov_b32_e32 v111, s41
	s_waitcnt lgkmcnt(1)
	v_mfma_f32_32x32x16_bf16 v[48:63], v[96:99], v[92:95], v[48:63]
	ds_read_b128 v[96:99], v121 offset:8832
	v_mfma_f32_32x32x16_bf16 v[32:47], v[116:119], v[100:103], v[32:47]
	v_mfma_f32_32x32x16_bf16 v[16:31], v[126:129], v[100:103], v[16:31]
	v_mfma_f32_32x32x16_bf16 v[0:15], v[130:133], v[100:103], v[0:15]
	ds_read_b128 v[100:103], v121 offset:17536
	ds_read_b128 v[114:117], v121 offset:8864
	global_load_dword v68, v68, s[18:19] offset:2304
	s_waitcnt lgkmcnt(2)
	v_mfma_f32_32x32x16_bf16 v[32:47], v[96:99], v[92:95], v[32:47]
	ds_read_b128 v[96:99], v121 offset:26240
	ds_read_b128 v[126:129], v121 offset:17568
	ds_read_b128 v[130:133], v121 offset:26272
	s_waitcnt lgkmcnt(4)
	v_mfma_f32_32x32x16_bf16 v[16:31], v[100:103], v[92:95], v[16:31]
	v_mad_u64_u32 v[100:101], s[16:17], v110, s16, v[104:105]
	v_mov_b32_e32 v102, 0x1400
	v_mad_u32_u24 v101, s41, v102, v101
	v_lshl_add_u64 v[100:101], v[100:101], 0, s[38:39]
	s_waitcnt lgkmcnt(2)
	v_mfma_f32_32x32x16_bf16 v[0:15], v[96:99], v[92:95], v[0:15]
	v_or_b32_e32 v92, 0x50, v120
	v_cmp_le_u32_e32 vcc, v92, v125
	s_waitcnt vmcnt(1)
	s_nop 0
	v_cndmask_b32_e32 v84, 0, v84, vcc
	v_cmp_lt_u32_e32 vcc, v92, v125
	v_bfe_u32 v92, v84, 16, 1
	v_add3_u32 v84, v84, v92, s14
	v_cndmask_b32_e32 v85, 0, v85, vcc
	v_bfe_u32 v92, v85, 16, 1
	v_lshrrev_b32_e32 v84, 16, v84
	v_add3_u32 v85, v85, v92, s14
	v_and_or_b32 v134, v85, s15, v84
	v_or_b32_e32 v84, 0x52, v120
	v_cmp_le_u32_e32 vcc, v84, v125
	v_or_b32_e32 v85, 0x53, v120
	s_nop 0
	v_cndmask_b32_e32 v84, 0, v86, vcc
	v_cmp_le_u32_e32 vcc, v85, v125
	v_bfe_u32 v86, v84, 16, 1
	v_add3_u32 v84, v84, v86, s14
	v_cndmask_b32_e32 v85, 0, v87, vcc
	v_bfe_u32 v86, v85, 16, 1
	v_lshrrev_b32_e32 v84, 16, v84
	v_add3_u32 v85, v85, v86, s14
	v_and_or_b32 v135, v85, s15, v84
	v_or_b32_e32 v84, 0x54, v120
	v_cmp_le_u32_e32 vcc, v84, v125
	v_or_b32_e32 v84, 0x55, v120
	s_nop 0
	v_cndmask_b32_e32 v80, 0, v80, vcc
	v_cmp_le_u32_e32 vcc, v84, v125
	v_bfe_u32 v84, v80, 16, 1
	v_add3_u32 v80, v80, v84, s14
	v_cndmask_b32_e32 v81, 0, v81, vcc
	v_bfe_u32 v84, v81, 16, 1
	v_lshrrev_b32_e32 v80, 16, v80
	v_add3_u32 v81, v81, v84, s14
	v_and_or_b32 v136, v81, s15, v80
	v_or_b32_e32 v80, 0x56, v120
	v_cmp_le_u32_e32 vcc, v80, v125
	v_or_b32_e32 v81, 0x57, v120
	s_nop 0
	v_cndmask_b32_e32 v80, 0, v82, vcc
	v_cmp_le_u32_e32 vcc, v81, v125
	v_bfe_u32 v82, v80, 16, 1
	v_add3_u32 v80, v80, v82, s14
	v_cndmask_b32_e32 v81, 0, v83, vcc
	v_bfe_u32 v82, v81, 16, 1
	v_lshrrev_b32_e32 v80, 16, v80
	v_add3_u32 v81, v81, v82, s14
	v_and_or_b32 v137, v81, s15, v80
	v_mov_b32_e32 v81, 0
	v_mov_b32_e32 v80, v122
	v_lshl_add_u64 v[80:81], v[100:101], 0, v[80:81]
	v_mfma_f32_32x32x16_bf16 v[48:63], v[88:91], v[134:137], v[48:63]
	v_bfe_u32 v174, v224, 5, 1
	v_lshlrev_b32_e32 v174, 3, v174
	v_mov_b32_e32 v175, 0
	v_lshl_add_u64 v[172:173], v[80:81], 0, v[174:175]
	global_load_dwordx4 v[140:143], v[172:173], off offset:3072
	global_load_dwordx4 v[144:147], v[172:173], off offset:3104
	global_load_dwordx4 v[148:151], v[172:173], off offset:3136
	global_load_dwordx4 v[152:155], v[172:173], off offset:3168
	global_load_dwordx4 v[156:159], v[172:173], off offset:3200
	global_load_dwordx4 v[160:163], v[172:173], off offset:3232
	global_load_dwordx4 v[164:167], v[172:173], off offset:3264
	global_load_dwordx4 v[168:171], v[172:173], off offset:3296
	s_nop 0
	s_and_b64 vcc, exec, s[10:11]
	v_mfma_f32_32x32x16_bf16 v[32:47], v[114:117], v[134:137], v[32:47]
	s_waitcnt lgkmcnt(1)
	v_mfma_f32_32x32x16_bf16 v[16:31], v[126:129], v[134:137], v[16:31]
	s_waitcnt lgkmcnt(0)
	v_mfma_f32_32x32x16_bf16 v[0:15], v[130:133], v[134:137], v[0:15]
	s_cbranch_vccnz .LBB0_1286
	v_or_b32_e32 v114, 0x60, v120
	v_cmp_le_u32_e32 vcc, v114, v125
	s_nop 1
	v_cndmask_b32_e32 v76, 0, v76, vcc
	v_cmp_lt_u32_e32 vcc, v114, v125
	v_bfe_u32 v114, v76, 16, 1
	v_add3_u32 v76, v76, v114, s14
	v_cndmask_b32_e32 v77, 0, v77, vcc
	v_bfe_u32 v114, v77, 16, 1
	v_lshrrev_b32_e32 v76, 16, v76
	v_add3_u32 v77, v77, v114, s14
	v_and_or_b32 v76, v77, s15, v76
	v_or_b32_e32 v77, 0x62, v120
	v_cmp_le_u32_e32 vcc, v77, v125
	ds_read_b128 v[114:117], v121 offset:192
	s_nop 0
	v_cndmask_b32_e32 v77, 0, v78, vcc
	v_or_b32_e32 v78, 0x63, v120
	v_cmp_le_u32_e32 vcc, v78, v125
	s_nop 1
	v_cndmask_b32_e32 v78, 0, v79, vcc
	v_bfe_u32 v79, v77, 16, 1
	v_add3_u32 v77, v77, v79, s14
	v_bfe_u32 v79, v78, 16, 1
	v_lshrrev_b32_e32 v77, 16, v77
	v_add3_u32 v78, v78, v79, s14
	v_and_or_b32 v77, v78, s15, v77
	v_or_b32_e32 v78, 0x64, v120
	v_cmp_le_u32_e32 vcc, v78, v125
	v_or_b32_e32 v78, 0x65, v120
	s_nop 0
	v_cndmask_b32_e32 v72, 0, v72, vcc
	v_cmp_le_u32_e32 vcc, v78, v125
	v_bfe_u32 v78, v72, 16, 1
	v_add3_u32 v72, v72, v78, s14
	v_cndmask_b32_e32 v73, 0, v73, vcc
	v_bfe_u32 v78, v73, 16, 1
	v_lshrrev_b32_e32 v72, 16, v72
	v_add3_u32 v73, v73, v78, s14
	v_and_or_b32 v78, v73, s15, v72
	v_or_b32_e32 v72, 0x66, v120
	v_cmp_le_u32_e32 vcc, v72, v125
	v_or_b32_e32 v73, 0x67, v120
	s_nop 0
	v_cndmask_b32_e32 v72, 0, v74, vcc
	v_cmp_le_u32_e32 vcc, v73, v125
	v_bfe_u32 v74, v72, 16, 1
	v_add3_u32 v72, v72, v74, s14
	v_cndmask_b32_e32 v73, 0, v75, vcc
	v_bfe_u32 v74, v73, 16, 1
	v_lshrrev_b32_e32 v72, 16, v72
	v_add3_u32 v73, v73, v74, s14
	v_and_or_b32 v79, v73, s15, v72
	ds_read_b128 v[72:75], v121 offset:8896
	s_waitcnt lgkmcnt(1)
	v_mfma_f32_32x32x16_bf16 v[48:63], v[114:117], v[76:79], v[48:63]
	s_waitcnt lgkmcnt(0)
	v_mfma_f32_32x32x16_bf16 v[32:47], v[72:75], v[76:79], v[32:47]
	ds_read_b128 v[72:75], v121 offset:17600
	ds_read_b128 v[114:117], v121 offset:26304
	s_waitcnt lgkmcnt(1)
	v_mfma_f32_32x32x16_bf16 v[16:31], v[72:75], v[76:79], v[16:31]
	s_waitcnt lgkmcnt(0)
	v_mfma_f32_32x32x16_bf16 v[0:15], v[114:117], v[76:79], v[0:15]

.LBB0_1288:
	s_waitcnt vmcnt(7)
	v_permlane32_swap_b32_e32 v140, v142
	v_permlane32_swap_b32_e32 v141, v143
	v_lshlrev_b32_e32 v66, 16, v140
	v_and_b32_e32 v67, 0xffff0000, v140
	v_pk_mul_f32 v[70:71], v[66:67], v[66:67]
	s_mov_b32 s10, 0x3d372713
	v_lshlrev_b32_e32 v72, 16, v141
	v_and_b32_e32 v73, 0xffff0000, v141
	v_lshlrev_b64 v[64:65], 11, v[110:111]
	v_pk_fma_f32 v[70:71], v[70:71], s[10:11], 1.0 op_sel_hi:[1,0,0]
	v_pk_mul_f32 v[74:75], v[72:73], v[72:73]
	v_lshl_add_u64 v[64:65], s[12:13], 0, v[64:65]
	v_pk_mul_f32 v[70:71], v[70:71], v[66:67]
	s_mov_b32 s12, 0xc0135761
	v_pk_fma_f32 v[74:75], v[74:75], s[10:11], 1.0 op_sel_hi:[1,0,0]
	v_pk_mul_f32 v[70:71], v[70:71], s[12:13] op_sel_hi:[1,0]
	v_pk_mul_f32 v[74:75], v[74:75], v[72:73]
	v_exp_f32_e32 v70, v70
	v_exp_f32_e32 v71, v71
	v_pk_mul_f32 v[74:75], v[74:75], s[12:13] op_sel_hi:[1,0]
	v_pk_add_f32 v[48:49], v[68:69], v[48:49] op_sel_hi:[0,1]
	v_exp_f32_e32 v74, v74
	v_exp_f32_e32 v75, v75
	v_pk_add_f32 v[70:71], v[70:71], 1.0 op_sel_hi:[1,0]
	v_lshl_add_u64 v[64:65], v[64:65], 0, s[38:39]
	v_rcp_f32_e32 v70, v70
	v_rcp_f32_e32 v71, v71
	v_pk_add_f32 v[74:75], v[74:75], 1.0 op_sel_hi:[1,0]
	v_mov_b32_e32 v123, 0
	v_rcp_f32_e32 v74, v74
	v_rcp_f32_e32 v75, v75
	v_pk_mul_f32 v[66:67], v[70:71], v[66:67]
	v_pk_add_f32 v[50:51], v[68:69], v[50:51] op_sel_hi:[0,1]
	v_pk_mul_f32 v[48:49], v[66:67], v[48:49]
	v_pk_mul_f32 v[66:67], v[74:75], v[72:73]
	v_lshl_add_u64 v[64:65], v[64:65], 0, v[122:123]
	v_bfe_u32 v138, v224, 5, 1
	v_lshlrev_b32_e32 v138, 3, v138
	v_mov_b32_e32 v139, 0
	v_lshl_add_u64 v[136:137], v[64:65], 0, v[138:139]
	v_pk_mul_f32 v[50:51], v[66:67], v[50:51]
	v_cvt_pk_bf16_f32 v128, v48, v49
	s_waitcnt vmcnt(7)
	v_lshlrev_b32_e32 v66, 16, v143
	v_cvt_pk_bf16_f32 v129, v50, v51
	v_lshlrev_b32_e32 v48, 16, v142
	v_and_b32_e32 v49, 0xffff0000, v142
	v_pk_mul_f32 v[50:51], v[48:49], v[48:49]
	v_and_b32_e32 v67, 0xffff0000, v143
	v_pk_fma_f32 v[50:51], v[50:51], s[10:11], 1.0 op_sel_hi:[1,0,0]
	v_pk_mul_f32 v[70:71], v[66:67], v[66:67]
	v_pk_mul_f32 v[50:51], v[50:51], v[48:49]
	v_pk_fma_f32 v[70:71], v[70:71], s[10:11], 1.0 op_sel_hi:[1,0,0]
	v_pk_mul_f32 v[50:51], v[50:51], s[12:13] op_sel_hi:[1,0]
	v_pk_mul_f32 v[70:71], v[70:71], v[66:67]
	v_exp_f32_e32 v50, v50
	v_exp_f32_e32 v51, v51
	v_pk_mul_f32 v[70:71], v[70:71], s[12:13] op_sel_hi:[1,0]
	v_pk_add_f32 v[32:33], v[68:69], v[32:33] op_sel_hi:[0,1]
	v_exp_f32_e32 v70, v70
	v_exp_f32_e32 v71, v71
	v_pk_add_f32 v[50:51], v[50:51], 1.0 op_sel_hi:[1,0]
	v_pk_add_f32 v[34:35], v[68:69], v[34:35] op_sel_hi:[0,1]
	v_rcp_f32_e32 v50, v50
	v_rcp_f32_e32 v51, v51
	v_pk_add_f32 v[70:71], v[70:71], 1.0 op_sel_hi:[1,0]
	v_pk_add_f32 v[16:17], v[68:69], v[16:17] op_sel_hi:[0,1]
	v_rcp_f32_e32 v70, v70
	v_rcp_f32_e32 v71, v71
	v_pk_mul_f32 v[48:49], v[50:51], v[48:49]
	v_pk_add_f32 v[50:51], v[68:69], v[52:53] op_sel_hi:[0,1]
	v_pk_mul_f32 v[48:49], v[48:49], v[50:51]
	v_pk_mul_f32 v[50:51], v[70:71], v[66:67]
	v_pk_add_f32 v[52:53], v[68:69], v[54:55] op_sel_hi:[0,1]
	v_pk_mul_f32 v[50:51], v[50:51], v[52:53]
	v_cvt_pk_bf16_f32 v130, v48, v49
	s_waitcnt vmcnt(6)
	v_permlane32_swap_b32_e32 v144, v146
	v_permlane32_swap_b32_e32 v145, v147
	v_lshlrev_b32_e32 v52, 16, v145
	v_cvt_pk_bf16_f32 v131, v50, v51
	s_nop 1
	v_permlane32_swap_b32_e32 v128, v130
	v_permlane32_swap_b32_e32 v129, v131
	global_store_dwordx4 v[136:137], v[128:131], off offset:1024
	v_lshlrev_b32_e32 v48, 16, v144
	v_and_b32_e32 v49, 0xffff0000, v144
	v_pk_mul_f32 v[50:51], v[48:49], v[48:49]
	v_and_b32_e32 v53, 0xffff0000, v145
	v_pk_fma_f32 v[50:51], v[50:51], s[10:11], 1.0 op_sel_hi:[1,0,0]
	v_pk_mul_f32 v[54:55], v[52:53], v[52:53]
	v_pk_mul_f32 v[50:51], v[50:51], v[48:49]
	v_pk_fma_f32 v[54:55], v[54:55], s[10:11], 1.0 op_sel_hi:[1,0,0]
	v_pk_mul_f32 v[50:51], v[50:51], s[12:13] op_sel_hi:[1,0]
	v_pk_mul_f32 v[54:55], v[54:55], v[52:53]
	v_exp_f32_e32 v50, v50
	v_exp_f32_e32 v51, v51
	v_pk_mul_f32 v[54:55], v[54:55], s[12:13] op_sel_hi:[1,0]
	v_pk_add_f32 v[18:19], v[68:69], v[18:19] op_sel_hi:[0,1]
	v_exp_f32_e32 v54, v54
	v_exp_f32_e32 v55, v55
	v_pk_add_f32 v[50:51], v[50:51], 1.0 op_sel_hi:[1,0]
	v_pk_add_f32 v[0:1], v[68:69], v[0:1] op_sel_hi:[0,1]
	v_rcp_f32_e32 v50, v50
	v_rcp_f32_e32 v51, v51
	v_pk_add_f32 v[54:55], v[54:55], 1.0 op_sel_hi:[1,0]
	v_pk_add_f32 v[2:3], v[68:69], v[2:3] op_sel_hi:[0,1]
	v_rcp_f32_e32 v54, v54
	v_rcp_f32_e32 v55, v55
	v_pk_mul_f32 v[48:49], v[50:51], v[48:49]
	v_pk_add_f32 v[50:51], v[68:69], v[56:57] op_sel_hi:[0,1]
	v_pk_mul_f32 v[48:49], v[48:49], v[50:51]
	v_pk_mul_f32 v[50:51], v[54:55], v[52:53]
	v_pk_add_f32 v[52:53], v[68:69], v[58:59] op_sel_hi:[0,1]
	v_pk_mul_f32 v[50:51], v[50:51], v[52:53]
	v_cvt_pk_bf16_f32 v132, v48, v49
	s_waitcnt vmcnt(7)
	v_lshlrev_b32_e32 v52, 16, v147
	v_cvt_pk_bf16_f32 v133, v50, v51
	v_lshlrev_b32_e32 v48, 16, v146
	v_and_b32_e32 v49, 0xffff0000, v146
	v_pk_mul_f32 v[50:51], v[48:49], v[48:49]
	v_and_b32_e32 v53, 0xffff0000, v147
	v_pk_fma_f32 v[50:51], v[50:51], s[10:11], 1.0 op_sel_hi:[1,0,0]
	v_pk_mul_f32 v[54:55], v[52:53], v[52:53]
	v_pk_mul_f32 v[50:51], v[50:51], v[48:49]
	v_pk_fma_f32 v[54:55], v[54:55], s[10:11], 1.0 op_sel_hi:[1,0,0]
	v_pk_mul_f32 v[50:51], v[50:51], s[12:13] op_sel_hi:[1,0]
	v_pk_mul_f32 v[54:55], v[54:55], v[52:53]
	v_exp_f32_e32 v50, v50
	v_exp_f32_e32 v51, v51
	v_pk_mul_f32 v[54:55], v[54:55], s[12:13] op_sel_hi:[1,0]
	v_pk_add_f32 v[50:51], v[50:51], 1.0 op_sel_hi:[1,0]
	v_exp_f32_e32 v54, v54
	v_exp_f32_e32 v55, v55
	v_rcp_f32_e32 v50, v50
	v_rcp_f32_e32 v51, v51
	v_pk_add_f32 v[54:55], v[54:55], 1.0 op_sel_hi:[1,0]
	s_nop 0
	v_rcp_f32_e32 v54, v54
	v_rcp_f32_e32 v55, v55
	v_pk_mul_f32 v[48:49], v[50:51], v[48:49]
	v_pk_add_f32 v[50:51], v[68:69], v[60:61] op_sel_hi:[0,1]
	v_pk_mul_f32 v[48:49], v[48:49], v[50:51]
	v_pk_mul_f32 v[50:51], v[54:55], v[52:53]
	v_pk_add_f32 v[52:53], v[68:69], v[62:63] op_sel_hi:[0,1]
	v_pk_mul_f32 v[50:51], v[50:51], v[52:53]
	v_cvt_pk_bf16_f32 v134, v48, v49
	s_waitcnt vmcnt(6)
	v_permlane32_swap_b32_e32 v148, v150
	v_permlane32_swap_b32_e32 v149, v151
	v_lshlrev_b32_e32 v52, 16, v149
	v_cvt_pk_bf16_f32 v135, v50, v51
	s_nop 1
	v_permlane32_swap_b32_e32 v132, v134
	v_permlane32_swap_b32_e32 v133, v135
	global_store_dwordx4 v[136:137], v[132:135], off offset:1056
	v_lshlrev_b32_e32 v48, 16, v148
	v_and_b32_e32 v49, 0xffff0000, v148
	v_pk_mul_f32 v[50:51], v[48:49], v[48:49]
	v_and_b32_e32 v53, 0xffff0000, v149
	v_pk_fma_f32 v[50:51], v[50:51], s[10:11], 1.0 op_sel_hi:[1,0,0]
	v_pk_mul_f32 v[54:55], v[52:53], v[52:53]
	v_pk_mul_f32 v[50:51], v[50:51], v[48:49]
	v_pk_fma_f32 v[54:55], v[54:55], s[10:11], 1.0 op_sel_hi:[1,0,0]
	v_pk_mul_f32 v[50:51], v[50:51], s[12:13] op_sel_hi:[1,0]
	v_pk_mul_f32 v[54:55], v[54:55], v[52:53]
	v_exp_f32_e32 v50, v50
	v_exp_f32_e32 v51, v51
	v_pk_mul_f32 v[54:55], v[54:55], s[12:13] op_sel_hi:[1,0]
	v_pk_add_f32 v[50:51], v[50:51], 1.0 op_sel_hi:[1,0]
	v_exp_f32_e32 v54, v54
	v_exp_f32_e32 v55, v55
	v_rcp_f32_e32 v50, v50
	v_rcp_f32_e32 v51, v51
	v_pk_add_f32 v[54:55], v[54:55], 1.0 op_sel_hi:[1,0]
	s_nop 0
	v_rcp_f32_e32 v54, v54
	v_rcp_f32_e32 v55, v55
	v_pk_mul_f32 v[48:49], v[50:51], v[48:49]
	s_nop 0
	v_pk_mul_f32 v[32:33], v[48:49], v[32:33]
	v_pk_mul_f32 v[48:49], v[54:55], v[52:53]
	v_cvt_pk_bf16_f32 v128, v32, v33
	s_nop 0
	v_pk_mul_f32 v[34:35], v[48:49], v[34:35]
	s_waitcnt vmcnt(7)
	v_lshlrev_b32_e32 v48, 16, v151
	v_cvt_pk_bf16_f32 v129, v34, v35
	v_lshlrev_b32_e32 v32, 16, v150
	v_and_b32_e32 v33, 0xffff0000, v150
	v_pk_mul_f32 v[34:35], v[32:33], v[32:33]
	v_and_b32_e32 v49, 0xffff0000, v151
	v_pk_fma_f32 v[34:35], v[34:35], s[10:11], 1.0 op_sel_hi:[1,0,0]
	v_pk_mul_f32 v[50:51], v[48:49], v[48:49]
	v_pk_mul_f32 v[34:35], v[34:35], v[32:33]
	v_pk_fma_f32 v[50:51], v[50:51], s[10:11], 1.0 op_sel_hi:[1,0,0]
	v_pk_mul_f32 v[34:35], v[34:35], s[12:13] op_sel_hi:[1,0]
	v_pk_mul_f32 v[50:51], v[50:51], v[48:49]
	v_exp_f32_e32 v34, v34
	v_exp_f32_e32 v35, v35
	v_pk_mul_f32 v[50:51], v[50:51], s[12:13] op_sel_hi:[1,0]
	v_pk_add_f32 v[34:35], v[34:35], 1.0 op_sel_hi:[1,0]
	v_exp_f32_e32 v50, v50
	v_exp_f32_e32 v51, v51
	v_rcp_f32_e32 v34, v34
	v_rcp_f32_e32 v35, v35
	v_pk_add_f32 v[50:51], v[50:51], 1.0 op_sel_hi:[1,0]
	s_nop 0
	v_rcp_f32_e32 v50, v50
	v_rcp_f32_e32 v51, v51
	v_pk_mul_f32 v[32:33], v[34:35], v[32:33]
	v_pk_add_f32 v[34:35], v[68:69], v[36:37] op_sel_hi:[0,1]
	v_pk_mul_f32 v[32:33], v[32:33], v[34:35]
	v_pk_mul_f32 v[34:35], v[50:51], v[48:49]
	v_pk_add_f32 v[36:37], v[68:69], v[38:39] op_sel_hi:[0,1]
	v_pk_mul_f32 v[34:35], v[34:35], v[36:37]
	v_cvt_pk_bf16_f32 v130, v32, v33
	s_waitcnt vmcnt(6)
	v_permlane32_swap_b32_e32 v152, v154
	v_permlane32_swap_b32_e32 v153, v155
	v_lshlrev_b32_e32 v36, 16, v153
	v_cvt_pk_bf16_f32 v131, v34, v35
	s_nop 1
	v_permlane32_swap_b32_e32 v128, v130
	v_permlane32_swap_b32_e32 v129, v131
	global_store_dwordx4 v[136:137], v[128:131], off offset:1088
	v_lshlrev_b32_e32 v32, 16, v152
	v_and_b32_e32 v33, 0xffff0000, v152
	v_pk_mul_f32 v[34:35], v[32:33], v[32:33]
	v_and_b32_e32 v37, 0xffff0000, v153
	v_pk_fma_f32 v[34:35], v[34:35], s[10:11], 1.0 op_sel_hi:[1,0,0]
	v_pk_mul_f32 v[38:39], v[36:37], v[36:37]
	v_pk_mul_f32 v[34:35], v[34:35], v[32:33]
	v_pk_fma_f32 v[38:39], v[38:39], s[10:11], 1.0 op_sel_hi:[1,0,0]
	v_pk_mul_f32 v[34:35], v[34:35], s[12:13] op_sel_hi:[1,0]
	v_pk_mul_f32 v[38:39], v[38:39], v[36:37]
	v_exp_f32_e32 v34, v34
	v_exp_f32_e32 v35, v35
	v_pk_mul_f32 v[38:39], v[38:39], s[12:13] op_sel_hi:[1,0]
	v_pk_add_f32 v[34:35], v[34:35], 1.0 op_sel_hi:[1,0]
	v_exp_f32_e32 v38, v38
	v_exp_f32_e32 v39, v39
	v_rcp_f32_e32 v34, v34
	v_rcp_f32_e32 v35, v35
	v_pk_add_f32 v[38:39], v[38:39], 1.0 op_sel_hi:[1,0]
	s_nop 0
	v_rcp_f32_e32 v38, v38
	v_rcp_f32_e32 v39, v39
	v_pk_mul_f32 v[32:33], v[34:35], v[32:33]
	v_pk_add_f32 v[34:35], v[68:69], v[40:41] op_sel_hi:[0,1]
	v_pk_mul_f32 v[32:33], v[32:33], v[34:35]
	v_pk_mul_f32 v[34:35], v[38:39], v[36:37]
	v_pk_add_f32 v[36:37], v[68:69], v[42:43] op_sel_hi:[0,1]
	v_pk_mul_f32 v[34:35], v[34:35], v[36:37]
	v_cvt_pk_bf16_f32 v132, v32, v33
	s_waitcnt vmcnt(7)
	v_lshlrev_b32_e32 v36, 16, v155
	v_cvt_pk_bf16_f32 v133, v34, v35
	v_lshlrev_b32_e32 v32, 16, v154
	v_and_b32_e32 v33, 0xffff0000, v154
	v_pk_mul_f32 v[34:35], v[32:33], v[32:33]
	v_and_b32_e32 v37, 0xffff0000, v155
	v_pk_fma_f32 v[34:35], v[34:35], s[10:11], 1.0 op_sel_hi:[1,0,0]
	v_pk_mul_f32 v[38:39], v[36:37], v[36:37]
	v_pk_mul_f32 v[34:35], v[34:35], v[32:33]
	v_pk_fma_f32 v[38:39], v[38:39], s[10:11], 1.0 op_sel_hi:[1,0,0]
	v_pk_mul_f32 v[34:35], v[34:35], s[12:13] op_sel_hi:[1,0]
	v_pk_mul_f32 v[38:39], v[38:39], v[36:37]
	v_exp_f32_e32 v34, v34
	v_exp_f32_e32 v35, v35
	v_pk_mul_f32 v[38:39], v[38:39], s[12:13] op_sel_hi:[1,0]
	v_pk_add_f32 v[34:35], v[34:35], 1.0 op_sel_hi:[1,0]
	v_exp_f32_e32 v38, v38
	v_exp_f32_e32 v39, v39
	v_rcp_f32_e32 v34, v34
	v_rcp_f32_e32 v35, v35
	v_pk_add_f32 v[38:39], v[38:39], 1.0 op_sel_hi:[1,0]
	s_nop 0
	v_rcp_f32_e32 v38, v38
	v_rcp_f32_e32 v39, v39
	v_pk_mul_f32 v[32:33], v[34:35], v[32:33]
	v_pk_add_f32 v[34:35], v[68:69], v[44:45] op_sel_hi:[0,1]
	v_pk_mul_f32 v[32:33], v[32:33], v[34:35]
	v_pk_mul_f32 v[34:35], v[38:39], v[36:37]
	v_pk_add_f32 v[36:37], v[68:69], v[46:47] op_sel_hi:[0,1]
	v_pk_mul_f32 v[34:35], v[34:35], v[36:37]
	v_cvt_pk_bf16_f32 v134, v32, v33
	s_waitcnt vmcnt(6)
	v_permlane32_swap_b32_e32 v156, v158
	v_permlane32_swap_b32_e32 v157, v159
	v_lshlrev_b32_e32 v36, 16, v157
	v_cvt_pk_bf16_f32 v135, v34, v35
	s_nop 1
	v_permlane32_swap_b32_e32 v132, v134
	v_permlane32_swap_b32_e32 v133, v135
	global_store_dwordx4 v[136:137], v[132:135], off offset:1120
	v_lshlrev_b32_e32 v32, 16, v156
	v_and_b32_e32 v33, 0xffff0000, v156
	v_pk_mul_f32 v[34:35], v[32:33], v[32:33]
	v_and_b32_e32 v37, 0xffff0000, v157
	v_pk_fma_f32 v[34:35], v[34:35], s[10:11], 1.0 op_sel_hi:[1,0,0]
	v_pk_mul_f32 v[38:39], v[36:37], v[36:37]
	v_pk_mul_f32 v[34:35], v[34:35], v[32:33]
	v_pk_fma_f32 v[38:39], v[38:39], s[10:11], 1.0 op_sel_hi:[1,0,0]
	v_pk_mul_f32 v[34:35], v[34:35], s[12:13] op_sel_hi:[1,0]
	v_pk_mul_f32 v[38:39], v[38:39], v[36:37]
	v_exp_f32_e32 v34, v34
	v_exp_f32_e32 v35, v35
	v_pk_mul_f32 v[38:39], v[38:39], s[12:13] op_sel_hi:[1,0]
	v_pk_add_f32 v[34:35], v[34:35], 1.0 op_sel_hi:[1,0]
	v_exp_f32_e32 v38, v38
	v_exp_f32_e32 v39, v39
	v_rcp_f32_e32 v34, v34
	v_rcp_f32_e32 v35, v35
	v_pk_add_f32 v[38:39], v[38:39], 1.0 op_sel_hi:[1,0]
	s_nop 0
	v_rcp_f32_e32 v38, v38
	v_rcp_f32_e32 v39, v39
	v_pk_mul_f32 v[32:33], v[34:35], v[32:33]
	s_nop 0
	v_pk_mul_f32 v[16:17], v[32:33], v[16:17]
	v_pk_mul_f32 v[32:33], v[38:39], v[36:37]
	v_cvt_pk_bf16_f32 v128, v16, v17
	s_nop 0
	v_pk_mul_f32 v[18:19], v[32:33], v[18:19]
	s_waitcnt vmcnt(7)
	v_lshlrev_b32_e32 v32, 16, v159
	v_cvt_pk_bf16_f32 v129, v18, v19
	v_lshlrev_b32_e32 v16, 16, v158
	v_and_b32_e32 v17, 0xffff0000, v158
	v_pk_mul_f32 v[18:19], v[16:17], v[16:17]
	v_and_b32_e32 v33, 0xffff0000, v159
	v_pk_fma_f32 v[18:19], v[18:19], s[10:11], 1.0 op_sel_hi:[1,0,0]
	v_pk_mul_f32 v[34:35], v[32:33], v[32:33]
	v_pk_mul_f32 v[18:19], v[18:19], v[16:17]
	v_pk_fma_f32 v[34:35], v[34:35], s[10:11], 1.0 op_sel_hi:[1,0,0]
	v_pk_mul_f32 v[18:19], v[18:19], s[12:13] op_sel_hi:[1,0]
	v_pk_mul_f32 v[34:35], v[34:35], v[32:33]
	v_exp_f32_e32 v18, v18
	v_exp_f32_e32 v19, v19
	v_pk_mul_f32 v[34:35], v[34:35], s[12:13] op_sel_hi:[1,0]
	v_pk_add_f32 v[18:19], v[18:19], 1.0 op_sel_hi:[1,0]
	v_exp_f32_e32 v34, v34
	v_exp_f32_e32 v35, v35
	v_rcp_f32_e32 v18, v18
	v_rcp_f32_e32 v19, v19
	v_pk_add_f32 v[34:35], v[34:35], 1.0 op_sel_hi:[1,0]
	s_nop 0
	v_rcp_f32_e32 v34, v34
	v_rcp_f32_e32 v35, v35
	v_pk_mul_f32 v[16:17], v[18:19], v[16:17]
	v_pk_add_f32 v[18:19], v[68:69], v[20:21] op_sel_hi:[0,1]
	v_pk_mul_f32 v[16:17], v[16:17], v[18:19]
	v_pk_mul_f32 v[18:19], v[34:35], v[32:33]
	v_pk_add_f32 v[20:21], v[68:69], v[22:23] op_sel_hi:[0,1]
	v_pk_mul_f32 v[18:19], v[18:19], v[20:21]
	v_cvt_pk_bf16_f32 v130, v16, v17
	s_waitcnt vmcnt(6)
	v_permlane32_swap_b32_e32 v160, v162
	v_permlane32_swap_b32_e32 v161, v163
	v_lshlrev_b32_e32 v20, 16, v161
	v_cvt_pk_bf16_f32 v131, v18, v19
	s_nop 1
	v_permlane32_swap_b32_e32 v128, v130
	v_permlane32_swap_b32_e32 v129, v131
	global_store_dwordx4 v[136:137], v[128:131], off offset:1152
	v_lshlrev_b32_e32 v16, 16, v160
	v_and_b32_e32 v17, 0xffff0000, v160
	v_pk_mul_f32 v[18:19], v[16:17], v[16:17]
	v_and_b32_e32 v21, 0xffff0000, v161
	v_pk_fma_f32 v[18:19], v[18:19], s[10:11], 1.0 op_sel_hi:[1,0,0]
	v_pk_mul_f32 v[22:23], v[20:21], v[20:21]
	v_pk_mul_f32 v[18:19], v[18:19], v[16:17]
	v_pk_fma_f32 v[22:23], v[22:23], s[10:11], 1.0 op_sel_hi:[1,0,0]
	v_pk_mul_f32 v[18:19], v[18:19], s[12:13] op_sel_hi:[1,0]
	v_pk_mul_f32 v[22:23], v[22:23], v[20:21]
	v_exp_f32_e32 v18, v18
	v_exp_f32_e32 v19, v19
	v_pk_mul_f32 v[22:23], v[22:23], s[12:13] op_sel_hi:[1,0]
	v_pk_add_f32 v[18:19], v[18:19], 1.0 op_sel_hi:[1,0]
	v_exp_f32_e32 v22, v22
	v_exp_f32_e32 v23, v23
	v_rcp_f32_e32 v18, v18
	v_rcp_f32_e32 v19, v19
	v_pk_add_f32 v[22:23], v[22:23], 1.0 op_sel_hi:[1,0]
	s_nop 0
	v_rcp_f32_e32 v22, v22
	v_rcp_f32_e32 v23, v23
	v_pk_mul_f32 v[16:17], v[18:19], v[16:17]
	v_pk_add_f32 v[18:19], v[68:69], v[24:25] op_sel_hi:[0,1]
	v_pk_mul_f32 v[16:17], v[16:17], v[18:19]
	v_pk_mul_f32 v[18:19], v[22:23], v[20:21]
	v_pk_add_f32 v[20:21], v[68:69], v[26:27] op_sel_hi:[0,1]
	v_pk_mul_f32 v[18:19], v[18:19], v[20:21]
	v_cvt_pk_bf16_f32 v132, v16, v17
	s_waitcnt vmcnt(7)
	v_lshlrev_b32_e32 v20, 16, v163
	v_cvt_pk_bf16_f32 v133, v18, v19
	v_lshlrev_b32_e32 v16, 16, v162
	v_and_b32_e32 v17, 0xffff0000, v162
	v_pk_mul_f32 v[18:19], v[16:17], v[16:17]
	v_and_b32_e32 v21, 0xffff0000, v163
	v_pk_fma_f32 v[18:19], v[18:19], s[10:11], 1.0 op_sel_hi:[1,0,0]
	v_pk_mul_f32 v[22:23], v[20:21], v[20:21]
	v_pk_mul_f32 v[18:19], v[18:19], v[16:17]
	v_pk_fma_f32 v[22:23], v[22:23], s[10:11], 1.0 op_sel_hi:[1,0,0]
	v_pk_mul_f32 v[18:19], v[18:19], s[12:13] op_sel_hi:[1,0]
	v_pk_mul_f32 v[22:23], v[22:23], v[20:21]
	v_exp_f32_e32 v18, v18
	v_exp_f32_e32 v19, v19
	v_pk_mul_f32 v[22:23], v[22:23], s[12:13] op_sel_hi:[1,0]
	v_pk_add_f32 v[18:19], v[18:19], 1.0 op_sel_hi:[1,0]
	v_exp_f32_e32 v22, v22
	v_exp_f32_e32 v23, v23
	v_rcp_f32_e32 v18, v18
	v_rcp_f32_e32 v19, v19
	v_pk_add_f32 v[22:23], v[22:23], 1.0 op_sel_hi:[1,0]
	s_nop 0
	v_rcp_f32_e32 v22, v22
	v_rcp_f32_e32 v23, v23
	v_pk_mul_f32 v[16:17], v[18:19], v[16:17]
	v_pk_add_f32 v[18:19], v[68:69], v[28:29] op_sel_hi:[0,1]
	v_pk_mul_f32 v[16:17], v[16:17], v[18:19]
	v_pk_mul_f32 v[18:19], v[22:23], v[20:21]
	v_pk_add_f32 v[20:21], v[68:69], v[30:31] op_sel_hi:[0,1]
	v_pk_mul_f32 v[18:19], v[18:19], v[20:21]
	v_cvt_pk_bf16_f32 v134, v16, v17
	s_waitcnt vmcnt(6)
	v_permlane32_swap_b32_e32 v164, v166
	v_permlane32_swap_b32_e32 v165, v167
	v_lshlrev_b32_e32 v20, 16, v165
	v_cvt_pk_bf16_f32 v135, v18, v19
	s_nop 1
	v_permlane32_swap_b32_e32 v132, v134
	v_permlane32_swap_b32_e32 v133, v135
	global_store_dwordx4 v[136:137], v[132:135], off offset:1184
	v_lshlrev_b32_e32 v16, 16, v164
	v_and_b32_e32 v17, 0xffff0000, v164
	v_pk_mul_f32 v[18:19], v[16:17], v[16:17]
	v_and_b32_e32 v21, 0xffff0000, v165
	v_pk_fma_f32 v[18:19], v[18:19], s[10:11], 1.0 op_sel_hi:[1,0,0]
	v_pk_mul_f32 v[22:23], v[20:21], v[20:21]
	v_pk_mul_f32 v[18:19], v[18:19], v[16:17]
	v_pk_fma_f32 v[22:23], v[22:23], s[10:11], 1.0 op_sel_hi:[1,0,0]
	v_pk_mul_f32 v[18:19], v[18:19], s[12:13] op_sel_hi:[1,0]
	v_pk_mul_f32 v[22:23], v[22:23], v[20:21]
	v_exp_f32_e32 v18, v18
	v_exp_f32_e32 v19, v19
	v_pk_mul_f32 v[22:23], v[22:23], s[12:13] op_sel_hi:[1,0]
	v_pk_add_f32 v[18:19], v[18:19], 1.0 op_sel_hi:[1,0]
	v_exp_f32_e32 v22, v22
	v_exp_f32_e32 v23, v23
	v_rcp_f32_e32 v18, v18
	v_rcp_f32_e32 v19, v19
	v_pk_add_f32 v[22:23], v[22:23], 1.0 op_sel_hi:[1,0]
	s_nop 0
	v_rcp_f32_e32 v22, v22
	v_rcp_f32_e32 v23, v23
	v_pk_mul_f32 v[16:17], v[18:19], v[16:17]
	s_nop 0
	v_pk_mul_f32 v[0:1], v[16:17], v[0:1]
	v_pk_mul_f32 v[16:17], v[22:23], v[20:21]
	v_cvt_pk_bf16_f32 v128, v0, v1
	s_nop 0
	v_pk_mul_f32 v[2:3], v[16:17], v[2:3]
	s_waitcnt vmcnt(7)
	v_lshlrev_b32_e32 v16, 16, v167
	v_cvt_pk_bf16_f32 v129, v2, v3
	v_lshlrev_b32_e32 v0, 16, v166
	v_and_b32_e32 v1, 0xffff0000, v166
	v_pk_mul_f32 v[2:3], v[0:1], v[0:1]
	v_and_b32_e32 v17, 0xffff0000, v167
	v_pk_fma_f32 v[2:3], v[2:3], s[10:11], 1.0 op_sel_hi:[1,0,0]
	v_pk_mul_f32 v[18:19], v[16:17], v[16:17]
	v_pk_mul_f32 v[2:3], v[2:3], v[0:1]
	v_pk_fma_f32 v[18:19], v[18:19], s[10:11], 1.0 op_sel_hi:[1,0,0]
	v_pk_mul_f32 v[2:3], v[2:3], s[12:13] op_sel_hi:[1,0]
	v_pk_mul_f32 v[18:19], v[18:19], v[16:17]
	v_exp_f32_e32 v2, v2
	v_exp_f32_e32 v3, v3
	v_pk_mul_f32 v[18:19], v[18:19], s[12:13] op_sel_hi:[1,0]
	v_pk_add_f32 v[2:3], v[2:3], 1.0 op_sel_hi:[1,0]
	v_exp_f32_e32 v18, v18
	v_exp_f32_e32 v19, v19
	v_rcp_f32_e32 v2, v2
	v_rcp_f32_e32 v3, v3
	v_pk_add_f32 v[18:19], v[18:19], 1.0 op_sel_hi:[1,0]
	s_nop 0
	v_rcp_f32_e32 v18, v18
	v_rcp_f32_e32 v19, v19
	v_pk_mul_f32 v[0:1], v[2:3], v[0:1]
	v_pk_add_f32 v[2:3], v[68:69], v[4:5] op_sel_hi:[0,1]
	v_pk_mul_f32 v[0:1], v[0:1], v[2:3]
	v_pk_mul_f32 v[2:3], v[18:19], v[16:17]
	v_pk_add_f32 v[4:5], v[68:69], v[6:7] op_sel_hi:[0,1]
	v_pk_mul_f32 v[2:3], v[2:3], v[4:5]
	v_cvt_pk_bf16_f32 v130, v0, v1
	s_waitcnt vmcnt(6)
	v_permlane32_swap_b32_e32 v168, v170
	v_permlane32_swap_b32_e32 v169, v171
	v_lshlrev_b32_e32 v4, 16, v169
	v_cvt_pk_bf16_f32 v131, v2, v3
	s_nop 1
	v_permlane32_swap_b32_e32 v128, v130
	v_permlane32_swap_b32_e32 v129, v131
	global_store_dwordx4 v[136:137], v[128:131], off offset:1216
	v_lshlrev_b32_e32 v0, 16, v168
	v_and_b32_e32 v1, 0xffff0000, v168
	v_pk_mul_f32 v[2:3], v[0:1], v[0:1]
	v_and_b32_e32 v5, 0xffff0000, v169
	v_pk_fma_f32 v[2:3], v[2:3], s[10:11], 1.0 op_sel_hi:[1,0,0]
	v_pk_mul_f32 v[6:7], v[4:5], v[4:5]
	v_pk_mul_f32 v[2:3], v[2:3], v[0:1]
	v_pk_fma_f32 v[6:7], v[6:7], s[10:11], 1.0 op_sel_hi:[1,0,0]
	v_pk_mul_f32 v[2:3], v[2:3], s[12:13] op_sel_hi:[1,0]
	v_pk_mul_f32 v[6:7], v[6:7], v[4:5]
	v_exp_f32_e32 v2, v2
	v_exp_f32_e32 v3, v3
	v_pk_mul_f32 v[6:7], v[6:7], s[12:13] op_sel_hi:[1,0]
	v_pk_add_f32 v[2:3], v[2:3], 1.0 op_sel_hi:[1,0]
	v_exp_f32_e32 v6, v6
	v_exp_f32_e32 v7, v7
	v_rcp_f32_e32 v2, v2
	v_rcp_f32_e32 v3, v3
	v_pk_add_f32 v[6:7], v[6:7], 1.0 op_sel_hi:[1,0]
	s_nop 0
	v_rcp_f32_e32 v6, v6
	v_rcp_f32_e32 v7, v7
	v_pk_mul_f32 v[0:1], v[2:3], v[0:1]
	v_pk_add_f32 v[2:3], v[68:69], v[8:9] op_sel_hi:[0,1]
	v_pk_mul_f32 v[0:1], v[0:1], v[2:3]
	v_pk_mul_f32 v[2:3], v[6:7], v[4:5]
	v_pk_add_f32 v[4:5], v[68:69], v[10:11] op_sel_hi:[0,1]
	v_pk_mul_f32 v[2:3], v[2:3], v[4:5]
	v_cvt_pk_bf16_f32 v132, v0, v1
	s_waitcnt vmcnt(7)
	v_lshlrev_b32_e32 v4, 16, v171
	v_cvt_pk_bf16_f32 v133, v2, v3
	v_lshlrev_b32_e32 v0, 16, v170
	v_and_b32_e32 v1, 0xffff0000, v170
	v_pk_mul_f32 v[2:3], v[0:1], v[0:1]
	v_and_b32_e32 v5, 0xffff0000, v171
	v_pk_fma_f32 v[2:3], v[2:3], s[10:11], 1.0 op_sel_hi:[1,0,0]
	v_pk_mul_f32 v[6:7], v[4:5], v[4:5]
	v_pk_mul_f32 v[2:3], v[2:3], v[0:1]
	v_pk_fma_f32 v[6:7], v[6:7], s[10:11], 1.0 op_sel_hi:[1,0,0]
	v_pk_mul_f32 v[2:3], v[2:3], s[12:13] op_sel_hi:[1,0]
	v_pk_mul_f32 v[6:7], v[6:7], v[4:5]
	v_exp_f32_e32 v2, v2
	v_exp_f32_e32 v3, v3
	v_pk_mul_f32 v[6:7], v[6:7], s[12:13] op_sel_hi:[1,0]
	v_pk_add_f32 v[2:3], v[2:3], 1.0 op_sel_hi:[1,0]
	v_exp_f32_e32 v6, v6
	v_exp_f32_e32 v7, v7
	v_rcp_f32_e32 v2, v2
	v_rcp_f32_e32 v3, v3
	v_pk_add_f32 v[6:7], v[6:7], 1.0 op_sel_hi:[1,0]
	s_nop 0
	v_rcp_f32_e32 v6, v6
	v_rcp_f32_e32 v7, v7
	v_pk_mul_f32 v[0:1], v[2:3], v[0:1]
	v_pk_add_f32 v[2:3], v[68:69], v[12:13] op_sel_hi:[0,1]
	v_pk_mul_f32 v[0:1], v[0:1], v[2:3]
	v_pk_mul_f32 v[2:3], v[6:7], v[4:5]
	v_pk_add_f32 v[4:5], v[68:69], v[14:15] op_sel_hi:[0,1]
	v_pk_mul_f32 v[2:3], v[2:3], v[4:5]
	v_cvt_pk_bf16_f32 v134, v0, v1
	s_nop 0
	v_cvt_pk_bf16_f32 v135, v2, v3
	s_nop 1
	v_permlane32_swap_b32_e32 v132, v134
	v_permlane32_swap_b32_e32 v133, v135
	global_store_dwordx4 v[136:137], v[132:135], off offset:1248
	s_barrier
